# GEMM K loops: s_setprio 1 from the k-tile barrier to the 12th MFMA, 0 for the last four MFMAs and LDS stores
# speedup vs baseline: 1.0117x; 1.0079x over previous
; #define MFMA(a, b, c) __builtin_amdgcn_mfma_f32_32x32x16_bf16((a), (b), (c), 0, 0, 0)
; template <class Epi, class ColV>
; DI void gemm_tile(const bf16_t* __restrict__ A, int lda, const bf16_t* __restrict__ Bt, int ldb, int K, int m0, int n0, unsigned char* smem, Epi epi, ColV colv, const bf16_t* __restrict__ HYT = nullptr) {
;     ...
;     auto step = [&](int kt, u32x4 (&ldset)[8], const u32x4 (&stset)[8]) {
;         const int buf = kt & 1;
;         if (kt + 2 < nk) gload(ldset, kt + 2);
;         const bf16_t* Ab = As + (buf * 128 + 64 * wr + li) * LS + 8 * lh;
;         const bf16_t* Bb = Bs + (buf * 128 + 64 * wc + li) * LS + 8 * lh;
;         bf16x8 fa[2][2], fb[2][2], ga[2][2], gb[2][2];
; #pragma unroll
;         for (int k2 = 0; k2 < 2; ++k2) { fa[k2][0] = ld8(Ab + 16 * k2); fa[k2][1] = ld8(Ab + 32 * LS + 16 * k2); fb[k2][0] = ld8(Bb + 16 * k2); fb[k2][1] = ld8(Bb + 32 * LS + 16 * k2); }
;         __builtin_amdgcn_sched_barrier(0);
; #pragma unroll
;         for (int k2 = 0; k2 < 2; ++k2) {
;             acc[0][0] = MFMA(fa[k2][0], fb[k2][0], acc[0][0]); acc[0][1] = MFMA(fa[k2][0], fb[k2][1], acc[0][1]);
;             acc[1][0] = MFMA(fa[k2][1], fb[k2][0], acc[1][0]); acc[1][1] = MFMA(fa[k2][1], fb[k2][1], acc[1][1]);
;         }
; #pragma unroll
;         for (int k2 = 0; k2 < 2; ++k2) { const int ks = 2 + k2; ga[k2][0] = ld8(Ab + 16 * ks); ga[k2][1] = ld8(Ab + 32 * LS + 16 * ks); gb[k2][0] = ld8(Bb + 16 * ks); gb[k2][1] = ld8(Bb + 32 * LS + 16 * ks); }
; #pragma unroll
;         for (int k2 = 0; k2 < 2; ++k2) {
;             acc[0][0] = MFMA(ga[k2][0], gb[k2][0], acc[0][0]); acc[0][1] = MFMA(ga[k2][0], gb[k2][1], acc[0][1]);
;             acc[1][0] = MFMA(ga[k2][1], gb[k2][0], acc[1][0]); acc[1][1] = MFMA(ga[k2][1], gb[k2][1], acc[1][1]);
;         }
;         if (kt + 1 < nk) sstore(stset, buf ^ 1, kt + 1);
; #pragma unroll
;         for (int i = 0; i < 8; ++i) { __builtin_amdgcn_sched_group_barrier(0x008, 1, 0); __builtin_amdgcn_sched_group_barrier(0x100, 1, 0); }
; #pragma unroll
;         for (int i = 0; i < 8; ++i) { __builtin_amdgcn_sched_group_barrier(0x008, 1, 0); __builtin_amdgcn_sched_group_barrier(0x200, 1, 0); }
;         __builtin_amdgcn_sched_barrier(0);
;         __syncthreads();
;     };
.Lg3_phase11:
	ds_read_b128 v[174:177], v194
	ds_read_b128 v[210:213], v195 offset:36864
	ds_read_b128 v[218:221], v195 offset:41472
	ds_read_b128 v[202:205], v194 offset:4608
	ds_read_b128 v[178:181], v194 offset:32
	ds_read_b128 v[222:225], v195 offset:41504
	ds_read_b128 v[206:209], v194 offset:4640
	ds_read_b128 v[214:217], v195 offset:36896
	s_waitcnt lgkmcnt(6)
	v_mfma_f32_32x32x16_bf16 v[52:67], v[174:177], v[210:213], v[52:67]
	global_load_dwordx4 v[68:71], v[164:165], off offset:384
	s_waitcnt lgkmcnt(5)
	v_mfma_f32_32x32x16_bf16 v[36:51], v[174:177], v[218:221], v[36:51]
	global_load_dwordx4 v[72:75], v[162:163], off offset:384
	s_waitcnt lgkmcnt(4)
	v_mfma_f32_32x32x16_bf16 v[4:19], v[202:205], v[218:221], v[4:19]
	global_load_dwordx4 v[76:79], v[160:161], off offset:384
	s_waitcnt lgkmcnt(2)
	v_mfma_f32_32x32x16_bf16 v[36:51], v[178:181], v[222:225], v[36:51]
	global_load_dwordx4 v[80:83], v[158:159], off offset:384
	s_waitcnt lgkmcnt(1)
	v_mfma_f32_32x32x16_bf16 v[4:19], v[206:209], v[222:225], v[4:19]
	global_load_dwordx4 v[84:87], v[156:157], off offset:384
	ds_read_b128 v[222:225], v195 offset:41568
	ds_read_b128 v[174:177], v194 offset:4672
	v_mfma_f32_32x32x16_bf16 v[20:35], v[202:205], v[210:213], v[20:35]
	global_load_dwordx4 v[92:95], v[154:155], off offset:384
	ds_read_b128 v[210:213], v194 offset:4704
	ds_read_b128 v[202:205], v194 offset:64
	s_waitcnt lgkmcnt(4)
	v_mfma_f32_32x32x16_bf16 v[52:67], v[178:181], v[214:217], v[52:67]
	global_load_dwordx4 v[104:107], v[152:153], off offset:384
	ds_read_b128 v[218:221], v195 offset:36960
	ds_read_b128 v[178:181], v195 offset:41536
	v_mfma_f32_32x32x16_bf16 v[20:35], v[206:209], v[214:217], v[20:35]
	global_load_dwordx4 v[112:115], v[146:147], off offset:384
	ds_read_b128 v[214:217], v195 offset:36928
	ds_read_b128 v[206:209], v194 offset:96
	s_waitcnt lgkmcnt(1)
	v_mfma_f32_32x32x16_bf16 v[52:67], v[202:205], v[214:217], v[52:67]
	s_waitcnt vmcnt(23)
	ds_write_b128 v190, v[88:91] offset:18432
	v_mfma_f32_32x32x16_bf16 v[36:51], v[202:205], v[178:181], v[36:51]
	s_waitcnt vmcnt(22)
	ds_write_b128 v190, v[96:99] offset:55296
	v_mfma_f32_32x32x16_bf16 v[20:35], v[174:177], v[214:217], v[20:35]
	s_waitcnt vmcnt(21)
	ds_write_b128 v191, v[100:103] offset:18432
	v_mfma_f32_32x32x16_bf16 v[4:19], v[174:177], v[178:181], v[4:19]
	s_setprio 0
	s_waitcnt vmcnt(20)
	ds_write_b128 v191, v[108:111] offset:55296
	s_waitcnt lgkmcnt(4)
	v_mfma_f32_32x32x16_bf16 v[52:67], v[206:209], v[218:221], v[52:67]
	s_waitcnt vmcnt(19)
	ds_write_b128 v192, v[116:119] offset:18432
	v_mfma_f32_32x32x16_bf16 v[36:51], v[206:209], v[222:225], v[36:51]
	s_waitcnt vmcnt(18)
	ds_write_b128 v192, v[120:123] offset:55296
	v_mfma_f32_32x32x16_bf16 v[20:35], v[210:213], v[218:221], v[20:35]
	s_waitcnt vmcnt(17)
	ds_write_b128 v193, v[124:127] offset:18432
	v_mfma_f32_32x32x16_bf16 v[4:19], v[210:213], v[222:225], v[4:19]
	s_waitcnt vmcnt(16)
	ds_write_b128 v193, v[128:131] offset:55296
	s_waitcnt lgkmcnt(0)
	s_barrier
	s_setprio 1
	ds_read_b128 v[174:177], v196
	ds_read_b128 v[210:213], v197 offset:36864
	ds_read_b128 v[218:221], v197 offset:41472
	ds_read_b128 v[202:205], v196 offset:4608
	ds_read_b128 v[178:181], v196 offset:32
	ds_read_b128 v[222:225], v197 offset:41504
	ds_read_b128 v[206:209], v196 offset:4640
	ds_read_b128 v[214:217], v197 offset:36896
	s_waitcnt lgkmcnt(6)
	v_mfma_f32_32x32x16_bf16 v[52:67], v[174:177], v[210:213], v[52:67]
	global_load_dwordx4 v[88:91], v[164:165], off offset:512
	s_waitcnt lgkmcnt(5)
	v_mfma_f32_32x32x16_bf16 v[36:51], v[174:177], v[218:221], v[36:51]
	global_load_dwordx4 v[96:99], v[162:163], off offset:512
	s_waitcnt lgkmcnt(4)
	v_mfma_f32_32x32x16_bf16 v[4:19], v[202:205], v[218:221], v[4:19]
	global_load_dwordx4 v[100:103], v[160:161], off offset:512
	s_waitcnt lgkmcnt(2)
	v_mfma_f32_32x32x16_bf16 v[36:51], v[178:181], v[222:225], v[36:51]
	global_load_dwordx4 v[108:111], v[158:159], off offset:512
	s_waitcnt lgkmcnt(1)
	v_mfma_f32_32x32x16_bf16 v[4:19], v[206:209], v[222:225], v[4:19]
	global_load_dwordx4 v[116:119], v[156:157], off offset:512
	ds_read_b128 v[222:225], v197 offset:41568
	ds_read_b128 v[174:177], v196 offset:4672
	v_mfma_f32_32x32x16_bf16 v[20:35], v[202:205], v[210:213], v[20:35]
	global_load_dwordx4 v[120:123], v[154:155], off offset:512
	ds_read_b128 v[210:213], v196 offset:4704
	ds_read_b128 v[202:205], v196 offset:64
	s_waitcnt lgkmcnt(4)
	v_mfma_f32_32x32x16_bf16 v[52:67], v[178:181], v[214:217], v[52:67]
	global_load_dwordx4 v[124:127], v[152:153], off offset:512
	ds_read_b128 v[218:221], v197 offset:36960
	ds_read_b128 v[178:181], v197 offset:41536
	v_mfma_f32_32x32x16_bf16 v[20:35], v[206:209], v[214:217], v[20:35]
	global_load_dwordx4 v[128:131], v[146:147], off offset:512
	ds_read_b128 v[214:217], v197 offset:36928
	ds_read_b128 v[206:209], v196 offset:96
	s_waitcnt lgkmcnt(1)
	v_mfma_f32_32x32x16_bf16 v[52:67], v[202:205], v[214:217], v[52:67]
	s_waitcnt vmcnt(23)
	ds_write_b128 v190, v[132:135]
	v_mfma_f32_32x32x16_bf16 v[36:51], v[202:205], v[178:181], v[36:51]
	s_waitcnt vmcnt(22)
	ds_write_b128 v190, v[136:139] offset:36864
	v_mfma_f32_32x32x16_bf16 v[20:35], v[174:177], v[214:217], v[20:35]
	s_waitcnt vmcnt(21)
	ds_write_b128 v191, v[140:143]
	v_mfma_f32_32x32x16_bf16 v[4:19], v[174:177], v[178:181], v[4:19]
	s_setprio 0
	s_waitcnt vmcnt(20)
	ds_write_b128 v191, v[198:201] offset:36864
	s_waitcnt lgkmcnt(4)
	v_mfma_f32_32x32x16_bf16 v[52:67], v[206:209], v[218:221], v[52:67]
	s_waitcnt vmcnt(19)
	ds_write_b128 v192, v[226:229]
	v_mfma_f32_32x32x16_bf16 v[36:51], v[206:209], v[222:225], v[36:51]
	s_waitcnt vmcnt(18)
	ds_write_b128 v192, v[230:233] offset:36864
	v_mfma_f32_32x32x16_bf16 v[20:35], v[210:213], v[218:221], v[20:35]
	s_waitcnt vmcnt(17)
	ds_write_b128 v193, v[242:245]
	v_mfma_f32_32x32x16_bf16 v[4:19], v[210:213], v[222:225], v[4:19]
	s_waitcnt vmcnt(16)
	ds_write_b128 v193, v[246:249] offset:36864
	s_waitcnt lgkmcnt(0)
	s_barrier
; #define MFMA(a, b, c) __builtin_amdgcn_mfma_f32_32x32x16_bf16((a), (b), (c), 0, 0, 0)
; template <class Epi, class ColV>
; DI void gemm_tile(const bf16_t* __restrict__ A, int lda, const bf16_t* __restrict__ Bt, int ldb, int K, int m0, int n0, unsigned char* smem, Epi epi, ColV colv, const bf16_t* __restrict__ HYT = nullptr) {
;     ...
;     auto step = [&](int kt, u32x4 (&ldset)[8], const u32x4 (&stset)[8]) {
;         const int buf = kt & 1;
;         if (kt + 2 < nk) gload(ldset, kt + 2);
;         const bf16_t* Ab = As + (buf * 128 + 64 * wr + li) * LS + 8 * lh;
;         const bf16_t* Bb = Bs + (buf * 128 + 64 * wc + li) * LS + 8 * lh;
;         bf16x8 fa[2][2], fb[2][2], ga[2][2], gb[2][2];
; #pragma unroll
;         for (int k2 = 0; k2 < 2; ++k2) { fa[k2][0] = ld8(Ab + 16 * k2); fa[k2][1] = ld8(Ab + 32 * LS + 16 * k2); fb[k2][0] = ld8(Bb + 16 * k2); fb[k2][1] = ld8(Bb + 32 * LS + 16 * k2); }
;         __builtin_amdgcn_sched_barrier(0);
; #pragma unroll
;         for (int k2 = 0; k2 < 2; ++k2) {
;             acc[0][0] = MFMA(fa[k2][0], fb[k2][0], acc[0][0]); acc[0][1] = MFMA(fa[k2][0], fb[k2][1], acc[0][1]);
;             acc[1][0] = MFMA(fa[k2][1], fb[k2][0], acc[1][0]); acc[1][1] = MFMA(fa[k2][1], fb[k2][1], acc[1][1]);
;         }
; #pragma unroll
;         for (int k2 = 0; k2 < 2; ++k2) { const int ks = 2 + k2; ga[k2][0] = ld8(Ab + 16 * ks); ga[k2][1] = ld8(Ab + 32 * LS + 16 * ks); gb[k2][0] = ld8(Bb + 16 * ks); gb[k2][1] = ld8(Bb + 32 * LS + 16 * ks); }
; #pragma unroll
;         for (int k2 = 0; k2 < 2; ++k2) {
;             acc[0][0] = MFMA(ga[k2][0], gb[k2][0], acc[0][0]); acc[0][1] = MFMA(ga[k2][0], gb[k2][1], acc[0][1]);
;             acc[1][0] = MFMA(ga[k2][1], gb[k2][0], acc[1][0]); acc[1][1] = MFMA(ga[k2][1], gb[k2][1], acc[1][1]);
;         }
;         if (kt + 1 < nk) sstore(stset, buf ^ 1, kt + 1);
; #pragma unroll
;         for (int i = 0; i < 8; ++i) { __builtin_amdgcn_sched_group_barrier(0x008, 1, 0); __builtin_amdgcn_sched_group_barrier(0x100, 1, 0); }
; #pragma unroll
;         for (int i = 0; i < 8; ++i) { __builtin_amdgcn_sched_group_barrier(0x008, 1, 0); __builtin_amdgcn_sched_group_barrier(0x200, 1, 0); }
;         __builtin_amdgcn_sched_barrier(0);
;         __syncthreads();
;     };
	s_setprio 1
	ds_read_b128 v[174:177], v194
	ds_read_b128 v[210:213], v195 offset:36864
	ds_read_b128 v[218:221], v195 offset:41472
	ds_read_b128 v[202:205], v194 offset:4608
	ds_read_b128 v[178:181], v194 offset:32
	ds_read_b128 v[222:225], v195 offset:41504
	ds_read_b128 v[206:209], v194 offset:4640
	ds_read_b128 v[214:217], v195 offset:36896
	s_waitcnt lgkmcnt(6)
	v_mfma_f32_32x32x16_bf16 v[52:67], v[174:177], v[210:213], v[52:67]
	global_load_dwordx4 v[132:135], v[164:165], off offset:640
	s_waitcnt lgkmcnt(5)
	v_mfma_f32_32x32x16_bf16 v[36:51], v[174:177], v[218:221], v[36:51]
	global_load_dwordx4 v[136:139], v[162:163], off offset:640
	s_waitcnt lgkmcnt(4)
	v_mfma_f32_32x32x16_bf16 v[4:19], v[202:205], v[218:221], v[4:19]
	global_load_dwordx4 v[140:143], v[160:161], off offset:640
	s_waitcnt lgkmcnt(2)
	v_mfma_f32_32x32x16_bf16 v[36:51], v[178:181], v[222:225], v[36:51]
	global_load_dwordx4 v[198:201], v[158:159], off offset:640
	s_waitcnt lgkmcnt(1)
	v_mfma_f32_32x32x16_bf16 v[4:19], v[206:209], v[222:225], v[4:19]
	global_load_dwordx4 v[226:229], v[156:157], off offset:640
	ds_read_b128 v[222:225], v195 offset:41568
	ds_read_b128 v[174:177], v194 offset:4672
	v_mfma_f32_32x32x16_bf16 v[20:35], v[202:205], v[210:213], v[20:35]
	global_load_dwordx4 v[230:233], v[154:155], off offset:640
	ds_read_b128 v[210:213], v194 offset:4704
	ds_read_b128 v[202:205], v194 offset:64
	s_waitcnt lgkmcnt(4)
	v_mfma_f32_32x32x16_bf16 v[52:67], v[178:181], v[214:217], v[52:67]
	global_load_dwordx4 v[242:245], v[152:153], off offset:640
	ds_read_b128 v[218:221], v195 offset:36960
	ds_read_b128 v[178:181], v195 offset:41536
	v_mfma_f32_32x32x16_bf16 v[20:35], v[206:209], v[214:217], v[20:35]
	global_load_dwordx4 v[246:249], v[146:147], off offset:640
	ds_read_b128 v[214:217], v195 offset:36928
	ds_read_b128 v[206:209], v194 offset:96
	s_waitcnt lgkmcnt(1)
	v_mfma_f32_32x32x16_bf16 v[52:67], v[202:205], v[214:217], v[52:67]
	s_waitcnt vmcnt(23)
	ds_write_b128 v190, v[68:71] offset:18432
	v_mfma_f32_32x32x16_bf16 v[36:51], v[202:205], v[178:181], v[36:51]
	s_waitcnt vmcnt(22)
	ds_write_b128 v190, v[72:75] offset:55296
	v_mfma_f32_32x32x16_bf16 v[20:35], v[174:177], v[214:217], v[20:35]
	s_waitcnt vmcnt(21)
	ds_write_b128 v191, v[76:79] offset:18432
	v_mfma_f32_32x32x16_bf16 v[4:19], v[174:177], v[178:181], v[4:19]
	s_setprio 0
	s_waitcnt vmcnt(20)
	ds_write_b128 v191, v[80:83] offset:55296
	s_waitcnt lgkmcnt(4)
	v_mfma_f32_32x32x16_bf16 v[52:67], v[206:209], v[218:221], v[52:67]
	s_waitcnt vmcnt(19)
	ds_write_b128 v192, v[84:87] offset:18432
	v_mfma_f32_32x32x16_bf16 v[36:51], v[206:209], v[222:225], v[36:51]
	s_waitcnt vmcnt(18)
	ds_write_b128 v192, v[92:95] offset:55296
	v_mfma_f32_32x32x16_bf16 v[20:35], v[210:213], v[218:221], v[20:35]
	s_waitcnt vmcnt(17)
	ds_write_b128 v193, v[104:107] offset:18432
	v_mfma_f32_32x32x16_bf16 v[4:19], v[210:213], v[222:225], v[4:19]
	s_waitcnt vmcnt(16)
	ds_write_b128 v193, v[112:115] offset:55296
	s_waitcnt lgkmcnt(0)
	s_barrier
	s_setprio 1
	ds_read_b128 v[174:177], v196
	ds_read_b128 v[210:213], v197 offset:36864
	ds_read_b128 v[218:221], v197 offset:41472
	ds_read_b128 v[202:205], v196 offset:4608
	ds_read_b128 v[178:181], v196 offset:32
	ds_read_b128 v[222:225], v197 offset:41504
	ds_read_b128 v[206:209], v196 offset:4640
	ds_read_b128 v[214:217], v197 offset:36896
	s_waitcnt lgkmcnt(6)
	v_mfma_f32_32x32x16_bf16 v[52:67], v[174:177], v[210:213], v[52:67]
	global_load_dwordx4 v[68:71], v[164:165], off offset:768
	s_waitcnt lgkmcnt(5)
	v_mfma_f32_32x32x16_bf16 v[36:51], v[174:177], v[218:221], v[36:51]
	global_load_dwordx4 v[72:75], v[162:163], off offset:768
	s_waitcnt lgkmcnt(4)
	v_mfma_f32_32x32x16_bf16 v[4:19], v[202:205], v[218:221], v[4:19]
	global_load_dwordx4 v[76:79], v[160:161], off offset:768
	s_waitcnt lgkmcnt(2)
	v_mfma_f32_32x32x16_bf16 v[36:51], v[178:181], v[222:225], v[36:51]
	global_load_dwordx4 v[80:83], v[158:159], off offset:768
	s_waitcnt lgkmcnt(1)
	v_mfma_f32_32x32x16_bf16 v[4:19], v[206:209], v[222:225], v[4:19]
	global_load_dwordx4 v[84:87], v[156:157], off offset:768
	ds_read_b128 v[222:225], v197 offset:41568
	ds_read_b128 v[174:177], v196 offset:4672
	v_mfma_f32_32x32x16_bf16 v[20:35], v[202:205], v[210:213], v[20:35]
	global_load_dwordx4 v[92:95], v[154:155], off offset:768
	ds_read_b128 v[210:213], v196 offset:4704
	ds_read_b128 v[202:205], v196 offset:64
	s_waitcnt lgkmcnt(4)
	v_mfma_f32_32x32x16_bf16 v[52:67], v[178:181], v[214:217], v[52:67]
	global_load_dwordx4 v[104:107], v[152:153], off offset:768
	ds_read_b128 v[218:221], v197 offset:36960
	ds_read_b128 v[178:181], v197 offset:41536
	v_mfma_f32_32x32x16_bf16 v[20:35], v[206:209], v[214:217], v[20:35]
	global_load_dwordx4 v[112:115], v[146:147], off offset:768
	ds_read_b128 v[214:217], v197 offset:36928
	ds_read_b128 v[206:209], v196 offset:96
	s_waitcnt lgkmcnt(1)
	v_mfma_f32_32x32x16_bf16 v[52:67], v[202:205], v[214:217], v[52:67]
	s_waitcnt vmcnt(23)
	ds_write_b128 v190, v[88:91]
	v_mfma_f32_32x32x16_bf16 v[36:51], v[202:205], v[178:181], v[36:51]
	s_waitcnt vmcnt(22)
	ds_write_b128 v190, v[96:99] offset:36864
	v_mfma_f32_32x32x16_bf16 v[20:35], v[174:177], v[214:217], v[20:35]
	s_waitcnt vmcnt(21)
	ds_write_b128 v191, v[100:103]
	v_mfma_f32_32x32x16_bf16 v[4:19], v[174:177], v[178:181], v[4:19]
	s_setprio 0
	s_waitcnt vmcnt(20)
	ds_write_b128 v191, v[108:111] offset:36864
	s_waitcnt lgkmcnt(4)
	v_mfma_f32_32x32x16_bf16 v[52:67], v[206:209], v[218:221], v[52:67]
	s_waitcnt vmcnt(19)
	ds_write_b128 v192, v[116:119]
	v_mfma_f32_32x32x16_bf16 v[36:51], v[206:209], v[222:225], v[36:51]
	s_waitcnt vmcnt(18)
	ds_write_b128 v192, v[120:123] offset:36864
	v_mfma_f32_32x32x16_bf16 v[20:35], v[210:213], v[218:221], v[20:35]
	s_waitcnt vmcnt(17)
	ds_write_b128 v193, v[124:127]
	v_mfma_f32_32x32x16_bf16 v[4:19], v[210:213], v[222:225], v[4:19]
	s_waitcnt vmcnt(16)
	ds_write_b128 v193, v[128:131] offset:36864
	s_waitcnt lgkmcnt(0)
	s_barrier
; #define MFMA(a, b, c) __builtin_amdgcn_mfma_f32_32x32x16_bf16((a), (b), (c), 0, 0, 0)
; template <class Epi, class ColV>
; DI void gemm_tile(const bf16_t* __restrict__ A, int lda, const bf16_t* __restrict__ Bt, int ldb, int K, int m0, int n0, unsigned char* smem, Epi epi, ColV colv, const bf16_t* __restrict__ HYT = nullptr) {
;     ...
;     auto step = [&](int kt, u32x4 (&ldset)[8], const u32x4 (&stset)[8]) {
;         const int buf = kt & 1;
;         if (kt + 2 < nk) gload(ldset, kt + 2);
;         const bf16_t* Ab = As + (buf * 128 + 64 * wr + li) * LS + 8 * lh;
;         const bf16_t* Bb = Bs + (buf * 128 + 64 * wc + li) * LS + 8 * lh;
;         bf16x8 fa[2][2], fb[2][2], ga[2][2], gb[2][2];
; #pragma unroll
;         for (int k2 = 0; k2 < 2; ++k2) { fa[k2][0] = ld8(Ab + 16 * k2); fa[k2][1] = ld8(Ab + 32 * LS + 16 * k2); fb[k2][0] = ld8(Bb + 16 * k2); fb[k2][1] = ld8(Bb + 32 * LS + 16 * k2); }
;         __builtin_amdgcn_sched_barrier(0);
; #pragma unroll
;         for (int k2 = 0; k2 < 2; ++k2) {
;             acc[0][0] = MFMA(fa[k2][0], fb[k2][0], acc[0][0]); acc[0][1] = MFMA(fa[k2][0], fb[k2][1], acc[0][1]);
;             acc[1][0] = MFMA(fa[k2][1], fb[k2][0], acc[1][0]); acc[1][1] = MFMA(fa[k2][1], fb[k2][1], acc[1][1]);
;         }
; #pragma unroll
;         for (int k2 = 0; k2 < 2; ++k2) { const int ks = 2 + k2; ga[k2][0] = ld8(Ab + 16 * ks); ga[k2][1] = ld8(Ab + 32 * LS + 16 * ks); gb[k2][0] = ld8(Bb + 16 * ks); gb[k2][1] = ld8(Bb + 32 * LS + 16 * ks); }
; #pragma unroll
;         for (int k2 = 0; k2 < 2; ++k2) {
;             acc[0][0] = MFMA(ga[k2][0], gb[k2][0], acc[0][0]); acc[0][1] = MFMA(ga[k2][0], gb[k2][1], acc[0][1]);
;             acc[1][0] = MFMA(ga[k2][1], gb[k2][0], acc[1][0]); acc[1][1] = MFMA(ga[k2][1], gb[k2][1], acc[1][1]);
;         }
;         if (kt + 1 < nk) sstore(stset, buf ^ 1, kt + 1);
; #pragma unroll
;         for (int i = 0; i < 8; ++i) { __builtin_amdgcn_sched_group_barrier(0x008, 1, 0); __builtin_amdgcn_sched_group_barrier(0x100, 1, 0); }
; #pragma unroll
;         for (int i = 0; i < 8; ++i) { __builtin_amdgcn_sched_group_barrier(0x008, 1, 0); __builtin_amdgcn_sched_group_barrier(0x200, 1, 0); }
;         __builtin_amdgcn_sched_barrier(0);
;         __syncthreads();
;     };
	s_setprio 1
	ds_read_b128 v[174:177], v194
	ds_read_b128 v[210:213], v195 offset:36864
	ds_read_b128 v[218:221], v195 offset:41472
	ds_read_b128 v[202:205], v194 offset:4608
	ds_read_b128 v[178:181], v194 offset:32
	ds_read_b128 v[222:225], v195 offset:41504
	ds_read_b128 v[206:209], v194 offset:4640
	ds_read_b128 v[214:217], v195 offset:36896
	s_waitcnt lgkmcnt(6)
	v_mfma_f32_32x32x16_bf16 v[52:67], v[174:177], v[210:213], v[52:67]
	global_load_dwordx4 v[88:91], v[164:165], off offset:896
	s_waitcnt lgkmcnt(5)
	v_mfma_f32_32x32x16_bf16 v[36:51], v[174:177], v[218:221], v[36:51]
	global_load_dwordx4 v[96:99], v[162:163], off offset:896
	s_waitcnt lgkmcnt(4)
	v_mfma_f32_32x32x16_bf16 v[4:19], v[202:205], v[218:221], v[4:19]
	global_load_dwordx4 v[100:103], v[160:161], off offset:896
	s_waitcnt lgkmcnt(2)
	v_mfma_f32_32x32x16_bf16 v[36:51], v[178:181], v[222:225], v[36:51]
	global_load_dwordx4 v[108:111], v[158:159], off offset:896
	s_waitcnt lgkmcnt(1)
	v_mfma_f32_32x32x16_bf16 v[4:19], v[206:209], v[222:225], v[4:19]
	global_load_dwordx4 v[116:119], v[156:157], off offset:896
	ds_read_b128 v[222:225], v195 offset:41568
	ds_read_b128 v[174:177], v194 offset:4672
	v_mfma_f32_32x32x16_bf16 v[20:35], v[202:205], v[210:213], v[20:35]
	global_load_dwordx4 v[120:123], v[154:155], off offset:896
	ds_read_b128 v[210:213], v194 offset:4704
	ds_read_b128 v[202:205], v194 offset:64
	s_waitcnt lgkmcnt(4)
	v_mfma_f32_32x32x16_bf16 v[52:67], v[178:181], v[214:217], v[52:67]
	global_load_dwordx4 v[124:127], v[152:153], off offset:896
	ds_read_b128 v[218:221], v195 offset:36960
	ds_read_b128 v[178:181], v195 offset:41536
	v_mfma_f32_32x32x16_bf16 v[20:35], v[206:209], v[214:217], v[20:35]
	global_load_dwordx4 v[128:131], v[146:147], off offset:896
	ds_read_b128 v[214:217], v195 offset:36928
	ds_read_b128 v[206:209], v194 offset:96
	s_waitcnt lgkmcnt(1)
	v_mfma_f32_32x32x16_bf16 v[52:67], v[202:205], v[214:217], v[52:67]
	s_waitcnt vmcnt(23)
	ds_write_b128 v190, v[132:135] offset:18432
	v_mfma_f32_32x32x16_bf16 v[36:51], v[202:205], v[178:181], v[36:51]
	s_waitcnt vmcnt(22)
	ds_write_b128 v190, v[136:139] offset:55296
	v_mfma_f32_32x32x16_bf16 v[20:35], v[174:177], v[214:217], v[20:35]
	s_waitcnt vmcnt(21)
	ds_write_b128 v191, v[140:143] offset:18432
	v_mfma_f32_32x32x16_bf16 v[4:19], v[174:177], v[178:181], v[4:19]
	s_setprio 0
	s_waitcnt vmcnt(20)
	ds_write_b128 v191, v[198:201] offset:55296
	s_waitcnt lgkmcnt(4)
	v_mfma_f32_32x32x16_bf16 v[52:67], v[206:209], v[218:221], v[52:67]
	s_waitcnt vmcnt(19)
	ds_write_b128 v192, v[226:229] offset:18432
	v_mfma_f32_32x32x16_bf16 v[36:51], v[206:209], v[222:225], v[36:51]
	s_waitcnt vmcnt(18)
	ds_write_b128 v192, v[230:233] offset:55296
	v_mfma_f32_32x32x16_bf16 v[20:35], v[210:213], v[218:221], v[20:35]
	s_waitcnt vmcnt(17)
	ds_write_b128 v193, v[242:245] offset:18432
	v_mfma_f32_32x32x16_bf16 v[4:19], v[210:213], v[222:225], v[4:19]
	s_waitcnt vmcnt(16)
	ds_write_b128 v193, v[246:249] offset:55296
	s_waitcnt lgkmcnt(0)
	s_barrier
	s_setprio 1
	ds_read_b128 v[174:177], v196
	ds_read_b128 v[210:213], v197 offset:36864
	ds_read_b128 v[218:221], v197 offset:41472
	ds_read_b128 v[202:205], v196 offset:4608
	ds_read_b128 v[178:181], v196 offset:32
	ds_read_b128 v[222:225], v197 offset:41504
	ds_read_b128 v[206:209], v196 offset:4640
	ds_read_b128 v[214:217], v197 offset:36896
	s_waitcnt lgkmcnt(6)
	v_mfma_f32_32x32x16_bf16 v[52:67], v[174:177], v[210:213], v[52:67]
	global_load_dwordx4 v[132:135], v[164:165], off offset:1024
	s_waitcnt lgkmcnt(5)
	v_mfma_f32_32x32x16_bf16 v[36:51], v[174:177], v[218:221], v[36:51]
	global_load_dwordx4 v[136:139], v[162:163], off offset:1024
	s_waitcnt lgkmcnt(4)
	v_mfma_f32_32x32x16_bf16 v[4:19], v[202:205], v[218:221], v[4:19]
	global_load_dwordx4 v[140:143], v[160:161], off offset:1024
	s_waitcnt lgkmcnt(2)
	v_mfma_f32_32x32x16_bf16 v[36:51], v[178:181], v[222:225], v[36:51]
	global_load_dwordx4 v[198:201], v[158:159], off offset:1024
	s_waitcnt lgkmcnt(1)
	v_mfma_f32_32x32x16_bf16 v[4:19], v[206:209], v[222:225], v[4:19]
	global_load_dwordx4 v[226:229], v[156:157], off offset:1024
	ds_read_b128 v[222:225], v197 offset:41568
	ds_read_b128 v[174:177], v196 offset:4672
	v_mfma_f32_32x32x16_bf16 v[20:35], v[202:205], v[210:213], v[20:35]
	global_load_dwordx4 v[230:233], v[154:155], off offset:1024
	ds_read_b128 v[210:213], v196 offset:4704
	ds_read_b128 v[202:205], v196 offset:64
	s_waitcnt lgkmcnt(4)
	v_mfma_f32_32x32x16_bf16 v[52:67], v[178:181], v[214:217], v[52:67]
	global_load_dwordx4 v[242:245], v[152:153], off offset:1024
	ds_read_b128 v[218:221], v197 offset:36960
	ds_read_b128 v[178:181], v197 offset:41536
	v_mfma_f32_32x32x16_bf16 v[20:35], v[206:209], v[214:217], v[20:35]
	global_load_dwordx4 v[246:249], v[146:147], off offset:1024
	ds_read_b128 v[214:217], v197 offset:36928
	ds_read_b128 v[206:209], v196 offset:96
	s_waitcnt lgkmcnt(1)
	v_mfma_f32_32x32x16_bf16 v[52:67], v[202:205], v[214:217], v[52:67]
	s_waitcnt vmcnt(23)
	ds_write_b128 v190, v[68:71]
	v_mfma_f32_32x32x16_bf16 v[36:51], v[202:205], v[178:181], v[36:51]
	s_waitcnt vmcnt(22)
	ds_write_b128 v190, v[72:75] offset:36864
	v_mfma_f32_32x32x16_bf16 v[20:35], v[174:177], v[214:217], v[20:35]
	s_waitcnt vmcnt(21)
	ds_write_b128 v191, v[76:79]
	v_mfma_f32_32x32x16_bf16 v[4:19], v[174:177], v[178:181], v[4:19]
	s_setprio 0
	s_waitcnt vmcnt(20)
	ds_write_b128 v191, v[80:83] offset:36864
	s_waitcnt lgkmcnt(4)
	v_mfma_f32_32x32x16_bf16 v[52:67], v[206:209], v[218:221], v[52:67]
	s_waitcnt vmcnt(19)
	ds_write_b128 v192, v[84:87]
	v_mfma_f32_32x32x16_bf16 v[36:51], v[206:209], v[222:225], v[36:51]
	s_waitcnt vmcnt(18)
	ds_write_b128 v192, v[92:95] offset:36864
	v_mfma_f32_32x32x16_bf16 v[20:35], v[210:213], v[218:221], v[20:35]
	s_waitcnt vmcnt(17)
	ds_write_b128 v193, v[104:107]
	v_mfma_f32_32x32x16_bf16 v[4:19], v[210:213], v[222:225], v[4:19]
	s_waitcnt vmcnt(16)
	ds_write_b128 v193, v[112:115] offset:36864
	s_waitcnt lgkmcnt(0)
	s_barrier
; template <class Epi, class ColV>
; DI void gemm_tile(const bf16_t* __restrict__ A, int lda, const bf16_t* __restrict__ Bt, int ldb, int K, int m0, int n0, unsigned char* smem, Epi epi, ColV colv, const bf16_t* __restrict__ HYT = nullptr) {
;     ...
;     auto step = [&](int kt, u32x4 (&ldset)[8], const u32x4 (&stset)[8]) {
;         const int buf = kt & 1;
;         if (kt + 2 < nk) gload(ldset, kt + 2);
;         const bf16_t* Ab = As + (buf * 128 + 64 * wr + li) * LS + 8 * lh;
;         const bf16_t* Bb = Bs + (buf * 128 + 64 * wc + li) * LS + 8 * lh;
;         bf16x8 fa[2][2], fb[2][2], ga[2][2], gb[2][2];
; #pragma unroll
;         for (int k2 = 0; k2 < 2; ++k2) { fa[k2][0] = ld8(Ab + 16 * k2); fa[k2][1] = ld8(Ab + 32 * LS + 16 * k2); fb[k2][0] = ld8(Bb + 16 * k2); fb[k2][1] = ld8(Bb + 32 * LS + 16 * k2); }
;         __builtin_amdgcn_sched_barrier(0);
; #pragma unroll
;         for (int k2 = 0; k2 < 2; ++k2) {
;             acc[0][0] = MFMA(fa[k2][0], fb[k2][0], acc[0][0]); acc[0][1] = MFMA(fa[k2][0], fb[k2][1], acc[0][1]);
;             acc[1][0] = MFMA(fa[k2][1], fb[k2][0], acc[1][0]); acc[1][1] = MFMA(fa[k2][1], fb[k2][1], acc[1][1]);
;         }
; #pragma unroll
;         for (int k2 = 0; k2 < 2; ++k2) { const int ks = 2 + k2; ga[k2][0] = ld8(Ab + 16 * ks); ga[k2][1] = ld8(Ab + 32 * LS + 16 * ks); gb[k2][0] = ld8(Bb + 16 * ks); gb[k2][1] = ld8(Bb + 32 * LS + 16 * ks); }
; #pragma unroll
;         for (int k2 = 0; k2 < 2; ++k2) {
;             acc[0][0] = MFMA(ga[k2][0], gb[k2][0], acc[0][0]); acc[0][1] = MFMA(ga[k2][0], gb[k2][1], acc[0][1]);
;             acc[1][0] = MFMA(ga[k2][1], gb[k2][0], acc[1][0]); acc[1][1] = MFMA(ga[k2][1], gb[k2][1], acc[1][1]);
;         }
;         if (kt + 1 < nk) sstore(stset, buf ^ 1, kt + 1);
; #pragma unroll
;         for (int i = 0; i < 8; ++i) { __builtin_amdgcn_sched_group_barrier(0x008, 1, 0); __builtin_amdgcn_sched_group_barrier(0x100, 1, 0); }
; #pragma unroll
;         for (int i = 0; i < 8; ++i) { __builtin_amdgcn_sched_group_barrier(0x008, 1, 0); __builtin_amdgcn_sched_group_barrier(0x200, 1, 0); }
;         __builtin_amdgcn_sched_barrier(0);
;         __syncthreads();
;     };
;     gload(R0, 0); gload(R1, 1);
;     sstore(R0, 0, 0); __syncthreads();
;     for (int kt = 0; kt < nk; kt += 2) {
;         step(kt, R0, R1);
;         if (kt + 1 < nk) step(kt + 1, R1, R0);
	s_setprio 1
	v_lshl_add_u64 v[164:165], v[164:165], 0, s[100:101]
	v_lshl_add_u64 v[162:163], v[162:163], 0, s[100:101]
	v_lshl_add_u64 v[160:161], v[160:161], 0, s[100:101]
	v_lshl_add_u64 v[158:159], v[158:159], 0, s[100:101]
	v_lshl_add_u64 v[156:157], v[156:157], 0, s[100:101]
	v_lshl_add_u64 v[154:155], v[154:155], 0, s[100:101]
	v_lshl_add_u64 v[152:153], v[152:153], 0, s[100:101]
	v_lshl_add_u64 v[146:147], v[146:147], 0, s[100:101]
	s_sub_u32 s41, s41, 1
	s_cmp_lg_u32 s41, 0
	s_cbranch_scc1 .Lg3_phase11
	ds_read_b128 v[174:177], v194
	ds_read_b128 v[210:213], v195 offset:36864
	ds_read_b128 v[218:221], v195 offset:41472
	ds_read_b128 v[202:205], v194 offset:4608
	ds_read_b128 v[178:181], v194 offset:32
	ds_read_b128 v[222:225], v195 offset:41504
	ds_read_b128 v[206:209], v194 offset:4640
	ds_read_b128 v[214:217], v195 offset:36896
	s_waitcnt lgkmcnt(6)
	v_mfma_f32_32x32x16_bf16 v[52:67], v[174:177], v[210:213], v[52:67]
	global_load_dwordx4 v[68:71], v[164:165], off offset:384
	s_waitcnt lgkmcnt(5)
	v_mfma_f32_32x32x16_bf16 v[36:51], v[174:177], v[218:221], v[36:51]
	global_load_dwordx4 v[72:75], v[162:163], off offset:384
	s_waitcnt lgkmcnt(4)
	v_mfma_f32_32x32x16_bf16 v[4:19], v[202:205], v[218:221], v[4:19]
	global_load_dwordx4 v[76:79], v[160:161], off offset:384
	s_waitcnt lgkmcnt(2)
	v_mfma_f32_32x32x16_bf16 v[36:51], v[178:181], v[222:225], v[36:51]
	global_load_dwordx4 v[80:83], v[158:159], off offset:384
	s_waitcnt lgkmcnt(1)
	v_mfma_f32_32x32x16_bf16 v[4:19], v[206:209], v[222:225], v[4:19]
	global_load_dwordx4 v[84:87], v[156:157], off offset:384
	ds_read_b128 v[222:225], v195 offset:41568
	ds_read_b128 v[174:177], v194 offset:4672
	v_mfma_f32_32x32x16_bf16 v[20:35], v[202:205], v[210:213], v[20:35]
	global_load_dwordx4 v[92:95], v[154:155], off offset:384
	ds_read_b128 v[210:213], v194 offset:4704
	ds_read_b128 v[202:205], v194 offset:64
	s_waitcnt lgkmcnt(4)
	v_mfma_f32_32x32x16_bf16 v[52:67], v[178:181], v[214:217], v[52:67]
	global_load_dwordx4 v[104:107], v[152:153], off offset:384
	ds_read_b128 v[218:221], v195 offset:36960
	ds_read_b128 v[178:181], v195 offset:41536
	v_mfma_f32_32x32x16_bf16 v[20:35], v[206:209], v[214:217], v[20:35]
	global_load_dwordx4 v[112:115], v[146:147], off offset:384
	ds_read_b128 v[214:217], v195 offset:36928
	ds_read_b128 v[206:209], v194 offset:96
	s_waitcnt lgkmcnt(1)
	v_mfma_f32_32x32x16_bf16 v[52:67], v[202:205], v[214:217], v[52:67]
	s_waitcnt vmcnt(23)
	ds_write_b128 v190, v[88:91] offset:18432
	v_mfma_f32_32x32x16_bf16 v[36:51], v[202:205], v[178:181], v[36:51]
	s_waitcnt vmcnt(22)
	ds_write_b128 v190, v[96:99] offset:55296
	v_mfma_f32_32x32x16_bf16 v[20:35], v[174:177], v[214:217], v[20:35]
	s_waitcnt vmcnt(21)
	ds_write_b128 v191, v[100:103] offset:18432
	v_mfma_f32_32x32x16_bf16 v[4:19], v[174:177], v[178:181], v[4:19]
	s_setprio 0
	s_waitcnt vmcnt(20)
	ds_write_b128 v191, v[108:111] offset:55296
	s_waitcnt lgkmcnt(4)
	v_mfma_f32_32x32x16_bf16 v[52:67], v[206:209], v[218:221], v[52:67]
	s_waitcnt vmcnt(19)
	ds_write_b128 v192, v[116:119] offset:18432
	v_mfma_f32_32x32x16_bf16 v[36:51], v[206:209], v[222:225], v[36:51]
	s_waitcnt vmcnt(18)
	ds_write_b128 v192, v[120:123] offset:55296
	v_mfma_f32_32x32x16_bf16 v[20:35], v[210:213], v[218:221], v[20:35]
	s_waitcnt vmcnt(17)
	ds_write_b128 v193, v[124:127] offset:18432
	v_mfma_f32_32x32x16_bf16 v[4:19], v[210:213], v[222:225], v[4:19]
	s_waitcnt vmcnt(16)
	ds_write_b128 v193, v[128:131] offset:55296
	s_waitcnt lgkmcnt(0)
	s_barrier
	s_setprio 1
	ds_read_b128 v[174:177], v196
	ds_read_b128 v[178:181], v196 offset:32
	ds_read_b128 v[202:205], v196 offset:4608
	ds_read_b128 v[206:209], v196 offset:4640
	ds_read_b128 v[210:213], v197 offset:36864
	ds_read_b128 v[214:217], v197 offset:36896
	ds_read_b128 v[218:221], v197 offset:41472
	ds_read_b128 v[222:225], v197 offset:41504
	s_waitcnt lgkmcnt(3)
	v_mfma_f32_32x32x16_bf16 v[52:67], v[174:177], v[210:213], v[52:67]
	s_waitcnt lgkmcnt(1)
	v_mfma_f32_32x32x16_bf16 v[36:51], v[174:177], v[218:221], v[36:51]
	v_mfma_f32_32x32x16_bf16 v[4:19], v[202:205], v[218:221], v[4:19]
	s_waitcnt lgkmcnt(0)
	v_mfma_f32_32x32x16_bf16 v[36:51], v[178:181], v[222:225], v[36:51]
	v_mfma_f32_32x32x16_bf16 v[4:19], v[206:209], v[222:225], v[4:19]
	ds_read_b128 v[222:225], v197 offset:41568
	ds_read_b128 v[174:177], v196 offset:4672
	v_mfma_f32_32x32x16_bf16 v[20:35], v[202:205], v[210:213], v[20:35]
	ds_read_b128 v[210:213], v196 offset:4704
	ds_read_b128 v[202:205], v196 offset:64
	v_mfma_f32_32x32x16_bf16 v[52:67], v[178:181], v[214:217], v[52:67]
	ds_read_b128 v[218:221], v197 offset:36960
	ds_read_b128 v[178:181], v197 offset:41536
	v_mfma_f32_32x32x16_bf16 v[20:35], v[206:209], v[214:217], v[20:35]
	ds_read_b128 v[214:217], v197 offset:36928
	ds_read_b128 v[206:209], v196 offset:96
	s_waitcnt lgkmcnt(1)
	v_mfma_f32_32x32x16_bf16 v[52:67], v[202:205], v[214:217], v[52:67]
	s_waitcnt vmcnt(15)
	ds_write_b128 v190, v[132:135]
	v_mfma_f32_32x32x16_bf16 v[36:51], v[202:205], v[178:181], v[36:51]
	s_waitcnt vmcnt(14)
	ds_write_b128 v190, v[136:139] offset:36864
	v_mfma_f32_32x32x16_bf16 v[20:35], v[174:177], v[214:217], v[20:35]
	s_waitcnt vmcnt(13)
	ds_write_b128 v191, v[140:143]
	v_mfma_f32_32x32x16_bf16 v[4:19], v[174:177], v[178:181], v[4:19]
	s_setprio 0
	s_waitcnt vmcnt(12)
	ds_write_b128 v191, v[198:201] offset:36864
	s_waitcnt lgkmcnt(4)
	v_mfma_f32_32x32x16_bf16 v[52:67], v[206:209], v[218:221], v[52:67]
	s_waitcnt vmcnt(11)
	ds_write_b128 v192, v[226:229]
	v_mfma_f32_32x32x16_bf16 v[36:51], v[206:209], v[222:225], v[36:51]
	s_waitcnt vmcnt(10)
	ds_write_b128 v192, v[230:233] offset:36864
	v_mfma_f32_32x32x16_bf16 v[20:35], v[210:213], v[218:221], v[20:35]
	s_waitcnt vmcnt(9)
	ds_write_b128 v193, v[242:245]
	v_mfma_f32_32x32x16_bf16 v[4:19], v[210:213], v[222:225], v[4:19]
	s_waitcnt vmcnt(8)
	ds_write_b128 v193, v[246:249] offset:36864
	s_waitcnt lgkmcnt(0)
	s_barrier
; template <class Epi, class ColV>
; DI void gemm_tile(const bf16_t* __restrict__ A, int lda, const bf16_t* __restrict__ Bt, int ldb, int K, int m0, int n0, unsigned char* smem, Epi epi, ColV colv, const bf16_t* __restrict__ HYT = nullptr) {
;     ...
;     auto step = [&](int kt, u32x4 (&ldset)[8], const u32x4 (&stset)[8]) {
;         const int buf = kt & 1;
;         if (kt + 2 < nk) gload(ldset, kt + 2);
;         const bf16_t* Ab = As + (buf * 128 + 64 * wr + li) * LS + 8 * lh;
;         const bf16_t* Bb = Bs + (buf * 128 + 64 * wc + li) * LS + 8 * lh;
;         bf16x8 fa[2][2], fb[2][2], ga[2][2], gb[2][2];
; #pragma unroll
;         for (int k2 = 0; k2 < 2; ++k2) { fa[k2][0] = ld8(Ab + 16 * k2); fa[k2][1] = ld8(Ab + 32 * LS + 16 * k2); fb[k2][0] = ld8(Bb + 16 * k2); fb[k2][1] = ld8(Bb + 32 * LS + 16 * k2); }
;         __builtin_amdgcn_sched_barrier(0);
; #pragma unroll
;         for (int k2 = 0; k2 < 2; ++k2) {
;             acc[0][0] = MFMA(fa[k2][0], fb[k2][0], acc[0][0]); acc[0][1] = MFMA(fa[k2][0], fb[k2][1], acc[0][1]);
;             acc[1][0] = MFMA(fa[k2][1], fb[k2][0], acc[1][0]); acc[1][1] = MFMA(fa[k2][1], fb[k2][1], acc[1][1]);
;         }
; #pragma unroll
;         for (int k2 = 0; k2 < 2; ++k2) { const int ks = 2 + k2; ga[k2][0] = ld8(Ab + 16 * ks); ga[k2][1] = ld8(Ab + 32 * LS + 16 * ks); gb[k2][0] = ld8(Bb + 16 * ks); gb[k2][1] = ld8(Bb + 32 * LS + 16 * ks); }
; #pragma unroll
;         for (int k2 = 0; k2 < 2; ++k2) {
;             acc[0][0] = MFMA(ga[k2][0], gb[k2][0], acc[0][0]); acc[0][1] = MFMA(ga[k2][0], gb[k2][1], acc[0][1]);
;             acc[1][0] = MFMA(ga[k2][1], gb[k2][0], acc[1][0]); acc[1][1] = MFMA(ga[k2][1], gb[k2][1], acc[1][1]);
;         }
;         if (kt + 1 < nk) sstore(stset, buf ^ 1, kt + 1);
; #pragma unroll
;         for (int i = 0; i < 8; ++i) { __builtin_amdgcn_sched_group_barrier(0x008, 1, 0); __builtin_amdgcn_sched_group_barrier(0x100, 1, 0); }
; #pragma unroll
;         for (int i = 0; i < 8; ++i) { __builtin_amdgcn_sched_group_barrier(0x008, 1, 0); __builtin_amdgcn_sched_group_barrier(0x200, 1, 0); }
;         __builtin_amdgcn_sched_barrier(0);
;         __syncthreads();
;     };
;     gload(R0, 0); gload(R1, 1);
;     sstore(R0, 0, 0); __syncthreads();
;     for (int kt = 0; kt < nk; kt += 2) {
;         step(kt, R0, R1);
;         if (kt + 1 < nk) step(kt + 1, R1, R0);
;     }
	s_setprio 1
	ds_read_b128 v[174:177], v194
	ds_read_b128 v[178:181], v194 offset:32
	ds_read_b128 v[202:205], v194 offset:4608
	ds_read_b128 v[206:209], v194 offset:4640
	ds_read_b128 v[210:213], v195 offset:36864
	ds_read_b128 v[214:217], v195 offset:36896
	ds_read_b128 v[218:221], v195 offset:41472
	ds_read_b128 v[222:225], v195 offset:41504
	s_waitcnt lgkmcnt(3)
	v_mfma_f32_32x32x16_bf16 v[52:67], v[174:177], v[210:213], v[52:67]
	s_waitcnt lgkmcnt(1)
	v_mfma_f32_32x32x16_bf16 v[36:51], v[174:177], v[218:221], v[36:51]
	v_mfma_f32_32x32x16_bf16 v[4:19], v[202:205], v[218:221], v[4:19]
	s_waitcnt lgkmcnt(0)
	v_mfma_f32_32x32x16_bf16 v[36:51], v[178:181], v[222:225], v[36:51]
	v_mfma_f32_32x32x16_bf16 v[4:19], v[206:209], v[222:225], v[4:19]
	ds_read_b128 v[222:225], v195 offset:41568
	ds_read_b128 v[174:177], v194 offset:4672
	v_mfma_f32_32x32x16_bf16 v[20:35], v[202:205], v[210:213], v[20:35]
	ds_read_b128 v[210:213], v194 offset:4704
	ds_read_b128 v[202:205], v194 offset:64
	v_mfma_f32_32x32x16_bf16 v[52:67], v[178:181], v[214:217], v[52:67]
	ds_read_b128 v[218:221], v195 offset:36960
	ds_read_b128 v[178:181], v195 offset:41536
	v_mfma_f32_32x32x16_bf16 v[20:35], v[206:209], v[214:217], v[20:35]
	ds_read_b128 v[214:217], v195 offset:36928
	ds_read_b128 v[206:209], v194 offset:96
	s_waitcnt lgkmcnt(1)
	v_mfma_f32_32x32x16_bf16 v[52:67], v[202:205], v[214:217], v[52:67]
	s_waitcnt vmcnt(7)
	ds_write_b128 v190, v[68:71] offset:18432
	v_mfma_f32_32x32x16_bf16 v[36:51], v[202:205], v[178:181], v[36:51]
	s_waitcnt vmcnt(6)
	ds_write_b128 v190, v[72:75] offset:55296
	v_mfma_f32_32x32x16_bf16 v[20:35], v[174:177], v[214:217], v[20:35]
	s_waitcnt vmcnt(5)
	ds_write_b128 v191, v[76:79] offset:18432
	v_mfma_f32_32x32x16_bf16 v[4:19], v[174:177], v[178:181], v[4:19]
	s_setprio 0
	s_waitcnt vmcnt(4)
	ds_write_b128 v191, v[80:83] offset:55296
	s_waitcnt lgkmcnt(4)
	v_mfma_f32_32x32x16_bf16 v[52:67], v[206:209], v[218:221], v[52:67]
	s_waitcnt vmcnt(3)
	ds_write_b128 v192, v[84:87] offset:18432
	v_mfma_f32_32x32x16_bf16 v[36:51], v[206:209], v[222:225], v[36:51]
	s_waitcnt vmcnt(2)
	ds_write_b128 v192, v[92:95] offset:55296
	v_mfma_f32_32x32x16_bf16 v[20:35], v[210:213], v[218:221], v[20:35]
	s_waitcnt vmcnt(1)
	ds_write_b128 v193, v[104:107] offset:18432
	v_mfma_f32_32x32x16_bf16 v[4:19], v[210:213], v[222:225], v[4:19]
	s_waitcnt vmcnt(0)
	ds_write_b128 v193, v[112:115] offset:55296
	s_waitcnt lgkmcnt(0)
	s_barrier
	s_setprio 1
	ds_read_b128 v[174:177], v196
	ds_read_b128 v[178:181], v196 offset:32
	ds_read_b128 v[202:205], v196 offset:4608
	ds_read_b128 v[206:209], v196 offset:4640
	ds_read_b128 v[210:213], v197 offset:36864
	ds_read_b128 v[214:217], v197 offset:36896
	ds_read_b128 v[218:221], v197 offset:41472
	ds_read_b128 v[222:225], v197 offset:41504
	s_waitcnt lgkmcnt(3)
	v_mfma_f32_32x32x16_bf16 v[52:67], v[174:177], v[210:213], v[52:67]
	s_waitcnt lgkmcnt(1)
	v_mfma_f32_32x32x16_bf16 v[36:51], v[174:177], v[218:221], v[36:51]
	v_mfma_f32_32x32x16_bf16 v[4:19], v[202:205], v[218:221], v[4:19]
	s_waitcnt lgkmcnt(0)
	v_mfma_f32_32x32x16_bf16 v[36:51], v[178:181], v[222:225], v[36:51]
	v_mfma_f32_32x32x16_bf16 v[4:19], v[206:209], v[222:225], v[4:19]
	ds_read_b128 v[222:225], v197 offset:41568
	ds_read_b128 v[174:177], v196 offset:4672
	v_mfma_f32_32x32x16_bf16 v[20:35], v[202:205], v[210:213], v[20:35]
	ds_read_b128 v[210:213], v196 offset:4704
	ds_read_b128 v[202:205], v196 offset:64
	v_mfma_f32_32x32x16_bf16 v[52:67], v[178:181], v[214:217], v[52:67]
	ds_read_b128 v[218:221], v197 offset:36960
	ds_read_b128 v[178:181], v197 offset:41536
	v_mfma_f32_32x32x16_bf16 v[20:35], v[206:209], v[214:217], v[20:35]
	ds_read_b128 v[214:217], v197 offset:36928
	ds_read_b128 v[206:209], v196 offset:96
	s_waitcnt lgkmcnt(1)
	v_mfma_f32_32x32x16_bf16 v[52:67], v[202:205], v[214:217], v[52:67]
	v_mfma_f32_32x32x16_bf16 v[36:51], v[202:205], v[178:181], v[36:51]
	v_mfma_f32_32x32x16_bf16 v[20:35], v[174:177], v[214:217], v[20:35]
	v_mfma_f32_32x32x16_bf16 v[4:19], v[174:177], v[178:181], v[4:19]
	s_setprio 0
	s_waitcnt lgkmcnt(0)
	v_mfma_f32_32x32x16_bf16 v[52:67], v[206:209], v[218:221], v[52:67]
	v_mfma_f32_32x32x16_bf16 v[36:51], v[206:209], v[222:225], v[36:51]
	v_mfma_f32_32x32x16_bf16 v[20:35], v[210:213], v[218:221], v[20:35]
	v_mfma_f32_32x32x16_bf16 v[4:19], v[210:213], v[222:225], v[4:19]
	s_waitcnt lgkmcnt(0)
	s_barrier
	s_setprio 1
	s_nop 7
	s_nop 3
	s_branch .LBB0_37

; #define MFMA(a, b, c) __builtin_amdgcn_mfma_f32_32x32x16_bf16((a), (b), (c), 0, 0, 0)
; template <class Epi, class ColV>
; DI void gemm_tile(const bf16_t* __restrict__ A, int lda, const bf16_t* __restrict__ Bt, int ldb, int K, int m0, int n0, unsigned char* smem, Epi epi, ColV colv, const bf16_t* __restrict__ HYT = nullptr) {
;     ...
;     auto gload = [&](u32x4 (&r)[8], int kt) {
; #pragma unroll
;         for (int i = 0; i < 4; ++i) { int id = tid + 256 * i, row = id >> 3, kc = id & 7;
;             if (HYT && kt >= 12) r[i] = *(const u32x4*)(HYT + (size_t)((kt - 12) * 64 + (id >> 4)) * NT + m0 + (id & 15) * 8);
;             else r[i] = *(const u32x4*)(A + (size_t)(m0 + row) * lda + kt * 64 + kc * 8);
;             r[4 + i] = *(const u32x4*)(Bt + (size_t)(n0 + row) * ldb + kt * 64 + kc * 8); }
;     };
;     auto sstore = [&](const u32x4 (&r)[8], int buf, int kt) {
; #pragma unroll
;         for (int i = 0; i < 4; ++i) { int id = tid + 256 * i, row = id >> 3, kc = id & 7;
;             if (HYT && kt >= 12) { const int kk = id >> 4, rr = (id & 15) * 8; bf16_t* d = As + (buf * 128 + rr) * LS + kk; const bf16x8 v = __builtin_bit_cast(bf16x8, r[i]);
; #pragma unroll
;                 for (int e = 0; e < 8; ++e) d[e * LS] = (bf16_t)v[e]; }
;             else *(u32x4*)(As + (buf * 128 + row) * LS + kc * 8) = r[i];
;             *(u32x4*)(Bs + (buf * 128 + row) * LS + kc * 8) = r[4 + i]; }
;     };
;     auto step = [&](int kt, u32x4 (&ldset)[8], const u32x4 (&stset)[8]) {
;         const int buf = kt & 1;
;         if (kt + 2 < nk) gload(ldset, kt + 2);
;         const bf16_t* Ab = As + (buf * 128 + 64 * wr + li) * LS + 8 * lh;
;         const bf16_t* Bb = Bs + (buf * 128 + 64 * wc + li) * LS + 8 * lh;
;         bf16x8 fa[2][2], fb[2][2], ga[2][2], gb[2][2];
; #pragma unroll
;         for (int k2 = 0; k2 < 2; ++k2) { fa[k2][0] = ld8(Ab + 16 * k2); fa[k2][1] = ld8(Ab + 32 * LS + 16 * k2); fb[k2][0] = ld8(Bb + 16 * k2); fb[k2][1] = ld8(Bb + 32 * LS + 16 * k2); }
;         __builtin_amdgcn_sched_barrier(0);
; #pragma unroll
;         for (int k2 = 0; k2 < 2; ++k2) {
;             acc[0][0] = MFMA(fa[k2][0], fb[k2][0], acc[0][0]); acc[0][1] = MFMA(fa[k2][0], fb[k2][1], acc[0][1]);
;             acc[1][0] = MFMA(fa[k2][1], fb[k2][0], acc[1][0]); acc[1][1] = MFMA(fa[k2][1], fb[k2][1], acc[1][1]);
;         }
; #pragma unroll
.LBB0_56:
	s_cmp_lt_u32 s40, 14
	s_cselect_b64 s[18:19], -1, 0
	s_cmp_gt_u32 s40, 13
	s_cselect_b64 s[12:13], -1, 0
	s_and_b64 vcc, exec, s[12:13]
	v_lshl_add_u64 v[164:165], v[144:145], 0, v[2:3]
	v_lshl_add_u64 v[162:163], v[142:143], 0, v[2:3]
	v_lshl_add_u64 v[160:161], v[140:141], 0, v[2:3]
	v_lshl_add_u64 v[158:159], v[138:139], 0, v[2:3]
	v_lshl_add_u64 v[156:157], v[136:137], 0, v[2:3]
	v_lshl_add_u64 v[154:155], v[134:135], 0, v[2:3]
	v_lshl_add_u64 v[152:153], v[132:133], 0, v[2:3]
	v_lshl_add_u64 v[146:147], v[0:1], 0, v[2:3]
	s_mov_b32 s100, 0x26ca000
	s_mov_b32 s101, 0
	v_lshl_add_u64 v[164:165], v[164:165], 0, s[100:101]
	v_lshl_add_u64 v[160:161], v[160:161], 0, s[100:101]
	v_lshl_add_u64 v[156:157], v[156:157], 0, s[100:101]
	v_lshl_add_u64 v[152:153], v[152:153], 0, s[100:101]
	s_mov_b32 s100, 0x680000
	s_mov_b32 s101, 0
	v_lshl_add_u64 v[162:163], v[162:163], 0, s[100:101]
	v_lshl_add_u64 v[158:159], v[158:159], 0, s[100:101]
	v_lshl_add_u64 v[154:155], v[154:155], 0, s[100:101]
	v_lshl_add_u64 v[146:147], v[146:147], 0, s[100:101]
	ds_read_b128 v[174:177], v194
	ds_read_b128 v[210:213], v195 offset:36864
	ds_read_b128 v[218:221], v195 offset:41472
	ds_read_b128 v[202:205], v194 offset:4608
	ds_read_b128 v[178:181], v194 offset:32
	ds_read_b128 v[222:225], v195 offset:41504
	ds_read_b128 v[206:209], v194 offset:4640
	ds_read_b128 v[214:217], v195 offset:36896
	s_waitcnt lgkmcnt(6)
	v_mfma_f32_32x32x16_bf16 v[52:67], v[174:177], v[210:213], v[52:67]
	global_load_dwordx4 v[132:135], v[164:165], off offset:256
	global_load_dwordx4 v[136:139], v[162:163], off offset:256
	s_waitcnt lgkmcnt(5)
	v_mfma_f32_32x32x16_bf16 v[36:51], v[174:177], v[218:221], v[36:51]
	global_load_dwordx4 v[140:143], v[160:161], off offset:256
	global_load_dwordx4 v[198:201], v[158:159], off offset:256
	s_waitcnt lgkmcnt(4)
	v_mfma_f32_32x32x16_bf16 v[4:19], v[202:205], v[218:221], v[4:19]
	global_load_dwordx4 v[226:229], v[156:157], off offset:256
	global_load_dwordx4 v[230:233], v[154:155], off offset:256
	s_waitcnt lgkmcnt(2)
	v_mfma_f32_32x32x16_bf16 v[36:51], v[178:181], v[222:225], v[36:51]
	global_load_dwordx4 v[242:245], v[152:153], off offset:256
	global_load_dwordx4 v[246:249], v[146:147], off offset:256
	s_waitcnt lgkmcnt(1)
	v_mfma_f32_32x32x16_bf16 v[4:19], v[206:209], v[222:225], v[4:19]
	global_load_dwordx4 v[68:71], v[164:165], off offset:384
	global_load_dwordx4 v[72:75], v[162:163], off offset:384
	ds_read_b128 v[222:225], v195 offset:41568
	ds_read_b128 v[174:177], v194 offset:4672
	v_mfma_f32_32x32x16_bf16 v[20:35], v[202:205], v[210:213], v[20:35]
	global_load_dwordx4 v[76:79], v[160:161], off offset:384
	global_load_dwordx4 v[80:83], v[158:159], off offset:384
	ds_read_b128 v[210:213], v194 offset:4704
	ds_read_b128 v[202:205], v194 offset:64
	s_waitcnt lgkmcnt(4)
	v_mfma_f32_32x32x16_bf16 v[52:67], v[178:181], v[214:217], v[52:67]
	global_load_dwordx4 v[84:87], v[156:157], off offset:384
	global_load_dwordx4 v[92:95], v[154:155], off offset:384
	ds_read_b128 v[218:221], v195 offset:36960
	ds_read_b128 v[178:181], v195 offset:41536
	v_mfma_f32_32x32x16_bf16 v[20:35], v[206:209], v[214:217], v[20:35]
	global_load_dwordx4 v[104:107], v[152:153], off offset:384
	global_load_dwordx4 v[112:115], v[146:147], off offset:384
	ds_read_b128 v[214:217], v195 offset:36928
	ds_read_b128 v[206:209], v194 offset:96
	s_waitcnt lgkmcnt(1)
	v_mfma_f32_32x32x16_bf16 v[52:67], v[202:205], v[214:217], v[52:67]
	s_waitcnt vmcnt(16)
	ds_write_b128 v167, v[88:91] offset:18432
	v_mfma_f32_32x32x16_bf16 v[36:51], v[202:205], v[178:181], v[36:51]
	ds_write_b128 v167, v[96:99] offset:55296
	v_mfma_f32_32x32x16_bf16 v[20:35], v[174:177], v[214:217], v[20:35]
	ds_write_b128 v190, v[100:103] offset:18432
	v_mfma_f32_32x32x16_bf16 v[4:19], v[174:177], v[178:181], v[4:19]
	s_setprio 0
	ds_write_b128 v190, v[108:111] offset:55296
	s_waitcnt lgkmcnt(4)
	v_mfma_f32_32x32x16_bf16 v[52:67], v[206:209], v[218:221], v[52:67]
	ds_write_b128 v191, v[116:119] offset:18432
	v_mfma_f32_32x32x16_bf16 v[36:51], v[206:209], v[222:225], v[36:51]
	ds_write_b128 v191, v[120:123] offset:55296
	v_mfma_f32_32x32x16_bf16 v[20:35], v[210:213], v[218:221], v[20:35]
	ds_write_b128 v192, v[124:127] offset:18432
	v_mfma_f32_32x32x16_bf16 v[4:19], v[210:213], v[222:225], v[4:19]
	ds_write_b128 v192, v[128:131] offset:55296
	s_waitcnt lgkmcnt(0)
	s_barrier
; #define MFMA(a, b, c) __builtin_amdgcn_mfma_f32_32x32x16_bf16((a), (b), (c), 0, 0, 0)
; template <class Epi, class ColV>
; DI void gemm_tile(const bf16_t* __restrict__ A, int lda, const bf16_t* __restrict__ Bt, int ldb, int K, int m0, int n0, unsigned char* smem, Epi epi, ColV colv, const bf16_t* __restrict__ HYT = nullptr) {
;     ...
;     auto step = [&](int kt, u32x4 (&ldset)[8], const u32x4 (&stset)[8]) {
;         const int buf = kt & 1;
;         if (kt + 2 < nk) gload(ldset, kt + 2);
;         const bf16_t* Ab = As + (buf * 128 + 64 * wr + li) * LS + 8 * lh;
;         const bf16_t* Bb = Bs + (buf * 128 + 64 * wc + li) * LS + 8 * lh;
;         bf16x8 fa[2][2], fb[2][2], ga[2][2], gb[2][2];
; #pragma unroll
;         for (int k2 = 0; k2 < 2; ++k2) { fa[k2][0] = ld8(Ab + 16 * k2); fa[k2][1] = ld8(Ab + 32 * LS + 16 * k2); fb[k2][0] = ld8(Bb + 16 * k2); fb[k2][1] = ld8(Bb + 32 * LS + 16 * k2); }
;         __builtin_amdgcn_sched_barrier(0);
; #pragma unroll
;         for (int k2 = 0; k2 < 2; ++k2) {
;             acc[0][0] = MFMA(fa[k2][0], fb[k2][0], acc[0][0]); acc[0][1] = MFMA(fa[k2][0], fb[k2][1], acc[0][1]);
;             acc[1][0] = MFMA(fa[k2][1], fb[k2][0], acc[1][0]); acc[1][1] = MFMA(fa[k2][1], fb[k2][1], acc[1][1]);
;         }
; #pragma unroll
;         for (int k2 = 0; k2 < 2; ++k2) { const int ks = 2 + k2; ga[k2][0] = ld8(Ab + 16 * ks); ga[k2][1] = ld8(Ab + 32 * LS + 16 * ks); gb[k2][0] = ld8(Bb + 16 * ks); gb[k2][1] = ld8(Bb + 32 * LS + 16 * ks); }
; #pragma unroll
;         for (int k2 = 0; k2 < 2; ++k2) {
;             acc[0][0] = MFMA(ga[k2][0], gb[k2][0], acc[0][0]); acc[0][1] = MFMA(ga[k2][0], gb[k2][1], acc[0][1]);
;             acc[1][0] = MFMA(ga[k2][1], gb[k2][0], acc[1][0]); acc[1][1] = MFMA(ga[k2][1], gb[k2][1], acc[1][1]);
;         }
;         if (kt + 1 < nk) sstore(stset, buf ^ 1, kt + 1);
; #pragma unroll
;         for (int i = 0; i < 8; ++i) { __builtin_amdgcn_sched_group_barrier(0x008, 1, 0); __builtin_amdgcn_sched_group_barrier(0x100, 1, 0); }
; #pragma unroll
;         for (int i = 0; i < 8; ++i) { __builtin_amdgcn_sched_group_barrier(0x008, 1, 0); __builtin_amdgcn_sched_group_barrier(0x200, 1, 0); }
;         __builtin_amdgcn_sched_barrier(0);
;         __syncthreads();
;     };
	s_setprio 1
	ds_read_b128 v[174:177], v196
	ds_read_b128 v[210:213], v197 offset:36864
	ds_read_b128 v[218:221], v197 offset:41472
	ds_read_b128 v[202:205], v196 offset:4608
	ds_read_b128 v[178:181], v196 offset:32
	ds_read_b128 v[222:225], v197 offset:41504
	ds_read_b128 v[206:209], v196 offset:4640
	ds_read_b128 v[214:217], v197 offset:36896
	s_waitcnt lgkmcnt(6)
	v_mfma_f32_32x32x16_bf16 v[52:67], v[174:177], v[210:213], v[52:67]
	global_load_dwordx4 v[88:91], v[164:165], off offset:512
	s_waitcnt lgkmcnt(5)
	v_mfma_f32_32x32x16_bf16 v[36:51], v[174:177], v[218:221], v[36:51]
	global_load_dwordx4 v[96:99], v[162:163], off offset:512
	s_waitcnt lgkmcnt(4)
	v_mfma_f32_32x32x16_bf16 v[4:19], v[202:205], v[218:221], v[4:19]
	global_load_dwordx4 v[100:103], v[160:161], off offset:512
	s_waitcnt lgkmcnt(2)
	v_mfma_f32_32x32x16_bf16 v[36:51], v[178:181], v[222:225], v[36:51]
	global_load_dwordx4 v[108:111], v[158:159], off offset:512
	s_waitcnt lgkmcnt(1)
	v_mfma_f32_32x32x16_bf16 v[4:19], v[206:209], v[222:225], v[4:19]
	global_load_dwordx4 v[116:119], v[156:157], off offset:512
	ds_read_b128 v[222:225], v197 offset:41568
	ds_read_b128 v[174:177], v196 offset:4672
	v_mfma_f32_32x32x16_bf16 v[20:35], v[202:205], v[210:213], v[20:35]
	global_load_dwordx4 v[120:123], v[154:155], off offset:512
	ds_read_b128 v[210:213], v196 offset:4704
	ds_read_b128 v[202:205], v196 offset:64
	s_waitcnt lgkmcnt(4)
	v_mfma_f32_32x32x16_bf16 v[52:67], v[178:181], v[214:217], v[52:67]
	global_load_dwordx4 v[124:127], v[152:153], off offset:512
	ds_read_b128 v[218:221], v197 offset:36960
	ds_read_b128 v[178:181], v197 offset:41536
	v_mfma_f32_32x32x16_bf16 v[20:35], v[206:209], v[214:217], v[20:35]
	global_load_dwordx4 v[128:131], v[146:147], off offset:512
	ds_read_b128 v[214:217], v197 offset:36928
	ds_read_b128 v[206:209], v196 offset:96
	s_waitcnt lgkmcnt(1)
	v_mfma_f32_32x32x16_bf16 v[52:67], v[202:205], v[214:217], v[52:67]
	s_waitcnt vmcnt(23)
	ds_write_b128 v167, v[132:135]
	v_mfma_f32_32x32x16_bf16 v[36:51], v[202:205], v[178:181], v[36:51]
	s_waitcnt vmcnt(22)
	ds_write_b128 v167, v[136:139] offset:36864
	v_mfma_f32_32x32x16_bf16 v[20:35], v[174:177], v[214:217], v[20:35]
	s_waitcnt vmcnt(21)
	ds_write_b128 v190, v[140:143]
	v_mfma_f32_32x32x16_bf16 v[4:19], v[174:177], v[178:181], v[4:19]
	s_setprio 0
	s_waitcnt vmcnt(20)
	ds_write_b128 v190, v[198:201] offset:36864
	s_waitcnt lgkmcnt(4)
	v_mfma_f32_32x32x16_bf16 v[52:67], v[206:209], v[218:221], v[52:67]
	s_waitcnt vmcnt(19)
	ds_write_b128 v191, v[226:229]
	v_mfma_f32_32x32x16_bf16 v[36:51], v[206:209], v[222:225], v[36:51]
	s_waitcnt vmcnt(18)
	ds_write_b128 v191, v[230:233] offset:36864
	v_mfma_f32_32x32x16_bf16 v[20:35], v[210:213], v[218:221], v[20:35]
	s_waitcnt vmcnt(17)
	ds_write_b128 v192, v[242:245]
	v_mfma_f32_32x32x16_bf16 v[4:19], v[210:213], v[222:225], v[4:19]
	s_waitcnt vmcnt(16)
	ds_write_b128 v192, v[246:249] offset:36864
	s_waitcnt lgkmcnt(0)
	s_barrier
	s_setprio 1
	ds_read_b128 v[174:177], v194
	ds_read_b128 v[210:213], v195 offset:36864
	ds_read_b128 v[218:221], v195 offset:41472
	ds_read_b128 v[202:205], v194 offset:4608
	ds_read_b128 v[178:181], v194 offset:32
	ds_read_b128 v[222:225], v195 offset:41504
	ds_read_b128 v[206:209], v194 offset:4640
	ds_read_b128 v[214:217], v195 offset:36896
	s_waitcnt lgkmcnt(6)
	v_mfma_f32_32x32x16_bf16 v[52:67], v[174:177], v[210:213], v[52:67]
	global_load_dwordx4 v[132:135], v[164:165], off offset:640
	s_waitcnt lgkmcnt(5)
	v_mfma_f32_32x32x16_bf16 v[36:51], v[174:177], v[218:221], v[36:51]
	global_load_dwordx4 v[136:139], v[162:163], off offset:640
	s_waitcnt lgkmcnt(4)
	v_mfma_f32_32x32x16_bf16 v[4:19], v[202:205], v[218:221], v[4:19]
	global_load_dwordx4 v[140:143], v[160:161], off offset:640
	s_waitcnt lgkmcnt(2)
	v_mfma_f32_32x32x16_bf16 v[36:51], v[178:181], v[222:225], v[36:51]
	global_load_dwordx4 v[198:201], v[158:159], off offset:640
	s_waitcnt lgkmcnt(1)
	v_mfma_f32_32x32x16_bf16 v[4:19], v[206:209], v[222:225], v[4:19]
	global_load_dwordx4 v[226:229], v[156:157], off offset:640
	ds_read_b128 v[222:225], v195 offset:41568
	ds_read_b128 v[174:177], v194 offset:4672
	v_mfma_f32_32x32x16_bf16 v[20:35], v[202:205], v[210:213], v[20:35]
	global_load_dwordx4 v[230:233], v[154:155], off offset:640
	ds_read_b128 v[210:213], v194 offset:4704
	ds_read_b128 v[202:205], v194 offset:64
	s_waitcnt lgkmcnt(4)
	v_mfma_f32_32x32x16_bf16 v[52:67], v[178:181], v[214:217], v[52:67]
	global_load_dwordx4 v[242:245], v[152:153], off offset:640
	ds_read_b128 v[218:221], v195 offset:36960
	ds_read_b128 v[178:181], v195 offset:41536
	v_mfma_f32_32x32x16_bf16 v[20:35], v[206:209], v[214:217], v[20:35]
	global_load_dwordx4 v[246:249], v[146:147], off offset:640
	ds_read_b128 v[214:217], v195 offset:36928
	ds_read_b128 v[206:209], v194 offset:96
	s_waitcnt lgkmcnt(1)
	v_mfma_f32_32x32x16_bf16 v[52:67], v[202:205], v[214:217], v[52:67]
	s_waitcnt vmcnt(23)
	ds_write_b128 v167, v[68:71] offset:18432
	v_mfma_f32_32x32x16_bf16 v[36:51], v[202:205], v[178:181], v[36:51]
	s_waitcnt vmcnt(22)
	ds_write_b128 v167, v[72:75] offset:55296
	v_mfma_f32_32x32x16_bf16 v[20:35], v[174:177], v[214:217], v[20:35]
	s_waitcnt vmcnt(21)
	ds_write_b128 v190, v[76:79] offset:18432
	v_mfma_f32_32x32x16_bf16 v[4:19], v[174:177], v[178:181], v[4:19]
	s_setprio 0
	s_waitcnt vmcnt(20)
	ds_write_b128 v190, v[80:83] offset:55296
	s_waitcnt lgkmcnt(4)
	v_mfma_f32_32x32x16_bf16 v[52:67], v[206:209], v[218:221], v[52:67]
	s_waitcnt vmcnt(19)
	ds_write_b128 v191, v[84:87] offset:18432
	v_mfma_f32_32x32x16_bf16 v[36:51], v[206:209], v[222:225], v[36:51]
	s_waitcnt vmcnt(18)
	ds_write_b128 v191, v[92:95] offset:55296
	v_mfma_f32_32x32x16_bf16 v[20:35], v[210:213], v[218:221], v[20:35]
	s_waitcnt vmcnt(17)
	ds_write_b128 v192, v[104:107] offset:18432
	v_mfma_f32_32x32x16_bf16 v[4:19], v[210:213], v[222:225], v[4:19]
	s_waitcnt vmcnt(16)
	ds_write_b128 v192, v[112:115] offset:55296
	s_waitcnt lgkmcnt(0)
	s_barrier
; #define MFMA(a, b, c) __builtin_amdgcn_mfma_f32_32x32x16_bf16((a), (b), (c), 0, 0, 0)
; template <class Epi, class ColV>
; DI void gemm_tile(const bf16_t* __restrict__ A, int lda, const bf16_t* __restrict__ Bt, int ldb, int K, int m0, int n0, unsigned char* smem, Epi epi, ColV colv, const bf16_t* __restrict__ HYT = nullptr) {
;     ...
;     auto step = [&](int kt, u32x4 (&ldset)[8], const u32x4 (&stset)[8]) {
;         const int buf = kt & 1;
;         if (kt + 2 < nk) gload(ldset, kt + 2);
;         const bf16_t* Ab = As + (buf * 128 + 64 * wr + li) * LS + 8 * lh;
;         const bf16_t* Bb = Bs + (buf * 128 + 64 * wc + li) * LS + 8 * lh;
;         bf16x8 fa[2][2], fb[2][2], ga[2][2], gb[2][2];
; #pragma unroll
;         for (int k2 = 0; k2 < 2; ++k2) { fa[k2][0] = ld8(Ab + 16 * k2); fa[k2][1] = ld8(Ab + 32 * LS + 16 * k2); fb[k2][0] = ld8(Bb + 16 * k2); fb[k2][1] = ld8(Bb + 32 * LS + 16 * k2); }
;         __builtin_amdgcn_sched_barrier(0);
; #pragma unroll
;         for (int k2 = 0; k2 < 2; ++k2) {
;             acc[0][0] = MFMA(fa[k2][0], fb[k2][0], acc[0][0]); acc[0][1] = MFMA(fa[k2][0], fb[k2][1], acc[0][1]);
;             acc[1][0] = MFMA(fa[k2][1], fb[k2][0], acc[1][0]); acc[1][1] = MFMA(fa[k2][1], fb[k2][1], acc[1][1]);
;         }
; #pragma unroll
;         for (int k2 = 0; k2 < 2; ++k2) { const int ks = 2 + k2; ga[k2][0] = ld8(Ab + 16 * ks); ga[k2][1] = ld8(Ab + 32 * LS + 16 * ks); gb[k2][0] = ld8(Bb + 16 * ks); gb[k2][1] = ld8(Bb + 32 * LS + 16 * ks); }
; #pragma unroll
;         for (int k2 = 0; k2 < 2; ++k2) {
;             acc[0][0] = MFMA(ga[k2][0], gb[k2][0], acc[0][0]); acc[0][1] = MFMA(ga[k2][0], gb[k2][1], acc[0][1]);
;             acc[1][0] = MFMA(ga[k2][1], gb[k2][0], acc[1][0]); acc[1][1] = MFMA(ga[k2][1], gb[k2][1], acc[1][1]);
;         }
;         if (kt + 1 < nk) sstore(stset, buf ^ 1, kt + 1);
; #pragma unroll
;         for (int i = 0; i < 8; ++i) { __builtin_amdgcn_sched_group_barrier(0x008, 1, 0); __builtin_amdgcn_sched_group_barrier(0x100, 1, 0); }
; #pragma unroll
;         for (int i = 0; i < 8; ++i) { __builtin_amdgcn_sched_group_barrier(0x008, 1, 0); __builtin_amdgcn_sched_group_barrier(0x200, 1, 0); }
;         __builtin_amdgcn_sched_barrier(0);
;         __syncthreads();
;     };
	s_setprio 1
	ds_read_b128 v[174:177], v196
	ds_read_b128 v[210:213], v197 offset:36864
	ds_read_b128 v[218:221], v197 offset:41472
	ds_read_b128 v[202:205], v196 offset:4608
	ds_read_b128 v[178:181], v196 offset:32
	ds_read_b128 v[222:225], v197 offset:41504
	ds_read_b128 v[206:209], v196 offset:4640
	ds_read_b128 v[214:217], v197 offset:36896
	s_waitcnt lgkmcnt(6)
	v_mfma_f32_32x32x16_bf16 v[52:67], v[174:177], v[210:213], v[52:67]
	global_load_dwordx4 v[68:71], v[164:165], off offset:768
	s_waitcnt lgkmcnt(5)
	v_mfma_f32_32x32x16_bf16 v[36:51], v[174:177], v[218:221], v[36:51]
	global_load_dwordx4 v[72:75], v[162:163], off offset:768
	s_waitcnt lgkmcnt(4)
	v_mfma_f32_32x32x16_bf16 v[4:19], v[202:205], v[218:221], v[4:19]
	global_load_dwordx4 v[76:79], v[160:161], off offset:768
	s_waitcnt lgkmcnt(2)
	v_mfma_f32_32x32x16_bf16 v[36:51], v[178:181], v[222:225], v[36:51]
	global_load_dwordx4 v[80:83], v[158:159], off offset:768
	s_waitcnt lgkmcnt(1)
	v_mfma_f32_32x32x16_bf16 v[4:19], v[206:209], v[222:225], v[4:19]
	global_load_dwordx4 v[84:87], v[156:157], off offset:768
	ds_read_b128 v[222:225], v197 offset:41568
	ds_read_b128 v[174:177], v196 offset:4672
	v_mfma_f32_32x32x16_bf16 v[20:35], v[202:205], v[210:213], v[20:35]
	global_load_dwordx4 v[92:95], v[154:155], off offset:768
	ds_read_b128 v[210:213], v196 offset:4704
	ds_read_b128 v[202:205], v196 offset:64
	s_waitcnt lgkmcnt(4)
	v_mfma_f32_32x32x16_bf16 v[52:67], v[178:181], v[214:217], v[52:67]
	global_load_dwordx4 v[104:107], v[152:153], off offset:768
	ds_read_b128 v[218:221], v197 offset:36960
	ds_read_b128 v[178:181], v197 offset:41536
	v_mfma_f32_32x32x16_bf16 v[20:35], v[206:209], v[214:217], v[20:35]
	global_load_dwordx4 v[112:115], v[146:147], off offset:768
	ds_read_b128 v[214:217], v197 offset:36928
	ds_read_b128 v[206:209], v196 offset:96
	s_waitcnt lgkmcnt(1)
	v_mfma_f32_32x32x16_bf16 v[52:67], v[202:205], v[214:217], v[52:67]
	s_waitcnt vmcnt(23)
	ds_write_b128 v167, v[88:91]
	v_mfma_f32_32x32x16_bf16 v[36:51], v[202:205], v[178:181], v[36:51]
	s_waitcnt vmcnt(22)
	ds_write_b128 v167, v[96:99] offset:36864
	v_mfma_f32_32x32x16_bf16 v[20:35], v[174:177], v[214:217], v[20:35]
	s_waitcnt vmcnt(21)
	ds_write_b128 v190, v[100:103]
	v_mfma_f32_32x32x16_bf16 v[4:19], v[174:177], v[178:181], v[4:19]
	s_setprio 0
	s_waitcnt vmcnt(20)
	ds_write_b128 v190, v[108:111] offset:36864
	s_waitcnt lgkmcnt(4)
	v_mfma_f32_32x32x16_bf16 v[52:67], v[206:209], v[218:221], v[52:67]
	s_waitcnt vmcnt(19)
	ds_write_b128 v191, v[116:119]
	v_mfma_f32_32x32x16_bf16 v[36:51], v[206:209], v[222:225], v[36:51]
	s_waitcnt vmcnt(18)
	ds_write_b128 v191, v[120:123] offset:36864
	v_mfma_f32_32x32x16_bf16 v[20:35], v[210:213], v[218:221], v[20:35]
	s_waitcnt vmcnt(17)
	ds_write_b128 v192, v[124:127]
	v_mfma_f32_32x32x16_bf16 v[4:19], v[210:213], v[222:225], v[4:19]
	s_waitcnt vmcnt(16)
	ds_write_b128 v192, v[128:131] offset:36864
	s_waitcnt lgkmcnt(0)
	s_barrier
	s_setprio 1
	ds_read_b128 v[174:177], v194
	ds_read_b128 v[210:213], v195 offset:36864
	ds_read_b128 v[218:221], v195 offset:41472
	ds_read_b128 v[202:205], v194 offset:4608
	ds_read_b128 v[178:181], v194 offset:32
	ds_read_b128 v[222:225], v195 offset:41504
	ds_read_b128 v[206:209], v194 offset:4640
	ds_read_b128 v[214:217], v195 offset:36896
	s_waitcnt lgkmcnt(6)
	v_mfma_f32_32x32x16_bf16 v[52:67], v[174:177], v[210:213], v[52:67]
	global_load_dwordx4 v[88:91], v[164:165], off offset:896
	s_waitcnt lgkmcnt(5)
	v_mfma_f32_32x32x16_bf16 v[36:51], v[174:177], v[218:221], v[36:51]
	global_load_dwordx4 v[96:99], v[162:163], off offset:896
	s_waitcnt lgkmcnt(4)
	v_mfma_f32_32x32x16_bf16 v[4:19], v[202:205], v[218:221], v[4:19]
	global_load_dwordx4 v[100:103], v[160:161], off offset:896
	s_waitcnt lgkmcnt(2)
	v_mfma_f32_32x32x16_bf16 v[36:51], v[178:181], v[222:225], v[36:51]
	global_load_dwordx4 v[108:111], v[158:159], off offset:896
	s_waitcnt lgkmcnt(1)
	v_mfma_f32_32x32x16_bf16 v[4:19], v[206:209], v[222:225], v[4:19]
	global_load_dwordx4 v[116:119], v[156:157], off offset:896
	ds_read_b128 v[222:225], v195 offset:41568
	ds_read_b128 v[174:177], v194 offset:4672
	v_mfma_f32_32x32x16_bf16 v[20:35], v[202:205], v[210:213], v[20:35]
	global_load_dwordx4 v[120:123], v[154:155], off offset:896
	ds_read_b128 v[210:213], v194 offset:4704
	ds_read_b128 v[202:205], v194 offset:64
	s_waitcnt lgkmcnt(4)
	v_mfma_f32_32x32x16_bf16 v[52:67], v[178:181], v[214:217], v[52:67]
	global_load_dwordx4 v[124:127], v[152:153], off offset:896
	ds_read_b128 v[218:221], v195 offset:36960
	ds_read_b128 v[178:181], v195 offset:41536
	v_mfma_f32_32x32x16_bf16 v[20:35], v[206:209], v[214:217], v[20:35]
	global_load_dwordx4 v[128:131], v[146:147], off offset:896
	ds_read_b128 v[214:217], v195 offset:36928
	ds_read_b128 v[206:209], v194 offset:96
	s_waitcnt lgkmcnt(1)
	v_mfma_f32_32x32x16_bf16 v[52:67], v[202:205], v[214:217], v[52:67]
	s_waitcnt vmcnt(23)
	ds_write_b128 v167, v[132:135] offset:18432
	v_mfma_f32_32x32x16_bf16 v[36:51], v[202:205], v[178:181], v[36:51]
	s_waitcnt vmcnt(22)
	ds_write_b128 v167, v[136:139] offset:55296
	v_mfma_f32_32x32x16_bf16 v[20:35], v[174:177], v[214:217], v[20:35]
	s_waitcnt vmcnt(21)
	ds_write_b128 v190, v[140:143] offset:18432
	v_mfma_f32_32x32x16_bf16 v[4:19], v[174:177], v[178:181], v[4:19]
	s_setprio 0
	s_waitcnt vmcnt(20)
	ds_write_b128 v190, v[198:201] offset:55296
	s_waitcnt lgkmcnt(4)
	v_mfma_f32_32x32x16_bf16 v[52:67], v[206:209], v[218:221], v[52:67]
	s_waitcnt vmcnt(19)
	ds_write_b128 v191, v[226:229] offset:18432
	v_mfma_f32_32x32x16_bf16 v[36:51], v[206:209], v[222:225], v[36:51]
	s_waitcnt vmcnt(18)
	ds_write_b128 v191, v[230:233] offset:55296
	v_mfma_f32_32x32x16_bf16 v[20:35], v[210:213], v[218:221], v[20:35]
	s_waitcnt vmcnt(17)
	ds_write_b128 v192, v[242:245] offset:18432
	v_mfma_f32_32x32x16_bf16 v[4:19], v[210:213], v[222:225], v[4:19]
	s_waitcnt vmcnt(16)
	ds_write_b128 v192, v[246:249] offset:55296
	s_waitcnt lgkmcnt(0)
	s_barrier
; #define MFMA(a, b, c) __builtin_amdgcn_mfma_f32_32x32x16_bf16((a), (b), (c), 0, 0, 0)
; template <class Epi, class ColV>
; DI void gemm_tile(const bf16_t* __restrict__ A, int lda, const bf16_t* __restrict__ Bt, int ldb, int K, int m0, int n0, unsigned char* smem, Epi epi, ColV colv, const bf16_t* __restrict__ HYT = nullptr) {
;     ...
;     auto step = [&](int kt, u32x4 (&ldset)[8], const u32x4 (&stset)[8]) {
;         const int buf = kt & 1;
;         if (kt + 2 < nk) gload(ldset, kt + 2);
;         const bf16_t* Ab = As + (buf * 128 + 64 * wr + li) * LS + 8 * lh;
;         const bf16_t* Bb = Bs + (buf * 128 + 64 * wc + li) * LS + 8 * lh;
;         bf16x8 fa[2][2], fb[2][2], ga[2][2], gb[2][2];
; #pragma unroll
;         for (int k2 = 0; k2 < 2; ++k2) { fa[k2][0] = ld8(Ab + 16 * k2); fa[k2][1] = ld8(Ab + 32 * LS + 16 * k2); fb[k2][0] = ld8(Bb + 16 * k2); fb[k2][1] = ld8(Bb + 32 * LS + 16 * k2); }
;         __builtin_amdgcn_sched_barrier(0);
; #pragma unroll
;         for (int k2 = 0; k2 < 2; ++k2) {
;             acc[0][0] = MFMA(fa[k2][0], fb[k2][0], acc[0][0]); acc[0][1] = MFMA(fa[k2][0], fb[k2][1], acc[0][1]);
;             acc[1][0] = MFMA(fa[k2][1], fb[k2][0], acc[1][0]); acc[1][1] = MFMA(fa[k2][1], fb[k2][1], acc[1][1]);
;         }
; #pragma unroll
;         for (int k2 = 0; k2 < 2; ++k2) { const int ks = 2 + k2; ga[k2][0] = ld8(Ab + 16 * ks); ga[k2][1] = ld8(Ab + 32 * LS + 16 * ks); gb[k2][0] = ld8(Bb + 16 * ks); gb[k2][1] = ld8(Bb + 32 * LS + 16 * ks); }
; #pragma unroll
;         for (int k2 = 0; k2 < 2; ++k2) {
;             acc[0][0] = MFMA(ga[k2][0], gb[k2][0], acc[0][0]); acc[0][1] = MFMA(ga[k2][0], gb[k2][1], acc[0][1]);
;             acc[1][0] = MFMA(ga[k2][1], gb[k2][0], acc[1][0]); acc[1][1] = MFMA(ga[k2][1], gb[k2][1], acc[1][1]);
;         }
;         if (kt + 1 < nk) sstore(stset, buf ^ 1, kt + 1);
; #pragma unroll
;         for (int i = 0; i < 8; ++i) { __builtin_amdgcn_sched_group_barrier(0x008, 1, 0); __builtin_amdgcn_sched_group_barrier(0x100, 1, 0); }
; #pragma unroll
;         for (int i = 0; i < 8; ++i) { __builtin_amdgcn_sched_group_barrier(0x008, 1, 0); __builtin_amdgcn_sched_group_barrier(0x200, 1, 0); }
;         __builtin_amdgcn_sched_barrier(0);
;         __syncthreads();
;     };
	s_setprio 1
	ds_read_b128 v[174:177], v196
	ds_read_b128 v[210:213], v197 offset:36864
	ds_read_b128 v[218:221], v197 offset:41472
	ds_read_b128 v[202:205], v196 offset:4608
	ds_read_b128 v[178:181], v196 offset:32
	ds_read_b128 v[222:225], v197 offset:41504
	ds_read_b128 v[206:209], v196 offset:4640
	ds_read_b128 v[214:217], v197 offset:36896
	s_waitcnt lgkmcnt(6)
	v_mfma_f32_32x32x16_bf16 v[52:67], v[174:177], v[210:213], v[52:67]
	global_load_dwordx4 v[132:135], v[164:165], off offset:1024
	s_waitcnt lgkmcnt(5)
	v_mfma_f32_32x32x16_bf16 v[36:51], v[174:177], v[218:221], v[36:51]
	global_load_dwordx4 v[136:139], v[162:163], off offset:1024
	s_waitcnt lgkmcnt(4)
	v_mfma_f32_32x32x16_bf16 v[4:19], v[202:205], v[218:221], v[4:19]
	global_load_dwordx4 v[140:143], v[160:161], off offset:1024
	s_waitcnt lgkmcnt(2)
	v_mfma_f32_32x32x16_bf16 v[36:51], v[178:181], v[222:225], v[36:51]
	global_load_dwordx4 v[198:201], v[158:159], off offset:1024
	s_waitcnt lgkmcnt(1)
	v_mfma_f32_32x32x16_bf16 v[4:19], v[206:209], v[222:225], v[4:19]
	global_load_dwordx4 v[226:229], v[156:157], off offset:1024
	ds_read_b128 v[222:225], v197 offset:41568
	ds_read_b128 v[174:177], v196 offset:4672
	v_mfma_f32_32x32x16_bf16 v[20:35], v[202:205], v[210:213], v[20:35]
	global_load_dwordx4 v[230:233], v[154:155], off offset:1024
	ds_read_b128 v[210:213], v196 offset:4704
	ds_read_b128 v[202:205], v196 offset:64
	s_waitcnt lgkmcnt(4)
	v_mfma_f32_32x32x16_bf16 v[52:67], v[178:181], v[214:217], v[52:67]
	global_load_dwordx4 v[242:245], v[152:153], off offset:1024
	ds_read_b128 v[218:221], v197 offset:36960
	ds_read_b128 v[178:181], v197 offset:41536
	v_mfma_f32_32x32x16_bf16 v[20:35], v[206:209], v[214:217], v[20:35]
	global_load_dwordx4 v[246:249], v[146:147], off offset:1024
	ds_read_b128 v[214:217], v197 offset:36928
	ds_read_b128 v[206:209], v196 offset:96
	s_waitcnt lgkmcnt(1)
	v_mfma_f32_32x32x16_bf16 v[52:67], v[202:205], v[214:217], v[52:67]
	s_waitcnt vmcnt(23)
	ds_write_b128 v167, v[68:71]
	v_mfma_f32_32x32x16_bf16 v[36:51], v[202:205], v[178:181], v[36:51]
	s_waitcnt vmcnt(22)
	ds_write_b128 v167, v[72:75] offset:36864
	v_mfma_f32_32x32x16_bf16 v[20:35], v[174:177], v[214:217], v[20:35]
	s_waitcnt vmcnt(21)
	ds_write_b128 v190, v[76:79]
	v_mfma_f32_32x32x16_bf16 v[4:19], v[174:177], v[178:181], v[4:19]
	s_setprio 0
	s_waitcnt vmcnt(20)
	ds_write_b128 v190, v[80:83] offset:36864
	s_waitcnt lgkmcnt(4)
	v_mfma_f32_32x32x16_bf16 v[52:67], v[206:209], v[218:221], v[52:67]
	s_waitcnt vmcnt(19)
	ds_write_b128 v191, v[84:87]
	v_mfma_f32_32x32x16_bf16 v[36:51], v[206:209], v[222:225], v[36:51]
	s_waitcnt vmcnt(18)
	ds_write_b128 v191, v[92:95] offset:36864
	v_mfma_f32_32x32x16_bf16 v[20:35], v[210:213], v[218:221], v[20:35]
	s_waitcnt vmcnt(17)
	ds_write_b128 v192, v[104:107]
	v_mfma_f32_32x32x16_bf16 v[4:19], v[210:213], v[222:225], v[4:19]
	s_waitcnt vmcnt(16)
	ds_write_b128 v192, v[112:115] offset:36864
	s_waitcnt lgkmcnt(0)
	s_barrier
	s_setprio 1
	ds_read_b128 v[174:177], v194
	ds_read_b128 v[210:213], v195 offset:36864
	ds_read_b128 v[218:221], v195 offset:41472
	ds_read_b128 v[202:205], v194 offset:4608
	ds_read_b128 v[178:181], v194 offset:32
	ds_read_b128 v[222:225], v195 offset:41504
	ds_read_b128 v[206:209], v194 offset:4640
	ds_read_b128 v[214:217], v195 offset:36896
	s_waitcnt lgkmcnt(6)
	v_mfma_f32_32x32x16_bf16 v[52:67], v[174:177], v[210:213], v[52:67]
	global_load_dwordx4 v[68:71], v[164:165], off offset:1152
	s_waitcnt lgkmcnt(5)
	v_mfma_f32_32x32x16_bf16 v[36:51], v[174:177], v[218:221], v[36:51]
	global_load_dwordx4 v[72:75], v[162:163], off offset:1152
	s_waitcnt lgkmcnt(4)
	v_mfma_f32_32x32x16_bf16 v[4:19], v[202:205], v[218:221], v[4:19]
	global_load_dwordx4 v[76:79], v[160:161], off offset:1152
	s_waitcnt lgkmcnt(2)
	v_mfma_f32_32x32x16_bf16 v[36:51], v[178:181], v[222:225], v[36:51]
	global_load_dwordx4 v[80:83], v[158:159], off offset:1152
	s_waitcnt lgkmcnt(1)
	v_mfma_f32_32x32x16_bf16 v[4:19], v[206:209], v[222:225], v[4:19]
	global_load_dwordx4 v[84:87], v[156:157], off offset:1152
	ds_read_b128 v[222:225], v195 offset:41568
	ds_read_b128 v[174:177], v194 offset:4672
	v_mfma_f32_32x32x16_bf16 v[20:35], v[202:205], v[210:213], v[20:35]
	global_load_dwordx4 v[92:95], v[154:155], off offset:1152
	ds_read_b128 v[210:213], v194 offset:4704
	ds_read_b128 v[202:205], v194 offset:64
	s_waitcnt lgkmcnt(4)
	v_mfma_f32_32x32x16_bf16 v[52:67], v[178:181], v[214:217], v[52:67]
	global_load_dwordx4 v[104:107], v[152:153], off offset:1152
	ds_read_b128 v[218:221], v195 offset:36960
	ds_read_b128 v[178:181], v195 offset:41536
	v_mfma_f32_32x32x16_bf16 v[20:35], v[206:209], v[214:217], v[20:35]
	global_load_dwordx4 v[112:115], v[146:147], off offset:1152
	ds_read_b128 v[214:217], v195 offset:36928
	ds_read_b128 v[206:209], v194 offset:96
	s_waitcnt lgkmcnt(1)
	v_mfma_f32_32x32x16_bf16 v[52:67], v[202:205], v[214:217], v[52:67]
	s_waitcnt vmcnt(23)
	ds_write_b128 v167, v[88:91] offset:18432
	v_mfma_f32_32x32x16_bf16 v[36:51], v[202:205], v[178:181], v[36:51]
	s_waitcnt vmcnt(22)
	ds_write_b128 v167, v[96:99] offset:55296
	v_mfma_f32_32x32x16_bf16 v[20:35], v[174:177], v[214:217], v[20:35]
	s_waitcnt vmcnt(21)
	ds_write_b128 v190, v[100:103] offset:18432
	v_mfma_f32_32x32x16_bf16 v[4:19], v[174:177], v[178:181], v[4:19]
	s_setprio 0
	s_waitcnt vmcnt(20)
	ds_write_b128 v190, v[108:111] offset:55296
	s_waitcnt lgkmcnt(4)
	v_mfma_f32_32x32x16_bf16 v[52:67], v[206:209], v[218:221], v[52:67]
	s_waitcnt vmcnt(19)
	ds_write_b128 v191, v[116:119] offset:18432
	v_mfma_f32_32x32x16_bf16 v[36:51], v[206:209], v[222:225], v[36:51]
	s_waitcnt vmcnt(18)
	ds_write_b128 v191, v[120:123] offset:55296
	v_mfma_f32_32x32x16_bf16 v[20:35], v[210:213], v[218:221], v[20:35]
	s_waitcnt vmcnt(17)
	ds_write_b128 v192, v[124:127] offset:18432
	v_mfma_f32_32x32x16_bf16 v[4:19], v[210:213], v[222:225], v[4:19]
	s_waitcnt vmcnt(16)
	ds_write_b128 v192, v[128:131] offset:55296
	s_waitcnt lgkmcnt(0)
	s_barrier
; #define MFMA(a, b, c) __builtin_amdgcn_mfma_f32_32x32x16_bf16((a), (b), (c), 0, 0, 0)
; template <class Epi, class ColV>
; DI void gemm_tile(const bf16_t* __restrict__ A, int lda, const bf16_t* __restrict__ Bt, int ldb, int K, int m0, int n0, unsigned char* smem, Epi epi, ColV colv, const bf16_t* __restrict__ HYT = nullptr) {
;     ...
;     auto step = [&](int kt, u32x4 (&ldset)[8], const u32x4 (&stset)[8]) {
;         const int buf = kt & 1;
;         if (kt + 2 < nk) gload(ldset, kt + 2);
;         const bf16_t* Ab = As + (buf * 128 + 64 * wr + li) * LS + 8 * lh;
;         const bf16_t* Bb = Bs + (buf * 128 + 64 * wc + li) * LS + 8 * lh;
;         bf16x8 fa[2][2], fb[2][2], ga[2][2], gb[2][2];
; #pragma unroll
;         for (int k2 = 0; k2 < 2; ++k2) { fa[k2][0] = ld8(Ab + 16 * k2); fa[k2][1] = ld8(Ab + 32 * LS + 16 * k2); fb[k2][0] = ld8(Bb + 16 * k2); fb[k2][1] = ld8(Bb + 32 * LS + 16 * k2); }
;         __builtin_amdgcn_sched_barrier(0);
; #pragma unroll
;         for (int k2 = 0; k2 < 2; ++k2) {
;             acc[0][0] = MFMA(fa[k2][0], fb[k2][0], acc[0][0]); acc[0][1] = MFMA(fa[k2][0], fb[k2][1], acc[0][1]);
;             acc[1][0] = MFMA(fa[k2][1], fb[k2][0], acc[1][0]); acc[1][1] = MFMA(fa[k2][1], fb[k2][1], acc[1][1]);
;         }
; #pragma unroll
;         for (int k2 = 0; k2 < 2; ++k2) { const int ks = 2 + k2; ga[k2][0] = ld8(Ab + 16 * ks); ga[k2][1] = ld8(Ab + 32 * LS + 16 * ks); gb[k2][0] = ld8(Bb + 16 * ks); gb[k2][1] = ld8(Bb + 32 * LS + 16 * ks); }
; #pragma unroll
;         for (int k2 = 0; k2 < 2; ++k2) {
;             acc[0][0] = MFMA(ga[k2][0], gb[k2][0], acc[0][0]); acc[0][1] = MFMA(ga[k2][0], gb[k2][1], acc[0][1]);
;             acc[1][0] = MFMA(ga[k2][1], gb[k2][0], acc[1][0]); acc[1][1] = MFMA(ga[k2][1], gb[k2][1], acc[1][1]);
;         }
;         if (kt + 1 < nk) sstore(stset, buf ^ 1, kt + 1);
; #pragma unroll
;         for (int i = 0; i < 8; ++i) { __builtin_amdgcn_sched_group_barrier(0x008, 1, 0); __builtin_amdgcn_sched_group_barrier(0x100, 1, 0); }
; #pragma unroll
;         for (int i = 0; i < 8; ++i) { __builtin_amdgcn_sched_group_barrier(0x008, 1, 0); __builtin_amdgcn_sched_group_barrier(0x200, 1, 0); }
;         __builtin_amdgcn_sched_barrier(0);
;         __syncthreads();
;     };
	s_setprio 1
	ds_read_b128 v[174:177], v196
	ds_read_b128 v[210:213], v197 offset:36864
	ds_read_b128 v[218:221], v197 offset:41472
	ds_read_b128 v[202:205], v196 offset:4608
	ds_read_b128 v[178:181], v196 offset:32
	ds_read_b128 v[222:225], v197 offset:41504
	ds_read_b128 v[206:209], v196 offset:4640
	ds_read_b128 v[214:217], v197 offset:36896
	s_waitcnt lgkmcnt(6)
	v_mfma_f32_32x32x16_bf16 v[52:67], v[174:177], v[210:213], v[52:67]
	global_load_dwordx4 v[88:91], v[164:165], off offset:1280
	s_waitcnt lgkmcnt(5)
	v_mfma_f32_32x32x16_bf16 v[36:51], v[174:177], v[218:221], v[36:51]
	global_load_dwordx4 v[96:99], v[162:163], off offset:1280
	s_waitcnt lgkmcnt(4)
	v_mfma_f32_32x32x16_bf16 v[4:19], v[202:205], v[218:221], v[4:19]
	global_load_dwordx4 v[100:103], v[160:161], off offset:1280
	s_waitcnt lgkmcnt(2)
	v_mfma_f32_32x32x16_bf16 v[36:51], v[178:181], v[222:225], v[36:51]
	global_load_dwordx4 v[108:111], v[158:159], off offset:1280
	s_waitcnt lgkmcnt(1)
	v_mfma_f32_32x32x16_bf16 v[4:19], v[206:209], v[222:225], v[4:19]
	global_load_dwordx4 v[116:119], v[156:157], off offset:1280
	ds_read_b128 v[222:225], v197 offset:41568
	ds_read_b128 v[174:177], v196 offset:4672
	v_mfma_f32_32x32x16_bf16 v[20:35], v[202:205], v[210:213], v[20:35]
	global_load_dwordx4 v[120:123], v[154:155], off offset:1280
	ds_read_b128 v[210:213], v196 offset:4704
	ds_read_b128 v[202:205], v196 offset:64
	s_waitcnt lgkmcnt(4)
	v_mfma_f32_32x32x16_bf16 v[52:67], v[178:181], v[214:217], v[52:67]
	global_load_dwordx4 v[124:127], v[152:153], off offset:1280
	ds_read_b128 v[218:221], v197 offset:36960
	ds_read_b128 v[178:181], v197 offset:41536
	v_mfma_f32_32x32x16_bf16 v[20:35], v[206:209], v[214:217], v[20:35]
	global_load_dwordx4 v[128:131], v[146:147], off offset:1280
	ds_read_b128 v[214:217], v197 offset:36928
	ds_read_b128 v[206:209], v196 offset:96
	s_waitcnt lgkmcnt(1)
	v_mfma_f32_32x32x16_bf16 v[52:67], v[202:205], v[214:217], v[52:67]
	s_waitcnt vmcnt(23)
	ds_write_b128 v167, v[132:135]
	v_mfma_f32_32x32x16_bf16 v[36:51], v[202:205], v[178:181], v[36:51]
	s_waitcnt vmcnt(22)
	ds_write_b128 v167, v[136:139] offset:36864
	v_mfma_f32_32x32x16_bf16 v[20:35], v[174:177], v[214:217], v[20:35]
	s_waitcnt vmcnt(21)
	ds_write_b128 v190, v[140:143]
	v_mfma_f32_32x32x16_bf16 v[4:19], v[174:177], v[178:181], v[4:19]
	s_setprio 0
	s_waitcnt vmcnt(20)
	ds_write_b128 v190, v[198:201] offset:36864
	s_waitcnt lgkmcnt(4)
	v_mfma_f32_32x32x16_bf16 v[52:67], v[206:209], v[218:221], v[52:67]
	s_waitcnt vmcnt(19)
	ds_write_b128 v191, v[226:229]
	v_mfma_f32_32x32x16_bf16 v[36:51], v[206:209], v[222:225], v[36:51]
	s_waitcnt vmcnt(18)
	ds_write_b128 v191, v[230:233] offset:36864
	v_mfma_f32_32x32x16_bf16 v[20:35], v[210:213], v[218:221], v[20:35]
	s_waitcnt vmcnt(17)
	ds_write_b128 v192, v[242:245]
	v_mfma_f32_32x32x16_bf16 v[4:19], v[210:213], v[222:225], v[4:19]
	s_waitcnt vmcnt(16)
	ds_write_b128 v192, v[246:249] offset:36864
	s_waitcnt lgkmcnt(0)
	s_barrier
	s_setprio 1
	ds_read_b128 v[174:177], v194
	ds_read_b128 v[210:213], v195 offset:36864
	ds_read_b128 v[218:221], v195 offset:41472
	ds_read_b128 v[202:205], v194 offset:4608
	ds_read_b128 v[178:181], v194 offset:32
	ds_read_b128 v[222:225], v195 offset:41504
	ds_read_b128 v[206:209], v194 offset:4640
	ds_read_b128 v[214:217], v195 offset:36896
	s_waitcnt lgkmcnt(6)
	v_mfma_f32_32x32x16_bf16 v[52:67], v[174:177], v[210:213], v[52:67]
	global_load_dwordx4 v[132:135], v[164:165], off offset:1408
	s_waitcnt lgkmcnt(5)
	v_mfma_f32_32x32x16_bf16 v[36:51], v[174:177], v[218:221], v[36:51]
	global_load_dwordx4 v[136:139], v[162:163], off offset:1408
	s_waitcnt lgkmcnt(4)
	v_mfma_f32_32x32x16_bf16 v[4:19], v[202:205], v[218:221], v[4:19]
	global_load_dwordx4 v[140:143], v[160:161], off offset:1408
	s_waitcnt lgkmcnt(2)
	v_mfma_f32_32x32x16_bf16 v[36:51], v[178:181], v[222:225], v[36:51]
	global_load_dwordx4 v[198:201], v[158:159], off offset:1408
	s_waitcnt lgkmcnt(1)
	v_mfma_f32_32x32x16_bf16 v[4:19], v[206:209], v[222:225], v[4:19]
	global_load_dwordx4 v[226:229], v[156:157], off offset:1408
	ds_read_b128 v[222:225], v195 offset:41568
	ds_read_b128 v[174:177], v194 offset:4672
	v_mfma_f32_32x32x16_bf16 v[20:35], v[202:205], v[210:213], v[20:35]
	global_load_dwordx4 v[230:233], v[154:155], off offset:1408
	ds_read_b128 v[210:213], v194 offset:4704
	ds_read_b128 v[202:205], v194 offset:64
	s_waitcnt lgkmcnt(4)
	v_mfma_f32_32x32x16_bf16 v[52:67], v[178:181], v[214:217], v[52:67]
	global_load_dwordx4 v[242:245], v[152:153], off offset:1408
	ds_read_b128 v[218:221], v195 offset:36960
	ds_read_b128 v[178:181], v195 offset:41536
	v_mfma_f32_32x32x16_bf16 v[20:35], v[206:209], v[214:217], v[20:35]
	global_load_dwordx4 v[246:249], v[146:147], off offset:1408
	ds_read_b128 v[214:217], v195 offset:36928
	ds_read_b128 v[206:209], v194 offset:96
	s_waitcnt lgkmcnt(1)
	v_mfma_f32_32x32x16_bf16 v[52:67], v[202:205], v[214:217], v[52:67]
	s_waitcnt vmcnt(23)
	ds_write_b128 v167, v[68:71] offset:18432
	v_mfma_f32_32x32x16_bf16 v[36:51], v[202:205], v[178:181], v[36:51]
	s_waitcnt vmcnt(22)
	ds_write_b128 v167, v[72:75] offset:55296
	v_mfma_f32_32x32x16_bf16 v[20:35], v[174:177], v[214:217], v[20:35]
	s_waitcnt vmcnt(21)
	ds_write_b128 v190, v[76:79] offset:18432
	v_mfma_f32_32x32x16_bf16 v[4:19], v[174:177], v[178:181], v[4:19]
	s_setprio 0
	s_waitcnt vmcnt(20)
	ds_write_b128 v190, v[80:83] offset:55296
	s_waitcnt lgkmcnt(4)
	v_mfma_f32_32x32x16_bf16 v[52:67], v[206:209], v[218:221], v[52:67]
	s_waitcnt vmcnt(19)
	ds_write_b128 v191, v[84:87] offset:18432
	v_mfma_f32_32x32x16_bf16 v[36:51], v[206:209], v[222:225], v[36:51]
	s_waitcnt vmcnt(18)
	ds_write_b128 v191, v[92:95] offset:55296
	v_mfma_f32_32x32x16_bf16 v[20:35], v[210:213], v[218:221], v[20:35]
	s_waitcnt vmcnt(17)
	ds_write_b128 v192, v[104:107] offset:18432
	v_mfma_f32_32x32x16_bf16 v[4:19], v[210:213], v[222:225], v[4:19]
	s_waitcnt vmcnt(16)
	ds_write_b128 v192, v[112:115] offset:55296
	s_waitcnt lgkmcnt(0)
	s_barrier
; #define MFMA(a, b, c) __builtin_amdgcn_mfma_f32_32x32x16_bf16((a), (b), (c), 0, 0, 0)
; template <class Epi, class ColV>
; DI void gemm_tile(const bf16_t* __restrict__ A, int lda, const bf16_t* __restrict__ Bt, int ldb, int K, int m0, int n0, unsigned char* smem, Epi epi, ColV colv, const bf16_t* __restrict__ HYT = nullptr) {
;     ...
;     auto step = [&](int kt, u32x4 (&ldset)[8], const u32x4 (&stset)[8]) {
;         const int buf = kt & 1;
;         if (kt + 2 < nk) gload(ldset, kt + 2);
;         const bf16_t* Ab = As + (buf * 128 + 64 * wr + li) * LS + 8 * lh;
;         const bf16_t* Bb = Bs + (buf * 128 + 64 * wc + li) * LS + 8 * lh;
;         bf16x8 fa[2][2], fb[2][2], ga[2][2], gb[2][2];
; #pragma unroll
;         for (int k2 = 0; k2 < 2; ++k2) { fa[k2][0] = ld8(Ab + 16 * k2); fa[k2][1] = ld8(Ab + 32 * LS + 16 * k2); fb[k2][0] = ld8(Bb + 16 * k2); fb[k2][1] = ld8(Bb + 32 * LS + 16 * k2); }
;         __builtin_amdgcn_sched_barrier(0);
; #pragma unroll
;         for (int k2 = 0; k2 < 2; ++k2) {
;             acc[0][0] = MFMA(fa[k2][0], fb[k2][0], acc[0][0]); acc[0][1] = MFMA(fa[k2][0], fb[k2][1], acc[0][1]);
;             acc[1][0] = MFMA(fa[k2][1], fb[k2][0], acc[1][0]); acc[1][1] = MFMA(fa[k2][1], fb[k2][1], acc[1][1]);
;         }
; #pragma unroll
;         for (int k2 = 0; k2 < 2; ++k2) { const int ks = 2 + k2; ga[k2][0] = ld8(Ab + 16 * ks); ga[k2][1] = ld8(Ab + 32 * LS + 16 * ks); gb[k2][0] = ld8(Bb + 16 * ks); gb[k2][1] = ld8(Bb + 32 * LS + 16 * ks); }
; #pragma unroll
;         for (int k2 = 0; k2 < 2; ++k2) {
;             acc[0][0] = MFMA(ga[k2][0], gb[k2][0], acc[0][0]); acc[0][1] = MFMA(ga[k2][0], gb[k2][1], acc[0][1]);
;             acc[1][0] = MFMA(ga[k2][1], gb[k2][0], acc[1][0]); acc[1][1] = MFMA(ga[k2][1], gb[k2][1], acc[1][1]);
;         }
;         if (kt + 1 < nk) sstore(stset, buf ^ 1, kt + 1);
; #pragma unroll
;         for (int i = 0; i < 8; ++i) { __builtin_amdgcn_sched_group_barrier(0x008, 1, 0); __builtin_amdgcn_sched_group_barrier(0x100, 1, 0); }
; #pragma unroll
;         for (int i = 0; i < 8; ++i) { __builtin_amdgcn_sched_group_barrier(0x008, 1, 0); __builtin_amdgcn_sched_group_barrier(0x200, 1, 0); }
;         __builtin_amdgcn_sched_barrier(0);
;         __syncthreads();
;     };
	s_setprio 1
	ds_read_b128 v[174:177], v196
	ds_read_b128 v[210:213], v197 offset:36864
	ds_read_b128 v[218:221], v197 offset:41472
	ds_read_b128 v[202:205], v196 offset:4608
	ds_read_b128 v[178:181], v196 offset:32
	ds_read_b128 v[222:225], v197 offset:41504
	ds_read_b128 v[206:209], v196 offset:4640
	ds_read_b128 v[214:217], v197 offset:36896
	s_waitcnt lgkmcnt(6)
	v_mfma_f32_32x32x16_bf16 v[52:67], v[174:177], v[210:213], v[52:67]
	global_load_dwordx4 v[68:71], v[164:165], off offset:1536
	s_waitcnt lgkmcnt(5)
	v_mfma_f32_32x32x16_bf16 v[36:51], v[174:177], v[218:221], v[36:51]
	global_load_dwordx4 v[72:75], v[162:163], off offset:1536
	s_waitcnt lgkmcnt(4)
	v_mfma_f32_32x32x16_bf16 v[4:19], v[202:205], v[218:221], v[4:19]
	global_load_dwordx4 v[76:79], v[160:161], off offset:1536
	s_waitcnt lgkmcnt(2)
	v_mfma_f32_32x32x16_bf16 v[36:51], v[178:181], v[222:225], v[36:51]
	global_load_dwordx4 v[80:83], v[158:159], off offset:1536
	s_waitcnt lgkmcnt(1)
	v_mfma_f32_32x32x16_bf16 v[4:19], v[206:209], v[222:225], v[4:19]
	global_load_dwordx4 v[84:87], v[156:157], off offset:1536
	ds_read_b128 v[222:225], v197 offset:41568
	ds_read_b128 v[174:177], v196 offset:4672
	v_mfma_f32_32x32x16_bf16 v[20:35], v[202:205], v[210:213], v[20:35]
	global_load_dwordx4 v[92:95], v[154:155], off offset:1536
	ds_read_b128 v[210:213], v196 offset:4704
	ds_read_b128 v[202:205], v196 offset:64
	s_waitcnt lgkmcnt(4)
	v_mfma_f32_32x32x16_bf16 v[52:67], v[178:181], v[214:217], v[52:67]
	global_load_dwordx4 v[104:107], v[152:153], off offset:1536
	ds_read_b128 v[218:221], v197 offset:36960
	ds_read_b128 v[178:181], v197 offset:41536
	v_mfma_f32_32x32x16_bf16 v[20:35], v[206:209], v[214:217], v[20:35]
	global_load_dwordx4 v[112:115], v[146:147], off offset:1536
	ds_read_b128 v[214:217], v197 offset:36928
	ds_read_b128 v[206:209], v196 offset:96
	s_waitcnt lgkmcnt(1)
	v_mfma_f32_32x32x16_bf16 v[52:67], v[202:205], v[214:217], v[52:67]
	s_waitcnt vmcnt(23)
	ds_write_b128 v167, v[88:91]
	v_mfma_f32_32x32x16_bf16 v[36:51], v[202:205], v[178:181], v[36:51]
	s_waitcnt vmcnt(22)
	ds_write_b128 v167, v[96:99] offset:36864
	v_mfma_f32_32x32x16_bf16 v[20:35], v[174:177], v[214:217], v[20:35]
	s_waitcnt vmcnt(21)
	ds_write_b128 v190, v[100:103]
	v_mfma_f32_32x32x16_bf16 v[4:19], v[174:177], v[178:181], v[4:19]
	s_setprio 0
	s_waitcnt vmcnt(20)
	ds_write_b128 v190, v[108:111] offset:36864
	s_waitcnt lgkmcnt(4)
	v_mfma_f32_32x32x16_bf16 v[52:67], v[206:209], v[218:221], v[52:67]
	s_waitcnt vmcnt(19)
	ds_write_b128 v191, v[116:119]
	v_mfma_f32_32x32x16_bf16 v[36:51], v[206:209], v[222:225], v[36:51]
	s_waitcnt vmcnt(18)
	ds_write_b128 v191, v[120:123] offset:36864
	v_mfma_f32_32x32x16_bf16 v[20:35], v[210:213], v[218:221], v[20:35]
	s_waitcnt vmcnt(17)
	ds_write_b128 v192, v[124:127]
	v_mfma_f32_32x32x16_bf16 v[4:19], v[210:213], v[222:225], v[4:19]
	s_waitcnt vmcnt(16)
	ds_write_b128 v192, v[128:131] offset:36864
	s_waitcnt lgkmcnt(0)
	s_barrier
	s_setprio 1
	ds_read_b128 v[174:177], v194
	ds_read_b128 v[210:213], v195 offset:36864
	ds_read_b128 v[218:221], v195 offset:41472
	ds_read_b128 v[202:205], v194 offset:4608
	ds_read_b128 v[178:181], v194 offset:32
	ds_read_b128 v[222:225], v195 offset:41504
	ds_read_b128 v[206:209], v194 offset:4640
	ds_read_b128 v[214:217], v195 offset:36896
	s_waitcnt lgkmcnt(6)
	v_mfma_f32_32x32x16_bf16 v[52:67], v[174:177], v[210:213], v[52:67]
	global_load_dwordx4 v[88:91], v[164:165], off offset:1664
	s_waitcnt lgkmcnt(5)
	v_mfma_f32_32x32x16_bf16 v[36:51], v[174:177], v[218:221], v[36:51]
	global_load_dwordx4 v[96:99], v[162:163], off offset:1664
	s_waitcnt lgkmcnt(4)
	v_mfma_f32_32x32x16_bf16 v[4:19], v[202:205], v[218:221], v[4:19]
	global_load_dwordx4 v[100:103], v[160:161], off offset:1664
	s_waitcnt lgkmcnt(2)
	v_mfma_f32_32x32x16_bf16 v[36:51], v[178:181], v[222:225], v[36:51]
	global_load_dwordx4 v[108:111], v[158:159], off offset:1664
	s_waitcnt lgkmcnt(1)
	v_mfma_f32_32x32x16_bf16 v[4:19], v[206:209], v[222:225], v[4:19]
	global_load_dwordx4 v[116:119], v[156:157], off offset:1664
	ds_read_b128 v[222:225], v195 offset:41568
	ds_read_b128 v[174:177], v194 offset:4672
	v_mfma_f32_32x32x16_bf16 v[20:35], v[202:205], v[210:213], v[20:35]
	global_load_dwordx4 v[120:123], v[154:155], off offset:1664
	ds_read_b128 v[210:213], v194 offset:4704
	ds_read_b128 v[202:205], v194 offset:64
	s_waitcnt lgkmcnt(4)
	v_mfma_f32_32x32x16_bf16 v[52:67], v[178:181], v[214:217], v[52:67]
	global_load_dwordx4 v[124:127], v[152:153], off offset:1664
	ds_read_b128 v[218:221], v195 offset:36960
	ds_read_b128 v[178:181], v195 offset:41536
	v_mfma_f32_32x32x16_bf16 v[20:35], v[206:209], v[214:217], v[20:35]
	global_load_dwordx4 v[128:131], v[146:147], off offset:1664
	ds_read_b128 v[214:217], v195 offset:36928
	ds_read_b128 v[206:209], v194 offset:96
	s_waitcnt lgkmcnt(1)
	v_mfma_f32_32x32x16_bf16 v[52:67], v[202:205], v[214:217], v[52:67]
	s_waitcnt vmcnt(23)
	ds_write_b128 v167, v[132:135] offset:18432
	v_mfma_f32_32x32x16_bf16 v[36:51], v[202:205], v[178:181], v[36:51]
	s_waitcnt vmcnt(22)
	ds_write_b128 v167, v[136:139] offset:55296
	v_mfma_f32_32x32x16_bf16 v[20:35], v[174:177], v[214:217], v[20:35]
	s_waitcnt vmcnt(21)
	ds_write_b128 v190, v[140:143] offset:18432
	v_mfma_f32_32x32x16_bf16 v[4:19], v[174:177], v[178:181], v[4:19]
	s_setprio 0
	s_waitcnt vmcnt(20)
	ds_write_b128 v190, v[198:201] offset:55296
	s_waitcnt lgkmcnt(4)
	v_mfma_f32_32x32x16_bf16 v[52:67], v[206:209], v[218:221], v[52:67]
	s_waitcnt vmcnt(19)
	ds_write_b128 v191, v[226:229] offset:18432
	v_mfma_f32_32x32x16_bf16 v[36:51], v[206:209], v[222:225], v[36:51]
	s_waitcnt vmcnt(18)
	ds_write_b128 v191, v[230:233] offset:55296
	v_mfma_f32_32x32x16_bf16 v[20:35], v[210:213], v[218:221], v[20:35]
	s_waitcnt vmcnt(17)
	ds_write_b128 v192, v[242:245] offset:18432
	v_mfma_f32_32x32x16_bf16 v[4:19], v[210:213], v[222:225], v[4:19]
	s_waitcnt vmcnt(16)
	ds_write_b128 v192, v[246:249] offset:55296
	s_waitcnt lgkmcnt(0)
	s_barrier
; #define MFMA(a, b, c) __builtin_amdgcn_mfma_f32_32x32x16_bf16((a), (b), (c), 0, 0, 0)
; template <class Epi, class ColV>
; DI void gemm_tile(const bf16_t* __restrict__ A, int lda, const bf16_t* __restrict__ Bt, int ldb, int K, int m0, int n0, unsigned char* smem, Epi epi, ColV colv, const bf16_t* __restrict__ HYT = nullptr) {
;     ...
;     auto step = [&](int kt, u32x4 (&ldset)[8], const u32x4 (&stset)[8]) {
;         const int buf = kt & 1;
;         if (kt + 2 < nk) gload(ldset, kt + 2);
;         const bf16_t* Ab = As + (buf * 128 + 64 * wr + li) * LS + 8 * lh;
;         const bf16_t* Bb = Bs + (buf * 128 + 64 * wc + li) * LS + 8 * lh;
;         bf16x8 fa[2][2], fb[2][2], ga[2][2], gb[2][2];
; #pragma unroll
;         for (int k2 = 0; k2 < 2; ++k2) { fa[k2][0] = ld8(Ab + 16 * k2); fa[k2][1] = ld8(Ab + 32 * LS + 16 * k2); fb[k2][0] = ld8(Bb + 16 * k2); fb[k2][1] = ld8(Bb + 32 * LS + 16 * k2); }
;         __builtin_amdgcn_sched_barrier(0);
; #pragma unroll
;         for (int k2 = 0; k2 < 2; ++k2) {
;             acc[0][0] = MFMA(fa[k2][0], fb[k2][0], acc[0][0]); acc[0][1] = MFMA(fa[k2][0], fb[k2][1], acc[0][1]);
;             acc[1][0] = MFMA(fa[k2][1], fb[k2][0], acc[1][0]); acc[1][1] = MFMA(fa[k2][1], fb[k2][1], acc[1][1]);
;         }
; #pragma unroll
;         for (int k2 = 0; k2 < 2; ++k2) { const int ks = 2 + k2; ga[k2][0] = ld8(Ab + 16 * ks); ga[k2][1] = ld8(Ab + 32 * LS + 16 * ks); gb[k2][0] = ld8(Bb + 16 * ks); gb[k2][1] = ld8(Bb + 32 * LS + 16 * ks); }
; #pragma unroll
;         for (int k2 = 0; k2 < 2; ++k2) {
;             acc[0][0] = MFMA(ga[k2][0], gb[k2][0], acc[0][0]); acc[0][1] = MFMA(ga[k2][0], gb[k2][1], acc[0][1]);
;             acc[1][0] = MFMA(ga[k2][1], gb[k2][0], acc[1][0]); acc[1][1] = MFMA(ga[k2][1], gb[k2][1], acc[1][1]);
;         }
;         if (kt + 1 < nk) sstore(stset, buf ^ 1, kt + 1);
; #pragma unroll
;         for (int i = 0; i < 8; ++i) { __builtin_amdgcn_sched_group_barrier(0x008, 1, 0); __builtin_amdgcn_sched_group_barrier(0x100, 1, 0); }
; #pragma unroll
;         for (int i = 0; i < 8; ++i) { __builtin_amdgcn_sched_group_barrier(0x008, 1, 0); __builtin_amdgcn_sched_group_barrier(0x200, 1, 0); }
;         __builtin_amdgcn_sched_barrier(0);
;         __syncthreads();
;     };
	s_setprio 1
	ds_read_b128 v[174:177], v196
	ds_read_b128 v[210:213], v197 offset:36864
	ds_read_b128 v[218:221], v197 offset:41472
	ds_read_b128 v[202:205], v196 offset:4608
	ds_read_b128 v[178:181], v196 offset:32
	ds_read_b128 v[222:225], v197 offset:41504
	ds_read_b128 v[206:209], v196 offset:4640
	ds_read_b128 v[214:217], v197 offset:36896
	s_waitcnt lgkmcnt(6)
	v_mfma_f32_32x32x16_bf16 v[52:67], v[174:177], v[210:213], v[52:67]
	global_load_dwordx4 v[132:135], v[164:165], off offset:1792
	s_waitcnt lgkmcnt(5)
	v_mfma_f32_32x32x16_bf16 v[36:51], v[174:177], v[218:221], v[36:51]
	global_load_dwordx4 v[136:139], v[162:163], off offset:1792
	s_waitcnt lgkmcnt(4)
	v_mfma_f32_32x32x16_bf16 v[4:19], v[202:205], v[218:221], v[4:19]
	global_load_dwordx4 v[140:143], v[160:161], off offset:1792
	s_waitcnt lgkmcnt(2)
	v_mfma_f32_32x32x16_bf16 v[36:51], v[178:181], v[222:225], v[36:51]
	global_load_dwordx4 v[198:201], v[158:159], off offset:1792
	s_waitcnt lgkmcnt(1)
	v_mfma_f32_32x32x16_bf16 v[4:19], v[206:209], v[222:225], v[4:19]
	global_load_dwordx4 v[226:229], v[156:157], off offset:1792
	ds_read_b128 v[222:225], v197 offset:41568
	ds_read_b128 v[174:177], v196 offset:4672
	v_mfma_f32_32x32x16_bf16 v[20:35], v[202:205], v[210:213], v[20:35]
	global_load_dwordx4 v[230:233], v[154:155], off offset:1792
	ds_read_b128 v[210:213], v196 offset:4704
	ds_read_b128 v[202:205], v196 offset:64
	s_waitcnt lgkmcnt(4)
	v_mfma_f32_32x32x16_bf16 v[52:67], v[178:181], v[214:217], v[52:67]
	global_load_dwordx4 v[242:245], v[152:153], off offset:1792
	ds_read_b128 v[218:221], v197 offset:36960
	ds_read_b128 v[178:181], v197 offset:41536
	v_mfma_f32_32x32x16_bf16 v[20:35], v[206:209], v[214:217], v[20:35]
	global_load_dwordx4 v[246:249], v[146:147], off offset:1792
	ds_read_b128 v[214:217], v197 offset:36928
	ds_read_b128 v[206:209], v196 offset:96
	s_waitcnt lgkmcnt(1)
	v_mfma_f32_32x32x16_bf16 v[52:67], v[202:205], v[214:217], v[52:67]
	s_waitcnt vmcnt(23)
	ds_write_b128 v167, v[68:71]
	v_mfma_f32_32x32x16_bf16 v[36:51], v[202:205], v[178:181], v[36:51]
	s_waitcnt vmcnt(22)
	ds_write_b128 v167, v[72:75] offset:36864
	v_mfma_f32_32x32x16_bf16 v[20:35], v[174:177], v[214:217], v[20:35]
	s_waitcnt vmcnt(21)
	ds_write_b128 v190, v[76:79]
	v_mfma_f32_32x32x16_bf16 v[4:19], v[174:177], v[178:181], v[4:19]
	s_setprio 0
	s_waitcnt vmcnt(20)
	ds_write_b128 v190, v[80:83] offset:36864
	s_waitcnt lgkmcnt(4)
	v_mfma_f32_32x32x16_bf16 v[52:67], v[206:209], v[218:221], v[52:67]
	s_waitcnt vmcnt(19)
	ds_write_b128 v191, v[84:87]
	v_mfma_f32_32x32x16_bf16 v[36:51], v[206:209], v[222:225], v[36:51]
	s_waitcnt vmcnt(18)
	ds_write_b128 v191, v[92:95] offset:36864
	v_mfma_f32_32x32x16_bf16 v[20:35], v[210:213], v[218:221], v[20:35]
	s_waitcnt vmcnt(17)
	ds_write_b128 v192, v[104:107]
	v_mfma_f32_32x32x16_bf16 v[4:19], v[210:213], v[222:225], v[4:19]
	s_waitcnt vmcnt(16)
	ds_write_b128 v192, v[112:115] offset:36864
	s_waitcnt lgkmcnt(0)
	s_barrier
	s_setprio 1
	ds_read_b128 v[174:177], v194
	ds_read_b128 v[210:213], v195 offset:36864
	ds_read_b128 v[218:221], v195 offset:41472
	ds_read_b128 v[202:205], v194 offset:4608
	ds_read_b128 v[178:181], v194 offset:32
	ds_read_b128 v[222:225], v195 offset:41504
	ds_read_b128 v[206:209], v194 offset:4640
	ds_read_b128 v[214:217], v195 offset:36896
	s_waitcnt lgkmcnt(6)
	v_mfma_f32_32x32x16_bf16 v[52:67], v[174:177], v[210:213], v[52:67]
	global_load_dwordx4 v[68:71], v[164:165], off offset:1920
	s_waitcnt lgkmcnt(5)
	v_mfma_f32_32x32x16_bf16 v[36:51], v[174:177], v[218:221], v[36:51]
	global_load_dwordx4 v[72:75], v[162:163], off offset:1920
	s_waitcnt lgkmcnt(4)
	v_mfma_f32_32x32x16_bf16 v[4:19], v[202:205], v[218:221], v[4:19]
	global_load_dwordx4 v[76:79], v[160:161], off offset:1920
	s_waitcnt lgkmcnt(2)
	v_mfma_f32_32x32x16_bf16 v[36:51], v[178:181], v[222:225], v[36:51]
	global_load_dwordx4 v[80:83], v[158:159], off offset:1920
	s_waitcnt lgkmcnt(1)
	v_mfma_f32_32x32x16_bf16 v[4:19], v[206:209], v[222:225], v[4:19]
	global_load_dwordx4 v[84:87], v[156:157], off offset:1920
	ds_read_b128 v[222:225], v195 offset:41568
	ds_read_b128 v[174:177], v194 offset:4672
	v_mfma_f32_32x32x16_bf16 v[20:35], v[202:205], v[210:213], v[20:35]
	global_load_dwordx4 v[92:95], v[154:155], off offset:1920
	ds_read_b128 v[210:213], v194 offset:4704
	ds_read_b128 v[202:205], v194 offset:64
	s_waitcnt lgkmcnt(4)
	v_mfma_f32_32x32x16_bf16 v[52:67], v[178:181], v[214:217], v[52:67]
	global_load_dwordx4 v[104:107], v[152:153], off offset:1920
	ds_read_b128 v[218:221], v195 offset:36960
	ds_read_b128 v[178:181], v195 offset:41536
	v_mfma_f32_32x32x16_bf16 v[20:35], v[206:209], v[214:217], v[20:35]
	global_load_dwordx4 v[112:115], v[146:147], off offset:1920
	ds_read_b128 v[214:217], v195 offset:36928
	ds_read_b128 v[206:209], v194 offset:96
	s_waitcnt lgkmcnt(1)
	v_mfma_f32_32x32x16_bf16 v[52:67], v[202:205], v[214:217], v[52:67]
	s_waitcnt vmcnt(23)
	ds_write_b128 v167, v[88:91] offset:18432
	v_mfma_f32_32x32x16_bf16 v[36:51], v[202:205], v[178:181], v[36:51]
	s_waitcnt vmcnt(22)
	ds_write_b128 v167, v[96:99] offset:55296
	v_mfma_f32_32x32x16_bf16 v[20:35], v[174:177], v[214:217], v[20:35]
	s_waitcnt vmcnt(21)
	ds_write_b128 v190, v[100:103] offset:18432
	v_mfma_f32_32x32x16_bf16 v[4:19], v[174:177], v[178:181], v[4:19]
	s_setprio 0
	s_waitcnt vmcnt(20)
	ds_write_b128 v190, v[108:111] offset:55296
	s_waitcnt lgkmcnt(4)
	v_mfma_f32_32x32x16_bf16 v[52:67], v[206:209], v[218:221], v[52:67]
	s_waitcnt vmcnt(19)
	ds_write_b128 v191, v[116:119] offset:18432
	v_mfma_f32_32x32x16_bf16 v[36:51], v[206:209], v[222:225], v[36:51]
	s_waitcnt vmcnt(18)
	ds_write_b128 v191, v[120:123] offset:55296
	v_mfma_f32_32x32x16_bf16 v[20:35], v[210:213], v[218:221], v[20:35]
	s_waitcnt vmcnt(17)
	ds_write_b128 v192, v[124:127] offset:18432
	v_mfma_f32_32x32x16_bf16 v[4:19], v[210:213], v[222:225], v[4:19]
	s_waitcnt vmcnt(16)
	ds_write_b128 v192, v[128:131] offset:55296
	s_waitcnt lgkmcnt(0)
	s_barrier
; #define MFMA(a, b, c) __builtin_amdgcn_mfma_f32_32x32x16_bf16((a), (b), (c), 0, 0, 0)
; template <class Epi, class ColV>
; DI void gemm_tile(const bf16_t* __restrict__ A, int lda, const bf16_t* __restrict__ Bt, int ldb, int K, int m0, int n0, unsigned char* smem, Epi epi, ColV colv, const bf16_t* __restrict__ HYT = nullptr) {
;     ...
;     auto step = [&](int kt, u32x4 (&ldset)[8], const u32x4 (&stset)[8]) {
;         const int buf = kt & 1;
;         if (kt + 2 < nk) gload(ldset, kt + 2);
;         const bf16_t* Ab = As + (buf * 128 + 64 * wr + li) * LS + 8 * lh;
;         const bf16_t* Bb = Bs + (buf * 128 + 64 * wc + li) * LS + 8 * lh;
;         bf16x8 fa[2][2], fb[2][2], ga[2][2], gb[2][2];
; #pragma unroll
;         for (int k2 = 0; k2 < 2; ++k2) { fa[k2][0] = ld8(Ab + 16 * k2); fa[k2][1] = ld8(Ab + 32 * LS + 16 * k2); fb[k2][0] = ld8(Bb + 16 * k2); fb[k2][1] = ld8(Bb + 32 * LS + 16 * k2); }
;         __builtin_amdgcn_sched_barrier(0);
; #pragma unroll
;         for (int k2 = 0; k2 < 2; ++k2) {
;             acc[0][0] = MFMA(fa[k2][0], fb[k2][0], acc[0][0]); acc[0][1] = MFMA(fa[k2][0], fb[k2][1], acc[0][1]);
;             acc[1][0] = MFMA(fa[k2][1], fb[k2][0], acc[1][0]); acc[1][1] = MFMA(fa[k2][1], fb[k2][1], acc[1][1]);
;         }
; #pragma unroll
;         for (int k2 = 0; k2 < 2; ++k2) { const int ks = 2 + k2; ga[k2][0] = ld8(Ab + 16 * ks); ga[k2][1] = ld8(Ab + 32 * LS + 16 * ks); gb[k2][0] = ld8(Bb + 16 * ks); gb[k2][1] = ld8(Bb + 32 * LS + 16 * ks); }
; #pragma unroll
;         for (int k2 = 0; k2 < 2; ++k2) {
;             acc[0][0] = MFMA(ga[k2][0], gb[k2][0], acc[0][0]); acc[0][1] = MFMA(ga[k2][0], gb[k2][1], acc[0][1]);
;             acc[1][0] = MFMA(ga[k2][1], gb[k2][0], acc[1][0]); acc[1][1] = MFMA(ga[k2][1], gb[k2][1], acc[1][1]);
;         }
;         if (kt + 1 < nk) sstore(stset, buf ^ 1, kt + 1);
; #pragma unroll
;         for (int i = 0; i < 8; ++i) { __builtin_amdgcn_sched_group_barrier(0x008, 1, 0); __builtin_amdgcn_sched_group_barrier(0x100, 1, 0); }
; #pragma unroll
;         for (int i = 0; i < 8; ++i) { __builtin_amdgcn_sched_group_barrier(0x008, 1, 0); __builtin_amdgcn_sched_group_barrier(0x200, 1, 0); }
;         __builtin_amdgcn_sched_barrier(0);
;         __syncthreads();
;     };
	s_setprio 1
	ds_read_b128 v[174:177], v196
	ds_read_b128 v[210:213], v197 offset:36864
	ds_read_b128 v[218:221], v197 offset:41472
	ds_read_b128 v[202:205], v196 offset:4608
	ds_read_b128 v[178:181], v196 offset:32
	ds_read_b128 v[222:225], v197 offset:41504
	ds_read_b128 v[206:209], v196 offset:4640
	ds_read_b128 v[214:217], v197 offset:36896
	s_waitcnt lgkmcnt(6)
	v_mfma_f32_32x32x16_bf16 v[52:67], v[174:177], v[210:213], v[52:67]
	s_waitcnt lgkmcnt(5)
	v_mfma_f32_32x32x16_bf16 v[36:51], v[174:177], v[218:221], v[36:51]
	s_waitcnt lgkmcnt(4)
	v_mfma_f32_32x32x16_bf16 v[4:19], v[202:205], v[218:221], v[4:19]
	s_waitcnt lgkmcnt(2)
	v_mfma_f32_32x32x16_bf16 v[36:51], v[178:181], v[222:225], v[36:51]
	s_waitcnt lgkmcnt(1)
	v_mfma_f32_32x32x16_bf16 v[4:19], v[206:209], v[222:225], v[4:19]
	ds_read_b128 v[222:225], v197 offset:41568
	ds_read_b128 v[174:177], v196 offset:4672
	v_mfma_f32_32x32x16_bf16 v[20:35], v[202:205], v[210:213], v[20:35]
	ds_read_b128 v[210:213], v196 offset:4704
	ds_read_b128 v[202:205], v196 offset:64
	s_waitcnt lgkmcnt(4)
	v_mfma_f32_32x32x16_bf16 v[52:67], v[178:181], v[214:217], v[52:67]
	ds_read_b128 v[218:221], v197 offset:36960
	ds_read_b128 v[178:181], v197 offset:41536
	v_mfma_f32_32x32x16_bf16 v[20:35], v[206:209], v[214:217], v[20:35]
	ds_read_b128 v[214:217], v197 offset:36928
	ds_read_b128 v[206:209], v196 offset:96
	s_waitcnt lgkmcnt(1)
	v_mfma_f32_32x32x16_bf16 v[52:67], v[202:205], v[214:217], v[52:67]
	s_waitcnt vmcnt(15)
	ds_write_b128 v167, v[132:135]
	v_mfma_f32_32x32x16_bf16 v[36:51], v[202:205], v[178:181], v[36:51]
	s_waitcnt vmcnt(14)
	ds_write_b128 v167, v[136:139] offset:36864
	v_mfma_f32_32x32x16_bf16 v[20:35], v[174:177], v[214:217], v[20:35]
	s_waitcnt vmcnt(13)
	ds_write_b128 v190, v[140:143]
	v_mfma_f32_32x32x16_bf16 v[4:19], v[174:177], v[178:181], v[4:19]
	s_setprio 0
	s_waitcnt vmcnt(12)
	ds_write_b128 v190, v[198:201] offset:36864
	s_waitcnt lgkmcnt(4)
	v_mfma_f32_32x32x16_bf16 v[52:67], v[206:209], v[218:221], v[52:67]
	s_waitcnt vmcnt(11)
	ds_write_b128 v191, v[226:229]
	v_mfma_f32_32x32x16_bf16 v[36:51], v[206:209], v[222:225], v[36:51]
	s_waitcnt vmcnt(10)
	ds_write_b128 v191, v[230:233] offset:36864
	v_mfma_f32_32x32x16_bf16 v[20:35], v[210:213], v[218:221], v[20:35]
	s_waitcnt vmcnt(9)
	ds_write_b128 v192, v[242:245]
	v_mfma_f32_32x32x16_bf16 v[4:19], v[210:213], v[222:225], v[4:19]
	s_waitcnt vmcnt(8)
	ds_write_b128 v192, v[246:249] offset:36864
	s_waitcnt lgkmcnt(0)
	s_barrier
; template <class Epi, class ColV>
; DI void gemm_tile(const bf16_t* __restrict__ A, int lda, const bf16_t* __restrict__ Bt, int ldb, int K, int m0, int n0, unsigned char* smem, Epi epi, ColV colv, const bf16_t* __restrict__ HYT = nullptr) {
;     ...
;     auto step = [&](int kt, u32x4 (&ldset)[8], const u32x4 (&stset)[8]) {
;         const int buf = kt & 1;
;         if (kt + 2 < nk) gload(ldset, kt + 2);
;         const bf16_t* Ab = As + (buf * 128 + 64 * wr + li) * LS + 8 * lh;
;         const bf16_t* Bb = Bs + (buf * 128 + 64 * wc + li) * LS + 8 * lh;
;         bf16x8 fa[2][2], fb[2][2], ga[2][2], gb[2][2];
; #pragma unroll
;         for (int k2 = 0; k2 < 2; ++k2) { fa[k2][0] = ld8(Ab + 16 * k2); fa[k2][1] = ld8(Ab + 32 * LS + 16 * k2); fb[k2][0] = ld8(Bb + 16 * k2); fb[k2][1] = ld8(Bb + 32 * LS + 16 * k2); }
;         __builtin_amdgcn_sched_barrier(0);
; #pragma unroll
;         for (int k2 = 0; k2 < 2; ++k2) {
;             acc[0][0] = MFMA(fa[k2][0], fb[k2][0], acc[0][0]); acc[0][1] = MFMA(fa[k2][0], fb[k2][1], acc[0][1]);
;             acc[1][0] = MFMA(fa[k2][1], fb[k2][0], acc[1][0]); acc[1][1] = MFMA(fa[k2][1], fb[k2][1], acc[1][1]);
;         }
; #pragma unroll
;         for (int k2 = 0; k2 < 2; ++k2) { const int ks = 2 + k2; ga[k2][0] = ld8(Ab + 16 * ks); ga[k2][1] = ld8(Ab + 32 * LS + 16 * ks); gb[k2][0] = ld8(Bb + 16 * ks); gb[k2][1] = ld8(Bb + 32 * LS + 16 * ks); }
; #pragma unroll
;         for (int k2 = 0; k2 < 2; ++k2) {
;             acc[0][0] = MFMA(ga[k2][0], gb[k2][0], acc[0][0]); acc[0][1] = MFMA(ga[k2][0], gb[k2][1], acc[0][1]);
;             acc[1][0] = MFMA(ga[k2][1], gb[k2][0], acc[1][0]); acc[1][1] = MFMA(ga[k2][1], gb[k2][1], acc[1][1]);
;         }
;         if (kt + 1 < nk) sstore(stset, buf ^ 1, kt + 1);
; #pragma unroll
;         for (int i = 0; i < 8; ++i) { __builtin_amdgcn_sched_group_barrier(0x008, 1, 0); __builtin_amdgcn_sched_group_barrier(0x100, 1, 0); }
; #pragma unroll
;         for (int i = 0; i < 8; ++i) { __builtin_amdgcn_sched_group_barrier(0x008, 1, 0); __builtin_amdgcn_sched_group_barrier(0x200, 1, 0); }
;         __builtin_amdgcn_sched_barrier(0);
;         __syncthreads();
;     };
;     gload(R0, 0); gload(R1, 1);
;     sstore(R0, 0, 0); __syncthreads();
;     for (int kt = 0; kt < nk; kt += 2) {
;         step(kt, R0, R1);
;         if (kt + 1 < nk) step(kt + 1, R1, R0);
;     }
	s_setprio 1
	ds_read_b128 v[174:177], v194
	ds_read_b128 v[210:213], v195 offset:36864
	ds_read_b128 v[218:221], v195 offset:41472
	ds_read_b128 v[202:205], v194 offset:4608
	ds_read_b128 v[178:181], v194 offset:32
	ds_read_b128 v[222:225], v195 offset:41504
	ds_read_b128 v[206:209], v194 offset:4640
	ds_read_b128 v[214:217], v195 offset:36896
	s_waitcnt lgkmcnt(6)
	v_mfma_f32_32x32x16_bf16 v[52:67], v[174:177], v[210:213], v[52:67]
	s_waitcnt lgkmcnt(5)
	v_mfma_f32_32x32x16_bf16 v[36:51], v[174:177], v[218:221], v[36:51]
	s_waitcnt lgkmcnt(4)
	v_mfma_f32_32x32x16_bf16 v[4:19], v[202:205], v[218:221], v[4:19]
	s_waitcnt lgkmcnt(2)
	v_mfma_f32_32x32x16_bf16 v[36:51], v[178:181], v[222:225], v[36:51]
	s_waitcnt lgkmcnt(1)
	v_mfma_f32_32x32x16_bf16 v[4:19], v[206:209], v[222:225], v[4:19]
	ds_read_b128 v[222:225], v195 offset:41568
	ds_read_b128 v[174:177], v194 offset:4672
	v_mfma_f32_32x32x16_bf16 v[20:35], v[202:205], v[210:213], v[20:35]
	ds_read_b128 v[210:213], v194 offset:4704
	ds_read_b128 v[202:205], v194 offset:64
	s_waitcnt lgkmcnt(4)
	v_mfma_f32_32x32x16_bf16 v[52:67], v[178:181], v[214:217], v[52:67]
	ds_read_b128 v[218:221], v195 offset:36960
	ds_read_b128 v[178:181], v195 offset:41536
	v_mfma_f32_32x32x16_bf16 v[20:35], v[206:209], v[214:217], v[20:35]
	ds_read_b128 v[214:217], v195 offset:36928
	ds_read_b128 v[206:209], v194 offset:96
	s_waitcnt lgkmcnt(1)
	v_mfma_f32_32x32x16_bf16 v[52:67], v[202:205], v[214:217], v[52:67]
	s_waitcnt vmcnt(7)
	ds_write_b128 v167, v[68:71] offset:18432
	v_mfma_f32_32x32x16_bf16 v[36:51], v[202:205], v[178:181], v[36:51]
	s_waitcnt vmcnt(6)
	ds_write_b128 v167, v[72:75] offset:55296
	v_mfma_f32_32x32x16_bf16 v[20:35], v[174:177], v[214:217], v[20:35]
	s_waitcnt vmcnt(5)
	ds_write_b128 v190, v[76:79] offset:18432
	v_mfma_f32_32x32x16_bf16 v[4:19], v[174:177], v[178:181], v[4:19]
	s_setprio 0
	s_waitcnt vmcnt(4)
	ds_write_b128 v190, v[80:83] offset:55296
	s_waitcnt lgkmcnt(4)
	v_mfma_f32_32x32x16_bf16 v[52:67], v[206:209], v[218:221], v[52:67]
	s_waitcnt vmcnt(3)
	ds_write_b128 v191, v[84:87] offset:18432
	v_mfma_f32_32x32x16_bf16 v[36:51], v[206:209], v[222:225], v[36:51]
	s_waitcnt vmcnt(2)
	ds_write_b128 v191, v[92:95] offset:55296
	v_mfma_f32_32x32x16_bf16 v[20:35], v[210:213], v[218:221], v[20:35]
	s_waitcnt vmcnt(1)
	ds_write_b128 v192, v[104:107] offset:18432
	v_mfma_f32_32x32x16_bf16 v[4:19], v[210:213], v[222:225], v[4:19]
	s_waitcnt vmcnt(0)
	ds_write_b128 v192, v[112:115] offset:55296
	s_waitcnt lgkmcnt(0)
	s_barrier
	s_setprio 1
	ds_read_b128 v[174:177], v196
	ds_read_b128 v[210:213], v197 offset:36864
	ds_read_b128 v[218:221], v197 offset:41472
	ds_read_b128 v[202:205], v196 offset:4608
	ds_read_b128 v[178:181], v196 offset:32
	ds_read_b128 v[222:225], v197 offset:41504
	ds_read_b128 v[206:209], v196 offset:4640
	ds_read_b128 v[214:217], v197 offset:36896
	s_waitcnt lgkmcnt(6)
	v_mfma_f32_32x32x16_bf16 v[52:67], v[174:177], v[210:213], v[52:67]
	s_waitcnt lgkmcnt(5)
	v_mfma_f32_32x32x16_bf16 v[36:51], v[174:177], v[218:221], v[36:51]
	s_waitcnt lgkmcnt(4)
	v_mfma_f32_32x32x16_bf16 v[4:19], v[202:205], v[218:221], v[4:19]
	s_waitcnt lgkmcnt(2)
	v_mfma_f32_32x32x16_bf16 v[36:51], v[178:181], v[222:225], v[36:51]
	s_waitcnt lgkmcnt(1)
	v_mfma_f32_32x32x16_bf16 v[4:19], v[206:209], v[222:225], v[4:19]
	ds_read_b128 v[222:225], v197 offset:41568
	ds_read_b128 v[174:177], v196 offset:4672
	v_mfma_f32_32x32x16_bf16 v[20:35], v[202:205], v[210:213], v[20:35]
	ds_read_b128 v[210:213], v196 offset:4704
	ds_read_b128 v[202:205], v196 offset:64
	s_waitcnt lgkmcnt(4)
	v_mfma_f32_32x32x16_bf16 v[52:67], v[178:181], v[214:217], v[52:67]
	ds_read_b128 v[218:221], v197 offset:36960
	ds_read_b128 v[178:181], v197 offset:41536
	v_mfma_f32_32x32x16_bf16 v[20:35], v[206:209], v[214:217], v[20:35]
	ds_read_b128 v[214:217], v197 offset:36928
	ds_read_b128 v[206:209], v196 offset:96
	s_waitcnt lgkmcnt(1)
	v_mfma_f32_32x32x16_bf16 v[52:67], v[202:205], v[214:217], v[52:67]
	v_mfma_f32_32x32x16_bf16 v[36:51], v[202:205], v[178:181], v[36:51]
	v_mfma_f32_32x32x16_bf16 v[20:35], v[174:177], v[214:217], v[20:35]
	v_mfma_f32_32x32x16_bf16 v[4:19], v[174:177], v[178:181], v[4:19]
	s_setprio 0
	s_waitcnt lgkmcnt(0)
	v_mfma_f32_32x32x16_bf16 v[52:67], v[206:209], v[218:221], v[52:67]
	v_mfma_f32_32x32x16_bf16 v[36:51], v[206:209], v[222:225], v[36:51]
	v_mfma_f32_32x32x16_bf16 v[20:35], v[210:213], v[218:221], v[20:35]
	v_mfma_f32_32x32x16_bf16 v[4:19], v[210:213], v[222:225], v[4:19]
	s_waitcnt lgkmcnt(0)
	s_barrier
	s_setprio 1
	s_nop 7
	s_nop 3
	s_branch .LBB0_53

; #define MFMA(a, b, c) __builtin_amdgcn_mfma_f32_32x32x16_bf16((a), (b), (c), 0, 0, 0)
; template <class Epi, class ColV>
; DI void gemm_tile(const bf16_t* __restrict__ A, int lda, const bf16_t* __restrict__ Bt, int ldb, int K, int m0, int n0, unsigned char* smem, Epi epi, ColV colv, const bf16_t* __restrict__ HYT = nullptr) {
;     ...
;     auto gload = [&](u32x4 (&r)[8], int kt) {
; #pragma unroll
;         for (int i = 0; i < 4; ++i) { int id = tid + 256 * i, row = id >> 3, kc = id & 7;
;             if (HYT && kt >= 12) r[i] = *(const u32x4*)(HYT + (size_t)((kt - 12) * 64 + (id >> 4)) * NT + m0 + (id & 15) * 8);
;             else r[i] = *(const u32x4*)(A + (size_t)(m0 + row) * lda + kt * 64 + kc * 8);
;             r[4 + i] = *(const u32x4*)(Bt + (size_t)(n0 + row) * ldb + kt * 64 + kc * 8); }
;     };
;     auto sstore = [&](const u32x4 (&r)[8], int buf, int kt) {
; #pragma unroll
;         for (int i = 0; i < 4; ++i) { int id = tid + 256 * i, row = id >> 3, kc = id & 7;
;             if (HYT && kt >= 12) { const int kk = id >> 4, rr = (id & 15) * 8; bf16_t* d = As + (buf * 128 + rr) * LS + kk; const bf16x8 v = __builtin_bit_cast(bf16x8, r[i]);
; #pragma unroll
;                 for (int e = 0; e < 8; ++e) d[e * LS] = (bf16_t)v[e]; }
;             else *(u32x4*)(As + (buf * 128 + row) * LS + kc * 8) = r[i];
;             *(u32x4*)(Bs + (buf * 128 + row) * LS + kc * 8) = r[4 + i]; }
;     };
;     auto step = [&](int kt, u32x4 (&ldset)[8], const u32x4 (&stset)[8]) {
;         const int buf = kt & 1;
;         if (kt + 2 < nk) gload(ldset, kt + 2);
;         const bf16_t* Ab = As + (buf * 128 + 64 * wr + li) * LS + 8 * lh;
;         const bf16_t* Bb = Bs + (buf * 128 + 64 * wc + li) * LS + 8 * lh;
;         bf16x8 fa[2][2], fb[2][2], ga[2][2], gb[2][2];
; #pragma unroll
;         for (int k2 = 0; k2 < 2; ++k2) { fa[k2][0] = ld8(Ab + 16 * k2); fa[k2][1] = ld8(Ab + 32 * LS + 16 * k2); fb[k2][0] = ld8(Bb + 16 * k2); fb[k2][1] = ld8(Bb + 32 * LS + 16 * k2); }
;         __builtin_amdgcn_sched_barrier(0);
; #pragma unroll
;         for (int k2 = 0; k2 < 2; ++k2) {
;             acc[0][0] = MFMA(fa[k2][0], fb[k2][0], acc[0][0]); acc[0][1] = MFMA(fa[k2][0], fb[k2][1], acc[0][1]);
;             acc[1][0] = MFMA(fa[k2][1], fb[k2][0], acc[1][0]); acc[1][1] = MFMA(fa[k2][1], fb[k2][1], acc[1][1]);
;         }
; #pragma unroll
.LBB0_1558:
	s_cmp_lt_u32 s19, 14
	s_cselect_b64 s[12:13], -1, 0
	s_cmp_gt_u32 s19, 13
	s_cselect_b64 s[10:11], -1, 0
	s_and_b64 vcc, exec, s[10:11]
	v_lshl_add_u64 v[164:165], v[144:145], 0, v[2:3]
	v_lshl_add_u64 v[162:163], v[0:1], 0, v[2:3]
	v_lshl_add_u64 v[160:161], v[142:143], 0, v[2:3]
	v_lshl_add_u64 v[158:159], v[132:133], 0, v[2:3]
	v_lshl_add_u64 v[156:157], v[140:141], 0, v[2:3]
	v_lshl_add_u64 v[154:155], v[134:135], 0, v[2:3]
	v_lshl_add_u64 v[152:153], v[138:139], 0, v[2:3]
	v_lshl_add_u64 v[146:147], v[136:137], 0, v[2:3]
	s_mov_b32 s100, 0x26ca000
	s_mov_b32 s101, 0
	v_lshl_add_u64 v[164:165], v[164:165], 0, s[100:101]
	v_lshl_add_u64 v[160:161], v[160:161], 0, s[100:101]
	v_lshl_add_u64 v[156:157], v[156:157], 0, s[100:101]
	v_lshl_add_u64 v[152:153], v[152:153], 0, s[100:101]
	ds_read_b128 v[202:205], v194
	ds_read_b128 v[218:221], v195 offset:36864
	ds_read_b128 v[226:229], v195 offset:41472
	ds_read_b128 v[210:213], v194 offset:4608
	ds_read_b128 v[206:209], v194 offset:32
	ds_read_b128 v[230:233], v195 offset:41504
	ds_read_b128 v[214:217], v194 offset:4640
	ds_read_b128 v[222:225], v195 offset:36896
	s_waitcnt lgkmcnt(6)
	v_mfma_f32_32x32x16_bf16 v[52:67], v[202:205], v[218:221], v[52:67]
	global_load_dwordx4 v[132:135], v[164:165], off offset:256
	global_load_dwordx4 v[136:139], v[162:163], off offset:256
	s_waitcnt lgkmcnt(5)
	v_mfma_f32_32x32x16_bf16 v[36:51], v[202:205], v[226:229], v[36:51]
	global_load_dwordx4 v[140:143], v[160:161], off offset:256
	global_load_dwordx4 v[198:201], v[158:159], off offset:256
	s_waitcnt lgkmcnt(4)
	v_mfma_f32_32x32x16_bf16 v[4:19], v[210:213], v[226:229], v[4:19]
	global_load_dwordx4 v[174:177], v[156:157], off offset:256
	global_load_dwordx4 v[178:181], v[154:155], off offset:256
	s_waitcnt lgkmcnt(2)
	v_mfma_f32_32x32x16_bf16 v[36:51], v[206:209], v[230:233], v[36:51]
	global_load_dwordx4 v[242:245], v[152:153], off offset:256
	global_load_dwordx4 v[246:249], v[146:147], off offset:256
	s_waitcnt lgkmcnt(1)
	v_mfma_f32_32x32x16_bf16 v[4:19], v[214:217], v[230:233], v[4:19]
	global_load_dwordx4 v[68:71], v[164:165], off offset:384
	global_load_dwordx4 v[72:75], v[162:163], off offset:384
	ds_read_b128 v[230:233], v195 offset:41568
	ds_read_b128 v[202:205], v194 offset:4672
	v_mfma_f32_32x32x16_bf16 v[20:35], v[210:213], v[218:221], v[20:35]
	global_load_dwordx4 v[76:79], v[160:161], off offset:384
	global_load_dwordx4 v[80:83], v[158:159], off offset:384
	ds_read_b128 v[218:221], v194 offset:4704
	ds_read_b128 v[210:213], v194 offset:64
	s_waitcnt lgkmcnt(4)
	v_mfma_f32_32x32x16_bf16 v[52:67], v[206:209], v[222:225], v[52:67]
	global_load_dwordx4 v[84:87], v[156:157], off offset:384
	global_load_dwordx4 v[88:91], v[154:155], off offset:384
	ds_read_b128 v[226:229], v195 offset:36960
	ds_read_b128 v[206:209], v195 offset:41536
	v_mfma_f32_32x32x16_bf16 v[20:35], v[214:217], v[222:225], v[20:35]
	global_load_dwordx4 v[92:95], v[152:153], off offset:384
	global_load_dwordx4 v[104:107], v[146:147], off offset:384
	ds_read_b128 v[222:225], v195 offset:36928
	ds_read_b128 v[214:217], v194 offset:96
	s_waitcnt lgkmcnt(1)
	v_mfma_f32_32x32x16_bf16 v[52:67], v[210:213], v[222:225], v[52:67]
	s_waitcnt vmcnt(16)
	ds_write_b128 v167, v[96:99] offset:18432
	v_mfma_f32_32x32x16_bf16 v[36:51], v[210:213], v[206:209], v[36:51]
	ds_write_b128 v167, v[100:103] offset:55296
	v_mfma_f32_32x32x16_bf16 v[20:35], v[202:205], v[222:225], v[20:35]
	ds_write_b128 v190, v[108:111] offset:18432
	v_mfma_f32_32x32x16_bf16 v[4:19], v[202:205], v[206:209], v[4:19]
	s_setprio 0
	ds_write_b128 v190, v[112:115] offset:55296
	s_waitcnt lgkmcnt(4)
	v_mfma_f32_32x32x16_bf16 v[52:67], v[214:217], v[226:229], v[52:67]
	ds_write_b128 v191, v[116:119] offset:18432
	v_mfma_f32_32x32x16_bf16 v[36:51], v[214:217], v[230:233], v[36:51]
	ds_write_b128 v191, v[120:123] offset:55296
	v_mfma_f32_32x32x16_bf16 v[20:35], v[218:221], v[226:229], v[20:35]
	ds_write_b128 v192, v[124:127] offset:18432
	v_mfma_f32_32x32x16_bf16 v[4:19], v[218:221], v[230:233], v[4:19]
	ds_write_b128 v192, v[128:131] offset:55296
	s_waitcnt lgkmcnt(0)
	s_barrier
	s_setprio 1
	ds_read_b128 v[202:205], v196
	ds_read_b128 v[218:221], v197 offset:36864
	ds_read_b128 v[226:229], v197 offset:41472
	ds_read_b128 v[210:213], v196 offset:4608
	ds_read_b128 v[206:209], v196 offset:32
	ds_read_b128 v[230:233], v197 offset:41504
	ds_read_b128 v[214:217], v196 offset:4640
	ds_read_b128 v[222:225], v197 offset:36896
	s_waitcnt lgkmcnt(6)
	v_mfma_f32_32x32x16_bf16 v[52:67], v[202:205], v[218:221], v[52:67]
	global_load_dwordx4 v[96:99], v[164:165], off offset:512
	s_waitcnt lgkmcnt(5)
	v_mfma_f32_32x32x16_bf16 v[36:51], v[202:205], v[226:229], v[36:51]
	global_load_dwordx4 v[100:103], v[162:163], off offset:512
	s_waitcnt lgkmcnt(4)
	v_mfma_f32_32x32x16_bf16 v[4:19], v[210:213], v[226:229], v[4:19]
	global_load_dwordx4 v[108:111], v[160:161], off offset:512
	s_waitcnt lgkmcnt(2)
	v_mfma_f32_32x32x16_bf16 v[36:51], v[206:209], v[230:233], v[36:51]
	global_load_dwordx4 v[112:115], v[158:159], off offset:512
	s_waitcnt lgkmcnt(1)
	v_mfma_f32_32x32x16_bf16 v[4:19], v[214:217], v[230:233], v[4:19]
	global_load_dwordx4 v[116:119], v[156:157], off offset:512
	ds_read_b128 v[230:233], v197 offset:41568
	ds_read_b128 v[202:205], v196 offset:4672
	v_mfma_f32_32x32x16_bf16 v[20:35], v[210:213], v[218:221], v[20:35]
	global_load_dwordx4 v[120:123], v[154:155], off offset:512
	ds_read_b128 v[218:221], v196 offset:4704
	ds_read_b128 v[210:213], v196 offset:64
	s_waitcnt lgkmcnt(4)
; #define MFMA(a, b, c) __builtin_amdgcn_mfma_f32_32x32x16_bf16((a), (b), (c), 0, 0, 0)
; template <class Epi, class ColV>
; DI void gemm_tile(const bf16_t* __restrict__ A, int lda, const bf16_t* __restrict__ Bt, int ldb, int K, int m0, int n0, unsigned char* smem, Epi epi, ColV colv, const bf16_t* __restrict__ HYT = nullptr) {
;     ...
;     auto step = [&](int kt, u32x4 (&ldset)[8], const u32x4 (&stset)[8]) {
;         const int buf = kt & 1;
;         if (kt + 2 < nk) gload(ldset, kt + 2);
;         const bf16_t* Ab = As + (buf * 128 + 64 * wr + li) * LS + 8 * lh;
;         const bf16_t* Bb = Bs + (buf * 128 + 64 * wc + li) * LS + 8 * lh;
;         bf16x8 fa[2][2], fb[2][2], ga[2][2], gb[2][2];
; #pragma unroll
;         for (int k2 = 0; k2 < 2; ++k2) { fa[k2][0] = ld8(Ab + 16 * k2); fa[k2][1] = ld8(Ab + 32 * LS + 16 * k2); fb[k2][0] = ld8(Bb + 16 * k2); fb[k2][1] = ld8(Bb + 32 * LS + 16 * k2); }
;         __builtin_amdgcn_sched_barrier(0);
; #pragma unroll
;         for (int k2 = 0; k2 < 2; ++k2) {
;             acc[0][0] = MFMA(fa[k2][0], fb[k2][0], acc[0][0]); acc[0][1] = MFMA(fa[k2][0], fb[k2][1], acc[0][1]);
;             acc[1][0] = MFMA(fa[k2][1], fb[k2][0], acc[1][0]); acc[1][1] = MFMA(fa[k2][1], fb[k2][1], acc[1][1]);
;         }
; #pragma unroll
;         for (int k2 = 0; k2 < 2; ++k2) { const int ks = 2 + k2; ga[k2][0] = ld8(Ab + 16 * ks); ga[k2][1] = ld8(Ab + 32 * LS + 16 * ks); gb[k2][0] = ld8(Bb + 16 * ks); gb[k2][1] = ld8(Bb + 32 * LS + 16 * ks); }
; #pragma unroll
;         for (int k2 = 0; k2 < 2; ++k2) {
;             acc[0][0] = MFMA(ga[k2][0], gb[k2][0], acc[0][0]); acc[0][1] = MFMA(ga[k2][0], gb[k2][1], acc[0][1]);
;             acc[1][0] = MFMA(ga[k2][1], gb[k2][0], acc[1][0]); acc[1][1] = MFMA(ga[k2][1], gb[k2][1], acc[1][1]);
;         }
;         if (kt + 1 < nk) sstore(stset, buf ^ 1, kt + 1);
; #pragma unroll
;         for (int i = 0; i < 8; ++i) { __builtin_amdgcn_sched_group_barrier(0x008, 1, 0); __builtin_amdgcn_sched_group_barrier(0x100, 1, 0); }
; #pragma unroll
;         for (int i = 0; i < 8; ++i) { __builtin_amdgcn_sched_group_barrier(0x008, 1, 0); __builtin_amdgcn_sched_group_barrier(0x200, 1, 0); }
;         __builtin_amdgcn_sched_barrier(0);
;         __syncthreads();
;     };
	v_mfma_f32_32x32x16_bf16 v[52:67], v[206:209], v[222:225], v[52:67]
	global_load_dwordx4 v[124:127], v[152:153], off offset:512
	ds_read_b128 v[226:229], v197 offset:36960
	ds_read_b128 v[206:209], v197 offset:41536
	v_mfma_f32_32x32x16_bf16 v[20:35], v[214:217], v[222:225], v[20:35]
	global_load_dwordx4 v[128:131], v[146:147], off offset:512
	ds_read_b128 v[222:225], v197 offset:36928
	ds_read_b128 v[214:217], v196 offset:96
	s_waitcnt lgkmcnt(1)
	v_mfma_f32_32x32x16_bf16 v[52:67], v[210:213], v[222:225], v[52:67]
	s_waitcnt vmcnt(23)
	ds_write_b128 v167, v[132:135]
	v_mfma_f32_32x32x16_bf16 v[36:51], v[210:213], v[206:209], v[36:51]
	s_waitcnt vmcnt(22)
	ds_write_b128 v167, v[136:139] offset:36864
	v_mfma_f32_32x32x16_bf16 v[20:35], v[202:205], v[222:225], v[20:35]
	s_waitcnt vmcnt(21)
	ds_write_b128 v190, v[140:143]
	v_mfma_f32_32x32x16_bf16 v[4:19], v[202:205], v[206:209], v[4:19]
	s_setprio 0
	s_waitcnt vmcnt(20)
	ds_write_b128 v190, v[198:201] offset:36864
	s_waitcnt lgkmcnt(4)
	v_mfma_f32_32x32x16_bf16 v[52:67], v[214:217], v[226:229], v[52:67]
	s_waitcnt vmcnt(19)
	ds_write_b128 v191, v[174:177]
	v_mfma_f32_32x32x16_bf16 v[36:51], v[214:217], v[230:233], v[36:51]
	s_waitcnt vmcnt(18)
	ds_write_b128 v191, v[178:181] offset:36864
	v_mfma_f32_32x32x16_bf16 v[20:35], v[218:221], v[226:229], v[20:35]
	s_waitcnt vmcnt(17)
	ds_write_b128 v192, v[242:245]
	v_mfma_f32_32x32x16_bf16 v[4:19], v[218:221], v[230:233], v[4:19]
	s_waitcnt vmcnt(16)
	ds_write_b128 v192, v[246:249] offset:36864
	s_waitcnt lgkmcnt(0)
	s_barrier
	s_setprio 1
	ds_read_b128 v[202:205], v194
	ds_read_b128 v[218:221], v195 offset:36864
	ds_read_b128 v[226:229], v195 offset:41472
	ds_read_b128 v[210:213], v194 offset:4608
	ds_read_b128 v[206:209], v194 offset:32
	ds_read_b128 v[230:233], v195 offset:41504
	ds_read_b128 v[214:217], v194 offset:4640
	ds_read_b128 v[222:225], v195 offset:36896
	s_waitcnt lgkmcnt(6)
	v_mfma_f32_32x32x16_bf16 v[52:67], v[202:205], v[218:221], v[52:67]
	global_load_dwordx4 v[132:135], v[164:165], off offset:640
	s_waitcnt lgkmcnt(5)
	v_mfma_f32_32x32x16_bf16 v[36:51], v[202:205], v[226:229], v[36:51]
	global_load_dwordx4 v[136:139], v[162:163], off offset:640
	s_waitcnt lgkmcnt(4)
	v_mfma_f32_32x32x16_bf16 v[4:19], v[210:213], v[226:229], v[4:19]
	global_load_dwordx4 v[140:143], v[160:161], off offset:640
	s_waitcnt lgkmcnt(2)
	v_mfma_f32_32x32x16_bf16 v[36:51], v[206:209], v[230:233], v[36:51]
	global_load_dwordx4 v[198:201], v[158:159], off offset:640
	s_waitcnt lgkmcnt(1)
	v_mfma_f32_32x32x16_bf16 v[4:19], v[214:217], v[230:233], v[4:19]
	global_load_dwordx4 v[174:177], v[156:157], off offset:640
	ds_read_b128 v[230:233], v195 offset:41568
	ds_read_b128 v[202:205], v194 offset:4672
	v_mfma_f32_32x32x16_bf16 v[20:35], v[210:213], v[218:221], v[20:35]
	global_load_dwordx4 v[178:181], v[154:155], off offset:640
	ds_read_b128 v[218:221], v194 offset:4704
	ds_read_b128 v[210:213], v194 offset:64
	s_waitcnt lgkmcnt(4)
	v_mfma_f32_32x32x16_bf16 v[52:67], v[206:209], v[222:225], v[52:67]
	global_load_dwordx4 v[242:245], v[152:153], off offset:640
	ds_read_b128 v[226:229], v195 offset:36960
	ds_read_b128 v[206:209], v195 offset:41536
	v_mfma_f32_32x32x16_bf16 v[20:35], v[214:217], v[222:225], v[20:35]
	global_load_dwordx4 v[246:249], v[146:147], off offset:640
	ds_read_b128 v[222:225], v195 offset:36928
	ds_read_b128 v[214:217], v194 offset:96
	s_waitcnt lgkmcnt(1)
	v_mfma_f32_32x32x16_bf16 v[52:67], v[210:213], v[222:225], v[52:67]
	s_waitcnt vmcnt(23)
	ds_write_b128 v167, v[68:71] offset:18432
	v_mfma_f32_32x32x16_bf16 v[36:51], v[210:213], v[206:209], v[36:51]
	s_waitcnt vmcnt(22)
	ds_write_b128 v167, v[72:75] offset:55296
	v_mfma_f32_32x32x16_bf16 v[20:35], v[202:205], v[222:225], v[20:35]
	s_waitcnt vmcnt(21)
	ds_write_b128 v190, v[76:79] offset:18432
	v_mfma_f32_32x32x16_bf16 v[4:19], v[202:205], v[206:209], v[4:19]
	s_setprio 0
	s_waitcnt vmcnt(20)
	ds_write_b128 v190, v[80:83] offset:55296
	s_waitcnt lgkmcnt(4)
	v_mfma_f32_32x32x16_bf16 v[52:67], v[214:217], v[226:229], v[52:67]
	s_waitcnt vmcnt(19)
	ds_write_b128 v191, v[84:87] offset:18432
	v_mfma_f32_32x32x16_bf16 v[36:51], v[214:217], v[230:233], v[36:51]
	s_waitcnt vmcnt(18)
	ds_write_b128 v191, v[88:91] offset:55296
	v_mfma_f32_32x32x16_bf16 v[20:35], v[218:221], v[226:229], v[20:35]
	s_waitcnt vmcnt(17)
	ds_write_b128 v192, v[92:95] offset:18432
	v_mfma_f32_32x32x16_bf16 v[4:19], v[218:221], v[230:233], v[4:19]
	s_waitcnt vmcnt(16)
	ds_write_b128 v192, v[104:107] offset:55296
	s_waitcnt lgkmcnt(0)
	s_barrier
; #define MFMA(a, b, c) __builtin_amdgcn_mfma_f32_32x32x16_bf16((a), (b), (c), 0, 0, 0)
; template <class Epi, class ColV>
; DI void gemm_tile(const bf16_t* __restrict__ A, int lda, const bf16_t* __restrict__ Bt, int ldb, int K, int m0, int n0, unsigned char* smem, Epi epi, ColV colv, const bf16_t* __restrict__ HYT = nullptr) {
;     ...
;     auto step = [&](int kt, u32x4 (&ldset)[8], const u32x4 (&stset)[8]) {
;         const int buf = kt & 1;
;         if (kt + 2 < nk) gload(ldset, kt + 2);
;         const bf16_t* Ab = As + (buf * 128 + 64 * wr + li) * LS + 8 * lh;
;         const bf16_t* Bb = Bs + (buf * 128 + 64 * wc + li) * LS + 8 * lh;
;         bf16x8 fa[2][2], fb[2][2], ga[2][2], gb[2][2];
; #pragma unroll
;         for (int k2 = 0; k2 < 2; ++k2) { fa[k2][0] = ld8(Ab + 16 * k2); fa[k2][1] = ld8(Ab + 32 * LS + 16 * k2); fb[k2][0] = ld8(Bb + 16 * k2); fb[k2][1] = ld8(Bb + 32 * LS + 16 * k2); }
;         __builtin_amdgcn_sched_barrier(0);
; #pragma unroll
;         for (int k2 = 0; k2 < 2; ++k2) {
;             acc[0][0] = MFMA(fa[k2][0], fb[k2][0], acc[0][0]); acc[0][1] = MFMA(fa[k2][0], fb[k2][1], acc[0][1]);
;             acc[1][0] = MFMA(fa[k2][1], fb[k2][0], acc[1][0]); acc[1][1] = MFMA(fa[k2][1], fb[k2][1], acc[1][1]);
;         }
; #pragma unroll
;         for (int k2 = 0; k2 < 2; ++k2) { const int ks = 2 + k2; ga[k2][0] = ld8(Ab + 16 * ks); ga[k2][1] = ld8(Ab + 32 * LS + 16 * ks); gb[k2][0] = ld8(Bb + 16 * ks); gb[k2][1] = ld8(Bb + 32 * LS + 16 * ks); }
; #pragma unroll
;         for (int k2 = 0; k2 < 2; ++k2) {
;             acc[0][0] = MFMA(ga[k2][0], gb[k2][0], acc[0][0]); acc[0][1] = MFMA(ga[k2][0], gb[k2][1], acc[0][1]);
;             acc[1][0] = MFMA(ga[k2][1], gb[k2][0], acc[1][0]); acc[1][1] = MFMA(ga[k2][1], gb[k2][1], acc[1][1]);
;         }
;         if (kt + 1 < nk) sstore(stset, buf ^ 1, kt + 1);
; #pragma unroll
;         for (int i = 0; i < 8; ++i) { __builtin_amdgcn_sched_group_barrier(0x008, 1, 0); __builtin_amdgcn_sched_group_barrier(0x100, 1, 0); }
; #pragma unroll
;         for (int i = 0; i < 8; ++i) { __builtin_amdgcn_sched_group_barrier(0x008, 1, 0); __builtin_amdgcn_sched_group_barrier(0x200, 1, 0); }
;         __builtin_amdgcn_sched_barrier(0);
;         __syncthreads();
;     };
	s_setprio 1
	ds_read_b128 v[202:205], v196
	ds_read_b128 v[218:221], v197 offset:36864
	ds_read_b128 v[226:229], v197 offset:41472
	ds_read_b128 v[210:213], v196 offset:4608
	ds_read_b128 v[206:209], v196 offset:32
	ds_read_b128 v[230:233], v197 offset:41504
	ds_read_b128 v[214:217], v196 offset:4640
	ds_read_b128 v[222:225], v197 offset:36896
	s_waitcnt lgkmcnt(6)
	v_mfma_f32_32x32x16_bf16 v[52:67], v[202:205], v[218:221], v[52:67]
	global_load_dwordx4 v[68:71], v[164:165], off offset:768
	s_waitcnt lgkmcnt(5)
	v_mfma_f32_32x32x16_bf16 v[36:51], v[202:205], v[226:229], v[36:51]
	global_load_dwordx4 v[72:75], v[162:163], off offset:768
	s_waitcnt lgkmcnt(4)
	v_mfma_f32_32x32x16_bf16 v[4:19], v[210:213], v[226:229], v[4:19]
	global_load_dwordx4 v[76:79], v[160:161], off offset:768
	s_waitcnt lgkmcnt(2)
	v_mfma_f32_32x32x16_bf16 v[36:51], v[206:209], v[230:233], v[36:51]
	global_load_dwordx4 v[80:83], v[158:159], off offset:768
	s_waitcnt lgkmcnt(1)
	v_mfma_f32_32x32x16_bf16 v[4:19], v[214:217], v[230:233], v[4:19]
	global_load_dwordx4 v[84:87], v[156:157], off offset:768
	ds_read_b128 v[230:233], v197 offset:41568
	ds_read_b128 v[202:205], v196 offset:4672
	v_mfma_f32_32x32x16_bf16 v[20:35], v[210:213], v[218:221], v[20:35]
	global_load_dwordx4 v[88:91], v[154:155], off offset:768
	ds_read_b128 v[218:221], v196 offset:4704
	ds_read_b128 v[210:213], v196 offset:64
	s_waitcnt lgkmcnt(4)
	v_mfma_f32_32x32x16_bf16 v[52:67], v[206:209], v[222:225], v[52:67]
	global_load_dwordx4 v[92:95], v[152:153], off offset:768
	ds_read_b128 v[226:229], v197 offset:36960
	ds_read_b128 v[206:209], v197 offset:41536
	v_mfma_f32_32x32x16_bf16 v[20:35], v[214:217], v[222:225], v[20:35]
	global_load_dwordx4 v[104:107], v[146:147], off offset:768
	ds_read_b128 v[222:225], v197 offset:36928
	ds_read_b128 v[214:217], v196 offset:96
	s_waitcnt lgkmcnt(1)
	v_mfma_f32_32x32x16_bf16 v[52:67], v[210:213], v[222:225], v[52:67]
	s_waitcnt vmcnt(23)
	ds_write_b128 v167, v[96:99]
	v_mfma_f32_32x32x16_bf16 v[36:51], v[210:213], v[206:209], v[36:51]
	s_waitcnt vmcnt(22)
	ds_write_b128 v167, v[100:103] offset:36864
	v_mfma_f32_32x32x16_bf16 v[20:35], v[202:205], v[222:225], v[20:35]
	s_waitcnt vmcnt(21)
	ds_write_b128 v190, v[108:111]
	v_mfma_f32_32x32x16_bf16 v[4:19], v[202:205], v[206:209], v[4:19]
	s_setprio 0
	s_waitcnt vmcnt(20)
	ds_write_b128 v190, v[112:115] offset:36864
	s_waitcnt lgkmcnt(4)
	v_mfma_f32_32x32x16_bf16 v[52:67], v[214:217], v[226:229], v[52:67]
	s_waitcnt vmcnt(19)
	ds_write_b128 v191, v[116:119]
	v_mfma_f32_32x32x16_bf16 v[36:51], v[214:217], v[230:233], v[36:51]
	s_waitcnt vmcnt(18)
	ds_write_b128 v191, v[120:123] offset:36864
	v_mfma_f32_32x32x16_bf16 v[20:35], v[218:221], v[226:229], v[20:35]
	s_waitcnt vmcnt(17)
	ds_write_b128 v192, v[124:127]
	v_mfma_f32_32x32x16_bf16 v[4:19], v[218:221], v[230:233], v[4:19]
	s_waitcnt vmcnt(16)
	ds_write_b128 v192, v[128:131] offset:36864
	s_waitcnt lgkmcnt(0)
	s_barrier
	s_setprio 1
	ds_read_b128 v[202:205], v194
	ds_read_b128 v[218:221], v195 offset:36864
	ds_read_b128 v[226:229], v195 offset:41472
	ds_read_b128 v[210:213], v194 offset:4608
	ds_read_b128 v[206:209], v194 offset:32
	ds_read_b128 v[230:233], v195 offset:41504
	ds_read_b128 v[214:217], v194 offset:4640
	ds_read_b128 v[222:225], v195 offset:36896
	s_waitcnt lgkmcnt(6)
	v_mfma_f32_32x32x16_bf16 v[52:67], v[202:205], v[218:221], v[52:67]
	global_load_dwordx4 v[96:99], v[164:165], off offset:896
	s_waitcnt lgkmcnt(5)
	v_mfma_f32_32x32x16_bf16 v[36:51], v[202:205], v[226:229], v[36:51]
	global_load_dwordx4 v[100:103], v[162:163], off offset:896
	s_waitcnt lgkmcnt(4)
	v_mfma_f32_32x32x16_bf16 v[4:19], v[210:213], v[226:229], v[4:19]
	global_load_dwordx4 v[108:111], v[160:161], off offset:896
	s_waitcnt lgkmcnt(2)
	v_mfma_f32_32x32x16_bf16 v[36:51], v[206:209], v[230:233], v[36:51]
	global_load_dwordx4 v[112:115], v[158:159], off offset:896
	s_waitcnt lgkmcnt(1)
	v_mfma_f32_32x32x16_bf16 v[4:19], v[214:217], v[230:233], v[4:19]
	global_load_dwordx4 v[116:119], v[156:157], off offset:896
	ds_read_b128 v[230:233], v195 offset:41568
	ds_read_b128 v[202:205], v194 offset:4672
	v_mfma_f32_32x32x16_bf16 v[20:35], v[210:213], v[218:221], v[20:35]
	global_load_dwordx4 v[120:123], v[154:155], off offset:896
	ds_read_b128 v[218:221], v194 offset:4704
	ds_read_b128 v[210:213], v194 offset:64
	s_waitcnt lgkmcnt(4)
	v_mfma_f32_32x32x16_bf16 v[52:67], v[206:209], v[222:225], v[52:67]
	global_load_dwordx4 v[124:127], v[152:153], off offset:896
	ds_read_b128 v[226:229], v195 offset:36960
	ds_read_b128 v[206:209], v195 offset:41536
	v_mfma_f32_32x32x16_bf16 v[20:35], v[214:217], v[222:225], v[20:35]
	global_load_dwordx4 v[128:131], v[146:147], off offset:896
	ds_read_b128 v[222:225], v195 offset:36928
	ds_read_b128 v[214:217], v194 offset:96
	s_waitcnt lgkmcnt(1)
	v_mfma_f32_32x32x16_bf16 v[52:67], v[210:213], v[222:225], v[52:67]
	s_waitcnt vmcnt(23)
	ds_write_b128 v167, v[132:135] offset:18432
	v_mfma_f32_32x32x16_bf16 v[36:51], v[210:213], v[206:209], v[36:51]
	s_waitcnt vmcnt(22)
	ds_write_b128 v167, v[136:139] offset:55296
	v_mfma_f32_32x32x16_bf16 v[20:35], v[202:205], v[222:225], v[20:35]
	s_waitcnt vmcnt(21)
	ds_write_b128 v190, v[140:143] offset:18432
	v_mfma_f32_32x32x16_bf16 v[4:19], v[202:205], v[206:209], v[4:19]
	s_setprio 0
	s_waitcnt vmcnt(20)
	ds_write_b128 v190, v[198:201] offset:55296
	s_waitcnt lgkmcnt(4)
	v_mfma_f32_32x32x16_bf16 v[52:67], v[214:217], v[226:229], v[52:67]
	s_waitcnt vmcnt(19)
	ds_write_b128 v191, v[174:177] offset:18432
	v_mfma_f32_32x32x16_bf16 v[36:51], v[214:217], v[230:233], v[36:51]
	s_waitcnt vmcnt(18)
	ds_write_b128 v191, v[178:181] offset:55296
	v_mfma_f32_32x32x16_bf16 v[20:35], v[218:221], v[226:229], v[20:35]
	s_waitcnt vmcnt(17)
	ds_write_b128 v192, v[242:245] offset:18432
	v_mfma_f32_32x32x16_bf16 v[4:19], v[218:221], v[230:233], v[4:19]
	s_waitcnt vmcnt(16)
	ds_write_b128 v192, v[246:249] offset:55296
	s_waitcnt lgkmcnt(0)
	s_barrier
; #define MFMA(a, b, c) __builtin_amdgcn_mfma_f32_32x32x16_bf16((a), (b), (c), 0, 0, 0)
; template <class Epi, class ColV>
; DI void gemm_tile(const bf16_t* __restrict__ A, int lda, const bf16_t* __restrict__ Bt, int ldb, int K, int m0, int n0, unsigned char* smem, Epi epi, ColV colv, const bf16_t* __restrict__ HYT = nullptr) {
;     ...
;     auto step = [&](int kt, u32x4 (&ldset)[8], const u32x4 (&stset)[8]) {
;         const int buf = kt & 1;
;         if (kt + 2 < nk) gload(ldset, kt + 2);
;         const bf16_t* Ab = As + (buf * 128 + 64 * wr + li) * LS + 8 * lh;
;         const bf16_t* Bb = Bs + (buf * 128 + 64 * wc + li) * LS + 8 * lh;
;         bf16x8 fa[2][2], fb[2][2], ga[2][2], gb[2][2];
; #pragma unroll
;         for (int k2 = 0; k2 < 2; ++k2) { fa[k2][0] = ld8(Ab + 16 * k2); fa[k2][1] = ld8(Ab + 32 * LS + 16 * k2); fb[k2][0] = ld8(Bb + 16 * k2); fb[k2][1] = ld8(Bb + 32 * LS + 16 * k2); }
;         __builtin_amdgcn_sched_barrier(0);
; #pragma unroll
;         for (int k2 = 0; k2 < 2; ++k2) {
;             acc[0][0] = MFMA(fa[k2][0], fb[k2][0], acc[0][0]); acc[0][1] = MFMA(fa[k2][0], fb[k2][1], acc[0][1]);
;             acc[1][0] = MFMA(fa[k2][1], fb[k2][0], acc[1][0]); acc[1][1] = MFMA(fa[k2][1], fb[k2][1], acc[1][1]);
;         }
; #pragma unroll
;         for (int k2 = 0; k2 < 2; ++k2) { const int ks = 2 + k2; ga[k2][0] = ld8(Ab + 16 * ks); ga[k2][1] = ld8(Ab + 32 * LS + 16 * ks); gb[k2][0] = ld8(Bb + 16 * ks); gb[k2][1] = ld8(Bb + 32 * LS + 16 * ks); }
; #pragma unroll
;         for (int k2 = 0; k2 < 2; ++k2) {
;             acc[0][0] = MFMA(ga[k2][0], gb[k2][0], acc[0][0]); acc[0][1] = MFMA(ga[k2][0], gb[k2][1], acc[0][1]);
;             acc[1][0] = MFMA(ga[k2][1], gb[k2][0], acc[1][0]); acc[1][1] = MFMA(ga[k2][1], gb[k2][1], acc[1][1]);
;         }
;         if (kt + 1 < nk) sstore(stset, buf ^ 1, kt + 1);
; #pragma unroll
;         for (int i = 0; i < 8; ++i) { __builtin_amdgcn_sched_group_barrier(0x008, 1, 0); __builtin_amdgcn_sched_group_barrier(0x100, 1, 0); }
; #pragma unroll
;         for (int i = 0; i < 8; ++i) { __builtin_amdgcn_sched_group_barrier(0x008, 1, 0); __builtin_amdgcn_sched_group_barrier(0x200, 1, 0); }
;         __builtin_amdgcn_sched_barrier(0);
;         __syncthreads();
;     };
	s_setprio 1
	ds_read_b128 v[202:205], v196
	ds_read_b128 v[218:221], v197 offset:36864
	ds_read_b128 v[226:229], v197 offset:41472
	ds_read_b128 v[210:213], v196 offset:4608
	ds_read_b128 v[206:209], v196 offset:32
	ds_read_b128 v[230:233], v197 offset:41504
	ds_read_b128 v[214:217], v196 offset:4640
	ds_read_b128 v[222:225], v197 offset:36896
	s_waitcnt lgkmcnt(6)
	v_mfma_f32_32x32x16_bf16 v[52:67], v[202:205], v[218:221], v[52:67]
	global_load_dwordx4 v[132:135], v[164:165], off offset:1024
	s_waitcnt lgkmcnt(5)
	v_mfma_f32_32x32x16_bf16 v[36:51], v[202:205], v[226:229], v[36:51]
	global_load_dwordx4 v[136:139], v[162:163], off offset:1024
	s_waitcnt lgkmcnt(4)
	v_mfma_f32_32x32x16_bf16 v[4:19], v[210:213], v[226:229], v[4:19]
	global_load_dwordx4 v[140:143], v[160:161], off offset:1024
	s_waitcnt lgkmcnt(2)
	v_mfma_f32_32x32x16_bf16 v[36:51], v[206:209], v[230:233], v[36:51]
	global_load_dwordx4 v[198:201], v[158:159], off offset:1024
	s_waitcnt lgkmcnt(1)
	v_mfma_f32_32x32x16_bf16 v[4:19], v[214:217], v[230:233], v[4:19]
	global_load_dwordx4 v[174:177], v[156:157], off offset:1024
	ds_read_b128 v[230:233], v197 offset:41568
	ds_read_b128 v[202:205], v196 offset:4672
	v_mfma_f32_32x32x16_bf16 v[20:35], v[210:213], v[218:221], v[20:35]
	global_load_dwordx4 v[178:181], v[154:155], off offset:1024
	ds_read_b128 v[218:221], v196 offset:4704
	ds_read_b128 v[210:213], v196 offset:64
	s_waitcnt lgkmcnt(4)
	v_mfma_f32_32x32x16_bf16 v[52:67], v[206:209], v[222:225], v[52:67]
	global_load_dwordx4 v[242:245], v[152:153], off offset:1024
	ds_read_b128 v[226:229], v197 offset:36960
	ds_read_b128 v[206:209], v197 offset:41536
	v_mfma_f32_32x32x16_bf16 v[20:35], v[214:217], v[222:225], v[20:35]
	global_load_dwordx4 v[246:249], v[146:147], off offset:1024
	ds_read_b128 v[222:225], v197 offset:36928
	ds_read_b128 v[214:217], v196 offset:96
	s_waitcnt lgkmcnt(1)
	v_mfma_f32_32x32x16_bf16 v[52:67], v[210:213], v[222:225], v[52:67]
	s_waitcnt vmcnt(23)
	ds_write_b128 v167, v[68:71]
	v_mfma_f32_32x32x16_bf16 v[36:51], v[210:213], v[206:209], v[36:51]
	s_waitcnt vmcnt(22)
	ds_write_b128 v167, v[72:75] offset:36864
	v_mfma_f32_32x32x16_bf16 v[20:35], v[202:205], v[222:225], v[20:35]
	s_waitcnt vmcnt(21)
	ds_write_b128 v190, v[76:79]
	v_mfma_f32_32x32x16_bf16 v[4:19], v[202:205], v[206:209], v[4:19]
	s_setprio 0
	s_waitcnt vmcnt(20)
	ds_write_b128 v190, v[80:83] offset:36864
	s_waitcnt lgkmcnt(4)
	v_mfma_f32_32x32x16_bf16 v[52:67], v[214:217], v[226:229], v[52:67]
	s_waitcnt vmcnt(19)
	ds_write_b128 v191, v[84:87]
	v_mfma_f32_32x32x16_bf16 v[36:51], v[214:217], v[230:233], v[36:51]
	s_waitcnt vmcnt(18)
	ds_write_b128 v191, v[88:91] offset:36864
	v_mfma_f32_32x32x16_bf16 v[20:35], v[218:221], v[226:229], v[20:35]
	s_waitcnt vmcnt(17)
	ds_write_b128 v192, v[92:95]
	v_mfma_f32_32x32x16_bf16 v[4:19], v[218:221], v[230:233], v[4:19]
	s_waitcnt vmcnt(16)
	ds_write_b128 v192, v[104:107] offset:36864
	s_waitcnt lgkmcnt(0)
	s_barrier
	s_setprio 1
	ds_read_b128 v[202:205], v194
	ds_read_b128 v[218:221], v195 offset:36864
	ds_read_b128 v[226:229], v195 offset:41472
	ds_read_b128 v[210:213], v194 offset:4608
	ds_read_b128 v[206:209], v194 offset:32
	ds_read_b128 v[230:233], v195 offset:41504
	ds_read_b128 v[214:217], v194 offset:4640
	ds_read_b128 v[222:225], v195 offset:36896
	s_waitcnt lgkmcnt(6)
	v_mfma_f32_32x32x16_bf16 v[52:67], v[202:205], v[218:221], v[52:67]
	global_load_dwordx4 v[68:71], v[164:165], off offset:1152
	s_waitcnt lgkmcnt(5)
	v_mfma_f32_32x32x16_bf16 v[36:51], v[202:205], v[226:229], v[36:51]
	global_load_dwordx4 v[72:75], v[162:163], off offset:1152
	s_waitcnt lgkmcnt(4)
	v_mfma_f32_32x32x16_bf16 v[4:19], v[210:213], v[226:229], v[4:19]
	global_load_dwordx4 v[76:79], v[160:161], off offset:1152
	s_waitcnt lgkmcnt(2)
	v_mfma_f32_32x32x16_bf16 v[36:51], v[206:209], v[230:233], v[36:51]
	global_load_dwordx4 v[80:83], v[158:159], off offset:1152
	s_waitcnt lgkmcnt(1)
	v_mfma_f32_32x32x16_bf16 v[4:19], v[214:217], v[230:233], v[4:19]
	global_load_dwordx4 v[84:87], v[156:157], off offset:1152
	ds_read_b128 v[230:233], v195 offset:41568
	ds_read_b128 v[202:205], v194 offset:4672
	v_mfma_f32_32x32x16_bf16 v[20:35], v[210:213], v[218:221], v[20:35]
	global_load_dwordx4 v[88:91], v[154:155], off offset:1152
	ds_read_b128 v[218:221], v194 offset:4704
	ds_read_b128 v[210:213], v194 offset:64
	s_waitcnt lgkmcnt(4)
	v_mfma_f32_32x32x16_bf16 v[52:67], v[206:209], v[222:225], v[52:67]
	global_load_dwordx4 v[92:95], v[152:153], off offset:1152
	ds_read_b128 v[226:229], v195 offset:36960
	ds_read_b128 v[206:209], v195 offset:41536
	v_mfma_f32_32x32x16_bf16 v[20:35], v[214:217], v[222:225], v[20:35]
	global_load_dwordx4 v[104:107], v[146:147], off offset:1152
	ds_read_b128 v[222:225], v195 offset:36928
	ds_read_b128 v[214:217], v194 offset:96
	s_waitcnt lgkmcnt(1)
	v_mfma_f32_32x32x16_bf16 v[52:67], v[210:213], v[222:225], v[52:67]
	s_waitcnt vmcnt(23)
	ds_write_b128 v167, v[96:99] offset:18432
	v_mfma_f32_32x32x16_bf16 v[36:51], v[210:213], v[206:209], v[36:51]
	s_waitcnt vmcnt(22)
	ds_write_b128 v167, v[100:103] offset:55296
	v_mfma_f32_32x32x16_bf16 v[20:35], v[202:205], v[222:225], v[20:35]
	s_waitcnt vmcnt(21)
	ds_write_b128 v190, v[108:111] offset:18432
	v_mfma_f32_32x32x16_bf16 v[4:19], v[202:205], v[206:209], v[4:19]
	s_setprio 0
	s_waitcnt vmcnt(20)
	ds_write_b128 v190, v[112:115] offset:55296
	s_waitcnt lgkmcnt(4)
	v_mfma_f32_32x32x16_bf16 v[52:67], v[214:217], v[226:229], v[52:67]
	s_waitcnt vmcnt(19)
	ds_write_b128 v191, v[116:119] offset:18432
	v_mfma_f32_32x32x16_bf16 v[36:51], v[214:217], v[230:233], v[36:51]
	s_waitcnt vmcnt(18)
	ds_write_b128 v191, v[120:123] offset:55296
	v_mfma_f32_32x32x16_bf16 v[20:35], v[218:221], v[226:229], v[20:35]
	s_waitcnt vmcnt(17)
	ds_write_b128 v192, v[124:127] offset:18432
	v_mfma_f32_32x32x16_bf16 v[4:19], v[218:221], v[230:233], v[4:19]
	s_waitcnt vmcnt(16)
	ds_write_b128 v192, v[128:131] offset:55296
	s_waitcnt lgkmcnt(0)
	s_barrier
; #define MFMA(a, b, c) __builtin_amdgcn_mfma_f32_32x32x16_bf16((a), (b), (c), 0, 0, 0)
; template <class Epi, class ColV>
; DI void gemm_tile(const bf16_t* __restrict__ A, int lda, const bf16_t* __restrict__ Bt, int ldb, int K, int m0, int n0, unsigned char* smem, Epi epi, ColV colv, const bf16_t* __restrict__ HYT = nullptr) {
;     ...
;     auto step = [&](int kt, u32x4 (&ldset)[8], const u32x4 (&stset)[8]) {
;         const int buf = kt & 1;
;         if (kt + 2 < nk) gload(ldset, kt + 2);
;         const bf16_t* Ab = As + (buf * 128 + 64 * wr + li) * LS + 8 * lh;
;         const bf16_t* Bb = Bs + (buf * 128 + 64 * wc + li) * LS + 8 * lh;
;         bf16x8 fa[2][2], fb[2][2], ga[2][2], gb[2][2];
; #pragma unroll
;         for (int k2 = 0; k2 < 2; ++k2) { fa[k2][0] = ld8(Ab + 16 * k2); fa[k2][1] = ld8(Ab + 32 * LS + 16 * k2); fb[k2][0] = ld8(Bb + 16 * k2); fb[k2][1] = ld8(Bb + 32 * LS + 16 * k2); }
;         __builtin_amdgcn_sched_barrier(0);
; #pragma unroll
;         for (int k2 = 0; k2 < 2; ++k2) {
;             acc[0][0] = MFMA(fa[k2][0], fb[k2][0], acc[0][0]); acc[0][1] = MFMA(fa[k2][0], fb[k2][1], acc[0][1]);
;             acc[1][0] = MFMA(fa[k2][1], fb[k2][0], acc[1][0]); acc[1][1] = MFMA(fa[k2][1], fb[k2][1], acc[1][1]);
;         }
; #pragma unroll
;         for (int k2 = 0; k2 < 2; ++k2) { const int ks = 2 + k2; ga[k2][0] = ld8(Ab + 16 * ks); ga[k2][1] = ld8(Ab + 32 * LS + 16 * ks); gb[k2][0] = ld8(Bb + 16 * ks); gb[k2][1] = ld8(Bb + 32 * LS + 16 * ks); }
; #pragma unroll
;         for (int k2 = 0; k2 < 2; ++k2) {
;             acc[0][0] = MFMA(ga[k2][0], gb[k2][0], acc[0][0]); acc[0][1] = MFMA(ga[k2][0], gb[k2][1], acc[0][1]);
;             acc[1][0] = MFMA(ga[k2][1], gb[k2][0], acc[1][0]); acc[1][1] = MFMA(ga[k2][1], gb[k2][1], acc[1][1]);
;         }
;         if (kt + 1 < nk) sstore(stset, buf ^ 1, kt + 1);
; #pragma unroll
;         for (int i = 0; i < 8; ++i) { __builtin_amdgcn_sched_group_barrier(0x008, 1, 0); __builtin_amdgcn_sched_group_barrier(0x100, 1, 0); }
; #pragma unroll
;         for (int i = 0; i < 8; ++i) { __builtin_amdgcn_sched_group_barrier(0x008, 1, 0); __builtin_amdgcn_sched_group_barrier(0x200, 1, 0); }
;         __builtin_amdgcn_sched_barrier(0);
;         __syncthreads();
;     };
	s_setprio 1
	ds_read_b128 v[202:205], v196
	ds_read_b128 v[218:221], v197 offset:36864
	ds_read_b128 v[226:229], v197 offset:41472
	ds_read_b128 v[210:213], v196 offset:4608
	ds_read_b128 v[206:209], v196 offset:32
	ds_read_b128 v[230:233], v197 offset:41504
	ds_read_b128 v[214:217], v196 offset:4640
	ds_read_b128 v[222:225], v197 offset:36896
	s_waitcnt lgkmcnt(6)
	v_mfma_f32_32x32x16_bf16 v[52:67], v[202:205], v[218:221], v[52:67]
	global_load_dwordx4 v[96:99], v[164:165], off offset:1280
	s_waitcnt lgkmcnt(5)
	v_mfma_f32_32x32x16_bf16 v[36:51], v[202:205], v[226:229], v[36:51]
	global_load_dwordx4 v[100:103], v[162:163], off offset:1280
	s_waitcnt lgkmcnt(4)
	v_mfma_f32_32x32x16_bf16 v[4:19], v[210:213], v[226:229], v[4:19]
	global_load_dwordx4 v[108:111], v[160:161], off offset:1280
	s_waitcnt lgkmcnt(2)
	v_mfma_f32_32x32x16_bf16 v[36:51], v[206:209], v[230:233], v[36:51]
	global_load_dwordx4 v[112:115], v[158:159], off offset:1280
	s_waitcnt lgkmcnt(1)
	v_mfma_f32_32x32x16_bf16 v[4:19], v[214:217], v[230:233], v[4:19]
	global_load_dwordx4 v[116:119], v[156:157], off offset:1280
	ds_read_b128 v[230:233], v197 offset:41568
	ds_read_b128 v[202:205], v196 offset:4672
	v_mfma_f32_32x32x16_bf16 v[20:35], v[210:213], v[218:221], v[20:35]
	global_load_dwordx4 v[120:123], v[154:155], off offset:1280
	ds_read_b128 v[218:221], v196 offset:4704
	ds_read_b128 v[210:213], v196 offset:64
	s_waitcnt lgkmcnt(4)
	v_mfma_f32_32x32x16_bf16 v[52:67], v[206:209], v[222:225], v[52:67]
	global_load_dwordx4 v[124:127], v[152:153], off offset:1280
	ds_read_b128 v[226:229], v197 offset:36960
	ds_read_b128 v[206:209], v197 offset:41536
	v_mfma_f32_32x32x16_bf16 v[20:35], v[214:217], v[222:225], v[20:35]
	global_load_dwordx4 v[128:131], v[146:147], off offset:1280
	ds_read_b128 v[222:225], v197 offset:36928
	ds_read_b128 v[214:217], v196 offset:96
	s_waitcnt lgkmcnt(1)
	v_mfma_f32_32x32x16_bf16 v[52:67], v[210:213], v[222:225], v[52:67]
	s_waitcnt vmcnt(23)
	ds_write_b128 v167, v[132:135]
	v_mfma_f32_32x32x16_bf16 v[36:51], v[210:213], v[206:209], v[36:51]
	s_waitcnt vmcnt(22)
	ds_write_b128 v167, v[136:139] offset:36864
	v_mfma_f32_32x32x16_bf16 v[20:35], v[202:205], v[222:225], v[20:35]
	s_waitcnt vmcnt(21)
	ds_write_b128 v190, v[140:143]
	v_mfma_f32_32x32x16_bf16 v[4:19], v[202:205], v[206:209], v[4:19]
	s_setprio 0
	s_waitcnt vmcnt(20)
	ds_write_b128 v190, v[198:201] offset:36864
	s_waitcnt lgkmcnt(4)
	v_mfma_f32_32x32x16_bf16 v[52:67], v[214:217], v[226:229], v[52:67]
	s_waitcnt vmcnt(19)
	ds_write_b128 v191, v[174:177]
	v_mfma_f32_32x32x16_bf16 v[36:51], v[214:217], v[230:233], v[36:51]
	s_waitcnt vmcnt(18)
	ds_write_b128 v191, v[178:181] offset:36864
	v_mfma_f32_32x32x16_bf16 v[20:35], v[218:221], v[226:229], v[20:35]
	s_waitcnt vmcnt(17)
	ds_write_b128 v192, v[242:245]
	v_mfma_f32_32x32x16_bf16 v[4:19], v[218:221], v[230:233], v[4:19]
	s_waitcnt vmcnt(16)
	ds_write_b128 v192, v[246:249] offset:36864
	s_waitcnt lgkmcnt(0)
	s_barrier
	s_setprio 1
	ds_read_b128 v[202:205], v194
	ds_read_b128 v[218:221], v195 offset:36864
	ds_read_b128 v[226:229], v195 offset:41472
	ds_read_b128 v[210:213], v194 offset:4608
	ds_read_b128 v[206:209], v194 offset:32
	ds_read_b128 v[230:233], v195 offset:41504
	ds_read_b128 v[214:217], v194 offset:4640
	ds_read_b128 v[222:225], v195 offset:36896
	s_waitcnt lgkmcnt(6)
	v_mfma_f32_32x32x16_bf16 v[52:67], v[202:205], v[218:221], v[52:67]
	global_load_dwordx4 v[132:135], v[164:165], off offset:1408
	s_waitcnt lgkmcnt(5)
	v_mfma_f32_32x32x16_bf16 v[36:51], v[202:205], v[226:229], v[36:51]
	global_load_dwordx4 v[136:139], v[162:163], off offset:1408
	s_waitcnt lgkmcnt(4)
	v_mfma_f32_32x32x16_bf16 v[4:19], v[210:213], v[226:229], v[4:19]
	global_load_dwordx4 v[140:143], v[160:161], off offset:1408
	s_waitcnt lgkmcnt(2)
	v_mfma_f32_32x32x16_bf16 v[36:51], v[206:209], v[230:233], v[36:51]
	global_load_dwordx4 v[198:201], v[158:159], off offset:1408
	s_waitcnt lgkmcnt(1)
	v_mfma_f32_32x32x16_bf16 v[4:19], v[214:217], v[230:233], v[4:19]
	global_load_dwordx4 v[174:177], v[156:157], off offset:1408
	ds_read_b128 v[230:233], v195 offset:41568
	ds_read_b128 v[202:205], v194 offset:4672
	v_mfma_f32_32x32x16_bf16 v[20:35], v[210:213], v[218:221], v[20:35]
	global_load_dwordx4 v[178:181], v[154:155], off offset:1408
	ds_read_b128 v[218:221], v194 offset:4704
	ds_read_b128 v[210:213], v194 offset:64
	s_waitcnt lgkmcnt(4)
	v_mfma_f32_32x32x16_bf16 v[52:67], v[206:209], v[222:225], v[52:67]
	global_load_dwordx4 v[242:245], v[152:153], off offset:1408
	ds_read_b128 v[226:229], v195 offset:36960
	ds_read_b128 v[206:209], v195 offset:41536
	v_mfma_f32_32x32x16_bf16 v[20:35], v[214:217], v[222:225], v[20:35]
	global_load_dwordx4 v[246:249], v[146:147], off offset:1408
	ds_read_b128 v[222:225], v195 offset:36928
	ds_read_b128 v[214:217], v194 offset:96
	s_waitcnt lgkmcnt(1)
	v_mfma_f32_32x32x16_bf16 v[52:67], v[210:213], v[222:225], v[52:67]
	s_waitcnt vmcnt(23)
	ds_write_b128 v167, v[68:71] offset:18432
	v_mfma_f32_32x32x16_bf16 v[36:51], v[210:213], v[206:209], v[36:51]
	s_waitcnt vmcnt(22)
	ds_write_b128 v167, v[72:75] offset:55296
	v_mfma_f32_32x32x16_bf16 v[20:35], v[202:205], v[222:225], v[20:35]
	s_waitcnt vmcnt(21)
	ds_write_b128 v190, v[76:79] offset:18432
	v_mfma_f32_32x32x16_bf16 v[4:19], v[202:205], v[206:209], v[4:19]
	s_setprio 0
	s_waitcnt vmcnt(20)
	ds_write_b128 v190, v[80:83] offset:55296
	s_waitcnt lgkmcnt(4)
	v_mfma_f32_32x32x16_bf16 v[52:67], v[214:217], v[226:229], v[52:67]
	s_waitcnt vmcnt(19)
	ds_write_b128 v191, v[84:87] offset:18432
	v_mfma_f32_32x32x16_bf16 v[36:51], v[214:217], v[230:233], v[36:51]
	s_waitcnt vmcnt(18)
	ds_write_b128 v191, v[88:91] offset:55296
	v_mfma_f32_32x32x16_bf16 v[20:35], v[218:221], v[226:229], v[20:35]
	s_waitcnt vmcnt(17)
	ds_write_b128 v192, v[92:95] offset:18432
	v_mfma_f32_32x32x16_bf16 v[4:19], v[218:221], v[230:233], v[4:19]
	s_waitcnt vmcnt(16)
	ds_write_b128 v192, v[104:107] offset:55296
	s_waitcnt lgkmcnt(0)
	s_barrier
; #define MFMA(a, b, c) __builtin_amdgcn_mfma_f32_32x32x16_bf16((a), (b), (c), 0, 0, 0)
; template <class Epi, class ColV>
; DI void gemm_tile(const bf16_t* __restrict__ A, int lda, const bf16_t* __restrict__ Bt, int ldb, int K, int m0, int n0, unsigned char* smem, Epi epi, ColV colv, const bf16_t* __restrict__ HYT = nullptr) {
;     ...
;     auto step = [&](int kt, u32x4 (&ldset)[8], const u32x4 (&stset)[8]) {
;         const int buf = kt & 1;
;         if (kt + 2 < nk) gload(ldset, kt + 2);
;         const bf16_t* Ab = As + (buf * 128 + 64 * wr + li) * LS + 8 * lh;
;         const bf16_t* Bb = Bs + (buf * 128 + 64 * wc + li) * LS + 8 * lh;
;         bf16x8 fa[2][2], fb[2][2], ga[2][2], gb[2][2];
; #pragma unroll
;         for (int k2 = 0; k2 < 2; ++k2) { fa[k2][0] = ld8(Ab + 16 * k2); fa[k2][1] = ld8(Ab + 32 * LS + 16 * k2); fb[k2][0] = ld8(Bb + 16 * k2); fb[k2][1] = ld8(Bb + 32 * LS + 16 * k2); }
;         __builtin_amdgcn_sched_barrier(0);
; #pragma unroll
;         for (int k2 = 0; k2 < 2; ++k2) {
;             acc[0][0] = MFMA(fa[k2][0], fb[k2][0], acc[0][0]); acc[0][1] = MFMA(fa[k2][0], fb[k2][1], acc[0][1]);
;             acc[1][0] = MFMA(fa[k2][1], fb[k2][0], acc[1][0]); acc[1][1] = MFMA(fa[k2][1], fb[k2][1], acc[1][1]);
;         }
; #pragma unroll
;         for (int k2 = 0; k2 < 2; ++k2) { const int ks = 2 + k2; ga[k2][0] = ld8(Ab + 16 * ks); ga[k2][1] = ld8(Ab + 32 * LS + 16 * ks); gb[k2][0] = ld8(Bb + 16 * ks); gb[k2][1] = ld8(Bb + 32 * LS + 16 * ks); }
; #pragma unroll
;         for (int k2 = 0; k2 < 2; ++k2) {
;             acc[0][0] = MFMA(ga[k2][0], gb[k2][0], acc[0][0]); acc[0][1] = MFMA(ga[k2][0], gb[k2][1], acc[0][1]);
;             acc[1][0] = MFMA(ga[k2][1], gb[k2][0], acc[1][0]); acc[1][1] = MFMA(ga[k2][1], gb[k2][1], acc[1][1]);
;         }
;         if (kt + 1 < nk) sstore(stset, buf ^ 1, kt + 1);
; #pragma unroll
;         for (int i = 0; i < 8; ++i) { __builtin_amdgcn_sched_group_barrier(0x008, 1, 0); __builtin_amdgcn_sched_group_barrier(0x100, 1, 0); }
; #pragma unroll
;         for (int i = 0; i < 8; ++i) { __builtin_amdgcn_sched_group_barrier(0x008, 1, 0); __builtin_amdgcn_sched_group_barrier(0x200, 1, 0); }
;         __builtin_amdgcn_sched_barrier(0);
;         __syncthreads();
;     };
	s_setprio 1
	ds_read_b128 v[202:205], v196
	ds_read_b128 v[218:221], v197 offset:36864
	ds_read_b128 v[226:229], v197 offset:41472
	ds_read_b128 v[210:213], v196 offset:4608
	ds_read_b128 v[206:209], v196 offset:32
	ds_read_b128 v[230:233], v197 offset:41504
	ds_read_b128 v[214:217], v196 offset:4640
	ds_read_b128 v[222:225], v197 offset:36896
	s_waitcnt lgkmcnt(6)
	v_mfma_f32_32x32x16_bf16 v[52:67], v[202:205], v[218:221], v[52:67]
	global_load_dwordx4 v[68:71], v[164:165], off offset:1536
	s_waitcnt lgkmcnt(5)
	v_mfma_f32_32x32x16_bf16 v[36:51], v[202:205], v[226:229], v[36:51]
	global_load_dwordx4 v[72:75], v[162:163], off offset:1536
	s_waitcnt lgkmcnt(4)
	v_mfma_f32_32x32x16_bf16 v[4:19], v[210:213], v[226:229], v[4:19]
	global_load_dwordx4 v[76:79], v[160:161], off offset:1536
	s_waitcnt lgkmcnt(2)
	v_mfma_f32_32x32x16_bf16 v[36:51], v[206:209], v[230:233], v[36:51]
	global_load_dwordx4 v[80:83], v[158:159], off offset:1536
	s_waitcnt lgkmcnt(1)
	v_mfma_f32_32x32x16_bf16 v[4:19], v[214:217], v[230:233], v[4:19]
	global_load_dwordx4 v[84:87], v[156:157], off offset:1536
	ds_read_b128 v[230:233], v197 offset:41568
	ds_read_b128 v[202:205], v196 offset:4672
	v_mfma_f32_32x32x16_bf16 v[20:35], v[210:213], v[218:221], v[20:35]
	global_load_dwordx4 v[88:91], v[154:155], off offset:1536
	ds_read_b128 v[218:221], v196 offset:4704
	ds_read_b128 v[210:213], v196 offset:64
	s_waitcnt lgkmcnt(4)
	v_mfma_f32_32x32x16_bf16 v[52:67], v[206:209], v[222:225], v[52:67]
	global_load_dwordx4 v[92:95], v[152:153], off offset:1536
	ds_read_b128 v[226:229], v197 offset:36960
	ds_read_b128 v[206:209], v197 offset:41536
	v_mfma_f32_32x32x16_bf16 v[20:35], v[214:217], v[222:225], v[20:35]
	global_load_dwordx4 v[104:107], v[146:147], off offset:1536
	ds_read_b128 v[222:225], v197 offset:36928
	ds_read_b128 v[214:217], v196 offset:96
	s_waitcnt lgkmcnt(1)
	v_mfma_f32_32x32x16_bf16 v[52:67], v[210:213], v[222:225], v[52:67]
	s_waitcnt vmcnt(23)
	ds_write_b128 v167, v[96:99]
	v_mfma_f32_32x32x16_bf16 v[36:51], v[210:213], v[206:209], v[36:51]
	s_waitcnt vmcnt(22)
	ds_write_b128 v167, v[100:103] offset:36864
	v_mfma_f32_32x32x16_bf16 v[20:35], v[202:205], v[222:225], v[20:35]
	s_waitcnt vmcnt(21)
	ds_write_b128 v190, v[108:111]
	v_mfma_f32_32x32x16_bf16 v[4:19], v[202:205], v[206:209], v[4:19]
	s_setprio 0
	s_waitcnt vmcnt(20)
	ds_write_b128 v190, v[112:115] offset:36864
	s_waitcnt lgkmcnt(4)
	v_mfma_f32_32x32x16_bf16 v[52:67], v[214:217], v[226:229], v[52:67]
	s_waitcnt vmcnt(19)
	ds_write_b128 v191, v[116:119]
	v_mfma_f32_32x32x16_bf16 v[36:51], v[214:217], v[230:233], v[36:51]
	s_waitcnt vmcnt(18)
	ds_write_b128 v191, v[120:123] offset:36864
	v_mfma_f32_32x32x16_bf16 v[20:35], v[218:221], v[226:229], v[20:35]
	s_waitcnt vmcnt(17)
	ds_write_b128 v192, v[124:127]
	v_mfma_f32_32x32x16_bf16 v[4:19], v[218:221], v[230:233], v[4:19]
	s_waitcnt vmcnt(16)
	ds_write_b128 v192, v[128:131] offset:36864
	s_waitcnt lgkmcnt(0)
	s_barrier
	s_setprio 1
	ds_read_b128 v[202:205], v194
	ds_read_b128 v[218:221], v195 offset:36864
	ds_read_b128 v[226:229], v195 offset:41472
	ds_read_b128 v[210:213], v194 offset:4608
	ds_read_b128 v[206:209], v194 offset:32
	ds_read_b128 v[230:233], v195 offset:41504
	ds_read_b128 v[214:217], v194 offset:4640
	ds_read_b128 v[222:225], v195 offset:36896
	s_waitcnt lgkmcnt(6)
	v_mfma_f32_32x32x16_bf16 v[52:67], v[202:205], v[218:221], v[52:67]
	global_load_dwordx4 v[96:99], v[164:165], off offset:1664
	s_waitcnt lgkmcnt(5)
	v_mfma_f32_32x32x16_bf16 v[36:51], v[202:205], v[226:229], v[36:51]
	global_load_dwordx4 v[100:103], v[162:163], off offset:1664
	s_waitcnt lgkmcnt(4)
	v_mfma_f32_32x32x16_bf16 v[4:19], v[210:213], v[226:229], v[4:19]
	global_load_dwordx4 v[108:111], v[160:161], off offset:1664
	s_waitcnt lgkmcnt(2)
	v_mfma_f32_32x32x16_bf16 v[36:51], v[206:209], v[230:233], v[36:51]
	global_load_dwordx4 v[112:115], v[158:159], off offset:1664
	s_waitcnt lgkmcnt(1)
	v_mfma_f32_32x32x16_bf16 v[4:19], v[214:217], v[230:233], v[4:19]
	global_load_dwordx4 v[116:119], v[156:157], off offset:1664
	ds_read_b128 v[230:233], v195 offset:41568
	ds_read_b128 v[202:205], v194 offset:4672
	v_mfma_f32_32x32x16_bf16 v[20:35], v[210:213], v[218:221], v[20:35]
	global_load_dwordx4 v[120:123], v[154:155], off offset:1664
	ds_read_b128 v[218:221], v194 offset:4704
	ds_read_b128 v[210:213], v194 offset:64
	s_waitcnt lgkmcnt(4)
	v_mfma_f32_32x32x16_bf16 v[52:67], v[206:209], v[222:225], v[52:67]
	global_load_dwordx4 v[124:127], v[152:153], off offset:1664
	ds_read_b128 v[226:229], v195 offset:36960
	ds_read_b128 v[206:209], v195 offset:41536
	v_mfma_f32_32x32x16_bf16 v[20:35], v[214:217], v[222:225], v[20:35]
	global_load_dwordx4 v[128:131], v[146:147], off offset:1664
	ds_read_b128 v[222:225], v195 offset:36928
	ds_read_b128 v[214:217], v194 offset:96
	s_waitcnt lgkmcnt(1)
	v_mfma_f32_32x32x16_bf16 v[52:67], v[210:213], v[222:225], v[52:67]
	s_waitcnt vmcnt(23)
	ds_write_b128 v167, v[132:135] offset:18432
	v_mfma_f32_32x32x16_bf16 v[36:51], v[210:213], v[206:209], v[36:51]
	s_waitcnt vmcnt(22)
	ds_write_b128 v167, v[136:139] offset:55296
	v_mfma_f32_32x32x16_bf16 v[20:35], v[202:205], v[222:225], v[20:35]
	s_waitcnt vmcnt(21)
	ds_write_b128 v190, v[140:143] offset:18432
	v_mfma_f32_32x32x16_bf16 v[4:19], v[202:205], v[206:209], v[4:19]
	s_setprio 0
	s_waitcnt vmcnt(20)
	ds_write_b128 v190, v[198:201] offset:55296
	s_waitcnt lgkmcnt(4)
	v_mfma_f32_32x32x16_bf16 v[52:67], v[214:217], v[226:229], v[52:67]
	s_waitcnt vmcnt(19)
	ds_write_b128 v191, v[174:177] offset:18432
	v_mfma_f32_32x32x16_bf16 v[36:51], v[214:217], v[230:233], v[36:51]
	s_waitcnt vmcnt(18)
	ds_write_b128 v191, v[178:181] offset:55296
	v_mfma_f32_32x32x16_bf16 v[20:35], v[218:221], v[226:229], v[20:35]
	s_waitcnt vmcnt(17)
	ds_write_b128 v192, v[242:245] offset:18432
	v_mfma_f32_32x32x16_bf16 v[4:19], v[218:221], v[230:233], v[4:19]
	s_waitcnt vmcnt(16)
	ds_write_b128 v192, v[246:249] offset:55296
	s_waitcnt lgkmcnt(0)
	s_barrier
; #define MFMA(a, b, c) __builtin_amdgcn_mfma_f32_32x32x16_bf16((a), (b), (c), 0, 0, 0)
; template <class Epi, class ColV>
; DI void gemm_tile(const bf16_t* __restrict__ A, int lda, const bf16_t* __restrict__ Bt, int ldb, int K, int m0, int n0, unsigned char* smem, Epi epi, ColV colv, const bf16_t* __restrict__ HYT = nullptr) {
;     ...
;     auto step = [&](int kt, u32x4 (&ldset)[8], const u32x4 (&stset)[8]) {
;         const int buf = kt & 1;
;         if (kt + 2 < nk) gload(ldset, kt + 2);
;         const bf16_t* Ab = As + (buf * 128 + 64 * wr + li) * LS + 8 * lh;
;         const bf16_t* Bb = Bs + (buf * 128 + 64 * wc + li) * LS + 8 * lh;
;         bf16x8 fa[2][2], fb[2][2], ga[2][2], gb[2][2];
; #pragma unroll
;         for (int k2 = 0; k2 < 2; ++k2) { fa[k2][0] = ld8(Ab + 16 * k2); fa[k2][1] = ld8(Ab + 32 * LS + 16 * k2); fb[k2][0] = ld8(Bb + 16 * k2); fb[k2][1] = ld8(Bb + 32 * LS + 16 * k2); }
;         __builtin_amdgcn_sched_barrier(0);
; #pragma unroll
;         for (int k2 = 0; k2 < 2; ++k2) {
;             acc[0][0] = MFMA(fa[k2][0], fb[k2][0], acc[0][0]); acc[0][1] = MFMA(fa[k2][0], fb[k2][1], acc[0][1]);
;             acc[1][0] = MFMA(fa[k2][1], fb[k2][0], acc[1][0]); acc[1][1] = MFMA(fa[k2][1], fb[k2][1], acc[1][1]);
;         }
; #pragma unroll
;         for (int k2 = 0; k2 < 2; ++k2) { const int ks = 2 + k2; ga[k2][0] = ld8(Ab + 16 * ks); ga[k2][1] = ld8(Ab + 32 * LS + 16 * ks); gb[k2][0] = ld8(Bb + 16 * ks); gb[k2][1] = ld8(Bb + 32 * LS + 16 * ks); }
; #pragma unroll
;         for (int k2 = 0; k2 < 2; ++k2) {
;             acc[0][0] = MFMA(ga[k2][0], gb[k2][0], acc[0][0]); acc[0][1] = MFMA(ga[k2][0], gb[k2][1], acc[0][1]);
;             acc[1][0] = MFMA(ga[k2][1], gb[k2][0], acc[1][0]); acc[1][1] = MFMA(ga[k2][1], gb[k2][1], acc[1][1]);
;         }
;         if (kt + 1 < nk) sstore(stset, buf ^ 1, kt + 1);
; #pragma unroll
;         for (int i = 0; i < 8; ++i) { __builtin_amdgcn_sched_group_barrier(0x008, 1, 0); __builtin_amdgcn_sched_group_barrier(0x100, 1, 0); }
; #pragma unroll
;         for (int i = 0; i < 8; ++i) { __builtin_amdgcn_sched_group_barrier(0x008, 1, 0); __builtin_amdgcn_sched_group_barrier(0x200, 1, 0); }
;         __builtin_amdgcn_sched_barrier(0);
;         __syncthreads();
;     };
	s_setprio 1
	ds_read_b128 v[202:205], v196
	ds_read_b128 v[218:221], v197 offset:36864
	ds_read_b128 v[226:229], v197 offset:41472
	ds_read_b128 v[210:213], v196 offset:4608
	ds_read_b128 v[206:209], v196 offset:32
	ds_read_b128 v[230:233], v197 offset:41504
	ds_read_b128 v[214:217], v196 offset:4640
	ds_read_b128 v[222:225], v197 offset:36896
	s_waitcnt lgkmcnt(6)
	v_mfma_f32_32x32x16_bf16 v[52:67], v[202:205], v[218:221], v[52:67]
	global_load_dwordx4 v[132:135], v[164:165], off offset:1792
	s_waitcnt lgkmcnt(5)
	v_mfma_f32_32x32x16_bf16 v[36:51], v[202:205], v[226:229], v[36:51]
	global_load_dwordx4 v[136:139], v[162:163], off offset:1792
	s_waitcnt lgkmcnt(4)
	v_mfma_f32_32x32x16_bf16 v[4:19], v[210:213], v[226:229], v[4:19]
	global_load_dwordx4 v[140:143], v[160:161], off offset:1792
	s_waitcnt lgkmcnt(2)
	v_mfma_f32_32x32x16_bf16 v[36:51], v[206:209], v[230:233], v[36:51]
	global_load_dwordx4 v[198:201], v[158:159], off offset:1792
	s_waitcnt lgkmcnt(1)
	v_mfma_f32_32x32x16_bf16 v[4:19], v[214:217], v[230:233], v[4:19]
	global_load_dwordx4 v[174:177], v[156:157], off offset:1792
	ds_read_b128 v[230:233], v197 offset:41568
	ds_read_b128 v[202:205], v196 offset:4672
	v_mfma_f32_32x32x16_bf16 v[20:35], v[210:213], v[218:221], v[20:35]
	global_load_dwordx4 v[178:181], v[154:155], off offset:1792
	ds_read_b128 v[218:221], v196 offset:4704
	ds_read_b128 v[210:213], v196 offset:64
	s_waitcnt lgkmcnt(4)
	v_mfma_f32_32x32x16_bf16 v[52:67], v[206:209], v[222:225], v[52:67]
	global_load_dwordx4 v[242:245], v[152:153], off offset:1792
	ds_read_b128 v[226:229], v197 offset:36960
	ds_read_b128 v[206:209], v197 offset:41536
	v_mfma_f32_32x32x16_bf16 v[20:35], v[214:217], v[222:225], v[20:35]
	global_load_dwordx4 v[246:249], v[146:147], off offset:1792
	ds_read_b128 v[222:225], v197 offset:36928
	ds_read_b128 v[214:217], v196 offset:96
	s_waitcnt lgkmcnt(1)
	v_mfma_f32_32x32x16_bf16 v[52:67], v[210:213], v[222:225], v[52:67]
	s_waitcnt vmcnt(23)
	ds_write_b128 v167, v[68:71]
	v_mfma_f32_32x32x16_bf16 v[36:51], v[210:213], v[206:209], v[36:51]
	s_waitcnt vmcnt(22)
	ds_write_b128 v167, v[72:75] offset:36864
	v_mfma_f32_32x32x16_bf16 v[20:35], v[202:205], v[222:225], v[20:35]
	s_waitcnt vmcnt(21)
	ds_write_b128 v190, v[76:79]
	v_mfma_f32_32x32x16_bf16 v[4:19], v[202:205], v[206:209], v[4:19]
	s_setprio 0
	s_waitcnt vmcnt(20)
	ds_write_b128 v190, v[80:83] offset:36864
	s_waitcnt lgkmcnt(4)
	v_mfma_f32_32x32x16_bf16 v[52:67], v[214:217], v[226:229], v[52:67]
	s_waitcnt vmcnt(19)
	ds_write_b128 v191, v[84:87]
	v_mfma_f32_32x32x16_bf16 v[36:51], v[214:217], v[230:233], v[36:51]
	s_waitcnt vmcnt(18)
	ds_write_b128 v191, v[88:91] offset:36864
	v_mfma_f32_32x32x16_bf16 v[20:35], v[218:221], v[226:229], v[20:35]
	s_waitcnt vmcnt(17)
	ds_write_b128 v192, v[92:95]
	v_mfma_f32_32x32x16_bf16 v[4:19], v[218:221], v[230:233], v[4:19]
	s_waitcnt vmcnt(16)
	ds_write_b128 v192, v[104:107] offset:36864
	s_waitcnt lgkmcnt(0)
	s_barrier
	s_setprio 1
	ds_read_b128 v[202:205], v194
	ds_read_b128 v[218:221], v195 offset:36864
	ds_read_b128 v[226:229], v195 offset:41472
	ds_read_b128 v[210:213], v194 offset:4608
	ds_read_b128 v[206:209], v194 offset:32
	ds_read_b128 v[230:233], v195 offset:41504
	ds_read_b128 v[214:217], v194 offset:4640
	ds_read_b128 v[222:225], v195 offset:36896
	s_waitcnt lgkmcnt(6)
	v_mfma_f32_32x32x16_bf16 v[52:67], v[202:205], v[218:221], v[52:67]
	global_load_dwordx4 v[68:71], v[164:165], off offset:1920
	s_waitcnt lgkmcnt(5)
	v_mfma_f32_32x32x16_bf16 v[36:51], v[202:205], v[226:229], v[36:51]
	global_load_dwordx4 v[72:75], v[162:163], off offset:1920
	s_waitcnt lgkmcnt(4)
	v_mfma_f32_32x32x16_bf16 v[4:19], v[210:213], v[226:229], v[4:19]
	global_load_dwordx4 v[76:79], v[160:161], off offset:1920
	s_waitcnt lgkmcnt(2)
	v_mfma_f32_32x32x16_bf16 v[36:51], v[206:209], v[230:233], v[36:51]
	global_load_dwordx4 v[80:83], v[158:159], off offset:1920
	s_waitcnt lgkmcnt(1)
	v_mfma_f32_32x32x16_bf16 v[4:19], v[214:217], v[230:233], v[4:19]
	global_load_dwordx4 v[84:87], v[156:157], off offset:1920
	ds_read_b128 v[230:233], v195 offset:41568
	ds_read_b128 v[202:205], v194 offset:4672
	v_mfma_f32_32x32x16_bf16 v[20:35], v[210:213], v[218:221], v[20:35]
	global_load_dwordx4 v[88:91], v[154:155], off offset:1920
	ds_read_b128 v[218:221], v194 offset:4704
	ds_read_b128 v[210:213], v194 offset:64
	s_waitcnt lgkmcnt(4)
	v_mfma_f32_32x32x16_bf16 v[52:67], v[206:209], v[222:225], v[52:67]
	global_load_dwordx4 v[92:95], v[152:153], off offset:1920
	ds_read_b128 v[226:229], v195 offset:36960
	ds_read_b128 v[206:209], v195 offset:41536
	v_mfma_f32_32x32x16_bf16 v[20:35], v[214:217], v[222:225], v[20:35]
	global_load_dwordx4 v[104:107], v[146:147], off offset:1920
	ds_read_b128 v[222:225], v195 offset:36928
	ds_read_b128 v[214:217], v194 offset:96
	s_waitcnt lgkmcnt(1)
	v_mfma_f32_32x32x16_bf16 v[52:67], v[210:213], v[222:225], v[52:67]
	s_waitcnt vmcnt(23)
	ds_write_b128 v167, v[96:99] offset:18432
	v_mfma_f32_32x32x16_bf16 v[36:51], v[210:213], v[206:209], v[36:51]
	s_waitcnt vmcnt(22)
	ds_write_b128 v167, v[100:103] offset:55296
	v_mfma_f32_32x32x16_bf16 v[20:35], v[202:205], v[222:225], v[20:35]
	s_waitcnt vmcnt(21)
	ds_write_b128 v190, v[108:111] offset:18432
	v_mfma_f32_32x32x16_bf16 v[4:19], v[202:205], v[206:209], v[4:19]
	s_setprio 0
	s_waitcnt vmcnt(20)
	ds_write_b128 v190, v[112:115] offset:55296
	s_waitcnt lgkmcnt(4)
	v_mfma_f32_32x32x16_bf16 v[52:67], v[214:217], v[226:229], v[52:67]
	s_waitcnt vmcnt(19)
	ds_write_b128 v191, v[116:119] offset:18432
	v_mfma_f32_32x32x16_bf16 v[36:51], v[214:217], v[230:233], v[36:51]
	s_waitcnt vmcnt(18)
	ds_write_b128 v191, v[120:123] offset:55296
	v_mfma_f32_32x32x16_bf16 v[20:35], v[218:221], v[226:229], v[20:35]
	s_waitcnt vmcnt(17)
	ds_write_b128 v192, v[124:127] offset:18432
	v_mfma_f32_32x32x16_bf16 v[4:19], v[218:221], v[230:233], v[4:19]
	s_waitcnt vmcnt(16)
	ds_write_b128 v192, v[128:131] offset:55296
	s_waitcnt lgkmcnt(0)
	s_barrier
; #define MFMA(a, b, c) __builtin_amdgcn_mfma_f32_32x32x16_bf16((a), (b), (c), 0, 0, 0)
; template <class Epi, class ColV>
; DI void gemm_tile(const bf16_t* __restrict__ A, int lda, const bf16_t* __restrict__ Bt, int ldb, int K, int m0, int n0, unsigned char* smem, Epi epi, ColV colv, const bf16_t* __restrict__ HYT = nullptr) {
;     ...
;     auto step = [&](int kt, u32x4 (&ldset)[8], const u32x4 (&stset)[8]) {
;         const int buf = kt & 1;
;         if (kt + 2 < nk) gload(ldset, kt + 2);
;         const bf16_t* Ab = As + (buf * 128 + 64 * wr + li) * LS + 8 * lh;
;         const bf16_t* Bb = Bs + (buf * 128 + 64 * wc + li) * LS + 8 * lh;
;         bf16x8 fa[2][2], fb[2][2], ga[2][2], gb[2][2];
; #pragma unroll
;         for (int k2 = 0; k2 < 2; ++k2) { fa[k2][0] = ld8(Ab + 16 * k2); fa[k2][1] = ld8(Ab + 32 * LS + 16 * k2); fb[k2][0] = ld8(Bb + 16 * k2); fb[k2][1] = ld8(Bb + 32 * LS + 16 * k2); }
;         __builtin_amdgcn_sched_barrier(0);
; #pragma unroll
;         for (int k2 = 0; k2 < 2; ++k2) {
;             acc[0][0] = MFMA(fa[k2][0], fb[k2][0], acc[0][0]); acc[0][1] = MFMA(fa[k2][0], fb[k2][1], acc[0][1]);
;             acc[1][0] = MFMA(fa[k2][1], fb[k2][0], acc[1][0]); acc[1][1] = MFMA(fa[k2][1], fb[k2][1], acc[1][1]);
;         }
; #pragma unroll
;         for (int k2 = 0; k2 < 2; ++k2) { const int ks = 2 + k2; ga[k2][0] = ld8(Ab + 16 * ks); ga[k2][1] = ld8(Ab + 32 * LS + 16 * ks); gb[k2][0] = ld8(Bb + 16 * ks); gb[k2][1] = ld8(Bb + 32 * LS + 16 * ks); }
; #pragma unroll
;         for (int k2 = 0; k2 < 2; ++k2) {
;             acc[0][0] = MFMA(ga[k2][0], gb[k2][0], acc[0][0]); acc[0][1] = MFMA(ga[k2][0], gb[k2][1], acc[0][1]);
;             acc[1][0] = MFMA(ga[k2][1], gb[k2][0], acc[1][0]); acc[1][1] = MFMA(ga[k2][1], gb[k2][1], acc[1][1]);
;         }
;         if (kt + 1 < nk) sstore(stset, buf ^ 1, kt + 1);
; #pragma unroll
;         for (int i = 0; i < 8; ++i) { __builtin_amdgcn_sched_group_barrier(0x008, 1, 0); __builtin_amdgcn_sched_group_barrier(0x100, 1, 0); }
; #pragma unroll
;         for (int i = 0; i < 8; ++i) { __builtin_amdgcn_sched_group_barrier(0x008, 1, 0); __builtin_amdgcn_sched_group_barrier(0x200, 1, 0); }
;         __builtin_amdgcn_sched_barrier(0);
;         __syncthreads();
;     };
	s_setprio 1
	ds_read_b128 v[202:205], v196
	ds_read_b128 v[218:221], v197 offset:36864
	ds_read_b128 v[226:229], v197 offset:41472
	ds_read_b128 v[210:213], v196 offset:4608
	ds_read_b128 v[206:209], v196 offset:32
	ds_read_b128 v[230:233], v197 offset:41504
	ds_read_b128 v[214:217], v196 offset:4640
	ds_read_b128 v[222:225], v197 offset:36896
	s_waitcnt lgkmcnt(6)
	v_mfma_f32_32x32x16_bf16 v[52:67], v[202:205], v[218:221], v[52:67]
	s_waitcnt lgkmcnt(5)
	v_mfma_f32_32x32x16_bf16 v[36:51], v[202:205], v[226:229], v[36:51]
	s_waitcnt lgkmcnt(4)
	v_mfma_f32_32x32x16_bf16 v[4:19], v[210:213], v[226:229], v[4:19]
	s_waitcnt lgkmcnt(2)
	v_mfma_f32_32x32x16_bf16 v[36:51], v[206:209], v[230:233], v[36:51]
	s_waitcnt lgkmcnt(1)
	v_mfma_f32_32x32x16_bf16 v[4:19], v[214:217], v[230:233], v[4:19]
	ds_read_b128 v[230:233], v197 offset:41568
	ds_read_b128 v[202:205], v196 offset:4672
	v_mfma_f32_32x32x16_bf16 v[20:35], v[210:213], v[218:221], v[20:35]
	ds_read_b128 v[218:221], v196 offset:4704
	ds_read_b128 v[210:213], v196 offset:64
	s_waitcnt lgkmcnt(4)
	v_mfma_f32_32x32x16_bf16 v[52:67], v[206:209], v[222:225], v[52:67]
	ds_read_b128 v[226:229], v197 offset:36960
	ds_read_b128 v[206:209], v197 offset:41536
	v_mfma_f32_32x32x16_bf16 v[20:35], v[214:217], v[222:225], v[20:35]
	ds_read_b128 v[222:225], v197 offset:36928
	ds_read_b128 v[214:217], v196 offset:96
	s_waitcnt lgkmcnt(1)
	v_mfma_f32_32x32x16_bf16 v[52:67], v[210:213], v[222:225], v[52:67]
	s_waitcnt vmcnt(15)
	ds_write_b128 v167, v[132:135]
	v_mfma_f32_32x32x16_bf16 v[36:51], v[210:213], v[206:209], v[36:51]
	s_waitcnt vmcnt(14)
	ds_write_b128 v167, v[136:139] offset:36864
	v_mfma_f32_32x32x16_bf16 v[20:35], v[202:205], v[222:225], v[20:35]
	s_waitcnt vmcnt(13)
	ds_write_b128 v190, v[140:143]
	v_mfma_f32_32x32x16_bf16 v[4:19], v[202:205], v[206:209], v[4:19]
	s_setprio 0
	s_waitcnt vmcnt(12)
	ds_write_b128 v190, v[198:201] offset:36864
	s_waitcnt lgkmcnt(4)
	v_mfma_f32_32x32x16_bf16 v[52:67], v[214:217], v[226:229], v[52:67]
	s_waitcnt vmcnt(11)
	ds_write_b128 v191, v[174:177]
	v_mfma_f32_32x32x16_bf16 v[36:51], v[214:217], v[230:233], v[36:51]
	s_waitcnt vmcnt(10)
	ds_write_b128 v191, v[178:181] offset:36864
	v_mfma_f32_32x32x16_bf16 v[20:35], v[218:221], v[226:229], v[20:35]
	s_waitcnt vmcnt(9)
	ds_write_b128 v192, v[242:245]
	v_mfma_f32_32x32x16_bf16 v[4:19], v[218:221], v[230:233], v[4:19]
	s_waitcnt vmcnt(8)
	ds_write_b128 v192, v[246:249] offset:36864
	s_waitcnt lgkmcnt(0)
	s_barrier
; #define MFMA(a, b, c) __builtin_amdgcn_mfma_f32_32x32x16_bf16((a), (b), (c), 0, 0, 0)
; template <class Epi, class ColV>
; DI void gemm_tile(const bf16_t* __restrict__ A, int lda, const bf16_t* __restrict__ Bt, int ldb, int K, int m0, int n0, unsigned char* smem, Epi epi, ColV colv, const bf16_t* __restrict__ HYT = nullptr) {
;     ...
;     auto step = [&](int kt, u32x4 (&ldset)[8], const u32x4 (&stset)[8]) {
;         const int buf = kt & 1;
;         if (kt + 2 < nk) gload(ldset, kt + 2);
;         const bf16_t* Ab = As + (buf * 128 + 64 * wr + li) * LS + 8 * lh;
;         const bf16_t* Bb = Bs + (buf * 128 + 64 * wc + li) * LS + 8 * lh;
;         bf16x8 fa[2][2], fb[2][2], ga[2][2], gb[2][2];
; #pragma unroll
;         for (int k2 = 0; k2 < 2; ++k2) { fa[k2][0] = ld8(Ab + 16 * k2); fa[k2][1] = ld8(Ab + 32 * LS + 16 * k2); fb[k2][0] = ld8(Bb + 16 * k2); fb[k2][1] = ld8(Bb + 32 * LS + 16 * k2); }
;         __builtin_amdgcn_sched_barrier(0);
; #pragma unroll
;         for (int k2 = 0; k2 < 2; ++k2) {
;             acc[0][0] = MFMA(fa[k2][0], fb[k2][0], acc[0][0]); acc[0][1] = MFMA(fa[k2][0], fb[k2][1], acc[0][1]);
;             acc[1][0] = MFMA(fa[k2][1], fb[k2][0], acc[1][0]); acc[1][1] = MFMA(fa[k2][1], fb[k2][1], acc[1][1]);
;         }
; #pragma unroll
;         for (int k2 = 0; k2 < 2; ++k2) { const int ks = 2 + k2; ga[k2][0] = ld8(Ab + 16 * ks); ga[k2][1] = ld8(Ab + 32 * LS + 16 * ks); gb[k2][0] = ld8(Bb + 16 * ks); gb[k2][1] = ld8(Bb + 32 * LS + 16 * ks); }
; #pragma unroll
;         for (int k2 = 0; k2 < 2; ++k2) {
;             acc[0][0] = MFMA(ga[k2][0], gb[k2][0], acc[0][0]); acc[0][1] = MFMA(ga[k2][0], gb[k2][1], acc[0][1]);
;             acc[1][0] = MFMA(ga[k2][1], gb[k2][0], acc[1][0]); acc[1][1] = MFMA(ga[k2][1], gb[k2][1], acc[1][1]);
;         }
;         if (kt + 1 < nk) sstore(stset, buf ^ 1, kt + 1);
; #pragma unroll
;         for (int i = 0; i < 8; ++i) { __builtin_amdgcn_sched_group_barrier(0x008, 1, 0); __builtin_amdgcn_sched_group_barrier(0x100, 1, 0); }
; #pragma unroll
;         for (int i = 0; i < 8; ++i) { __builtin_amdgcn_sched_group_barrier(0x008, 1, 0); __builtin_amdgcn_sched_group_barrier(0x200, 1, 0); }
;         __builtin_amdgcn_sched_barrier(0);
;         __syncthreads();
;     };
	s_setprio 1
	ds_read_b128 v[202:205], v194
	ds_read_b128 v[218:221], v195 offset:36864
	ds_read_b128 v[226:229], v195 offset:41472
	ds_read_b128 v[210:213], v194 offset:4608
	ds_read_b128 v[206:209], v194 offset:32
	ds_read_b128 v[230:233], v195 offset:41504
	ds_read_b128 v[214:217], v194 offset:4640
	ds_read_b128 v[222:225], v195 offset:36896
	s_waitcnt lgkmcnt(6)
	v_mfma_f32_32x32x16_bf16 v[52:67], v[202:205], v[218:221], v[52:67]
	s_waitcnt lgkmcnt(5)
	v_mfma_f32_32x32x16_bf16 v[36:51], v[202:205], v[226:229], v[36:51]
	s_waitcnt lgkmcnt(4)
	v_mfma_f32_32x32x16_bf16 v[4:19], v[210:213], v[226:229], v[4:19]
	s_waitcnt lgkmcnt(2)
	v_mfma_f32_32x32x16_bf16 v[36:51], v[206:209], v[230:233], v[36:51]
	s_waitcnt lgkmcnt(1)
	v_mfma_f32_32x32x16_bf16 v[4:19], v[214:217], v[230:233], v[4:19]
	ds_read_b128 v[230:233], v195 offset:41568
	ds_read_b128 v[202:205], v194 offset:4672
	v_mfma_f32_32x32x16_bf16 v[20:35], v[210:213], v[218:221], v[20:35]
	ds_read_b128 v[218:221], v194 offset:4704
	ds_read_b128 v[210:213], v194 offset:64
	s_waitcnt lgkmcnt(4)
	v_mfma_f32_32x32x16_bf16 v[52:67], v[206:209], v[222:225], v[52:67]
	ds_read_b128 v[226:229], v195 offset:36960
	ds_read_b128 v[206:209], v195 offset:41536
	v_mfma_f32_32x32x16_bf16 v[20:35], v[214:217], v[222:225], v[20:35]
	ds_read_b128 v[222:225], v195 offset:36928
	ds_read_b128 v[214:217], v194 offset:96
	s_waitcnt lgkmcnt(1)
	v_mfma_f32_32x32x16_bf16 v[52:67], v[210:213], v[222:225], v[52:67]
	s_waitcnt vmcnt(7)
	ds_write_b128 v167, v[68:71] offset:18432
	v_mfma_f32_32x32x16_bf16 v[36:51], v[210:213], v[206:209], v[36:51]
	s_waitcnt vmcnt(6)
	ds_write_b128 v167, v[72:75] offset:55296
	v_mfma_f32_32x32x16_bf16 v[20:35], v[202:205], v[222:225], v[20:35]
	s_waitcnt vmcnt(5)
	ds_write_b128 v190, v[76:79] offset:18432
	v_mfma_f32_32x32x16_bf16 v[4:19], v[202:205], v[206:209], v[4:19]
	s_setprio 0
	s_waitcnt vmcnt(4)
	ds_write_b128 v190, v[80:83] offset:55296
	s_waitcnt lgkmcnt(4)
	v_mfma_f32_32x32x16_bf16 v[52:67], v[214:217], v[226:229], v[52:67]
	s_waitcnt vmcnt(3)
	ds_write_b128 v191, v[84:87] offset:18432
	v_mfma_f32_32x32x16_bf16 v[36:51], v[214:217], v[230:233], v[36:51]
	s_waitcnt vmcnt(2)
	ds_write_b128 v191, v[88:91] offset:55296
	v_mfma_f32_32x32x16_bf16 v[20:35], v[218:221], v[226:229], v[20:35]
	s_waitcnt vmcnt(1)
	ds_write_b128 v192, v[92:95] offset:18432
	v_mfma_f32_32x32x16_bf16 v[4:19], v[218:221], v[230:233], v[4:19]
	s_waitcnt vmcnt(0)
	ds_write_b128 v192, v[104:107] offset:55296
	s_waitcnt lgkmcnt(0)
	s_barrier
	s_setprio 1
	ds_read_b128 v[202:205], v196
	ds_read_b128 v[218:221], v197 offset:36864
	ds_read_b128 v[226:229], v197 offset:41472
	ds_read_b128 v[210:213], v196 offset:4608
	ds_read_b128 v[206:209], v196 offset:32
	ds_read_b128 v[230:233], v197 offset:41504
	ds_read_b128 v[214:217], v196 offset:4640
	ds_read_b128 v[222:225], v197 offset:36896
	s_waitcnt lgkmcnt(6)
	v_mfma_f32_32x32x16_bf16 v[52:67], v[202:205], v[218:221], v[52:67]
	s_waitcnt lgkmcnt(5)
	v_mfma_f32_32x32x16_bf16 v[36:51], v[202:205], v[226:229], v[36:51]
	s_waitcnt lgkmcnt(4)
	v_mfma_f32_32x32x16_bf16 v[4:19], v[210:213], v[226:229], v[4:19]
	s_waitcnt lgkmcnt(2)
	v_mfma_f32_32x32x16_bf16 v[36:51], v[206:209], v[230:233], v[36:51]
	s_waitcnt lgkmcnt(1)
	v_mfma_f32_32x32x16_bf16 v[4:19], v[214:217], v[230:233], v[4:19]
	ds_read_b128 v[230:233], v197 offset:41568
	ds_read_b128 v[202:205], v196 offset:4672
	v_mfma_f32_32x32x16_bf16 v[20:35], v[210:213], v[218:221], v[20:35]
	ds_read_b128 v[218:221], v196 offset:4704
	ds_read_b128 v[210:213], v196 offset:64
	s_waitcnt lgkmcnt(4)
	v_mfma_f32_32x32x16_bf16 v[52:67], v[206:209], v[222:225], v[52:67]
	ds_read_b128 v[226:229], v197 offset:36960
	ds_read_b128 v[206:209], v197 offset:41536
	v_mfma_f32_32x32x16_bf16 v[20:35], v[214:217], v[222:225], v[20:35]
	ds_read_b128 v[222:225], v197 offset:36928
	ds_read_b128 v[214:217], v196 offset:96
	s_waitcnt lgkmcnt(1)
	v_mfma_f32_32x32x16_bf16 v[52:67], v[210:213], v[222:225], v[52:67]
	v_mfma_f32_32x32x16_bf16 v[36:51], v[210:213], v[206:209], v[36:51]
	v_mfma_f32_32x32x16_bf16 v[20:35], v[202:205], v[222:225], v[20:35]
	v_mfma_f32_32x32x16_bf16 v[4:19], v[202:205], v[206:209], v[4:19]
	s_setprio 0
	s_waitcnt lgkmcnt(0)
	v_mfma_f32_32x32x16_bf16 v[52:67], v[214:217], v[226:229], v[52:67]
	v_mfma_f32_32x32x16_bf16 v[36:51], v[214:217], v[230:233], v[36:51]
	v_mfma_f32_32x32x16_bf16 v[20:35], v[218:221], v[226:229], v[20:35]
	v_mfma_f32_32x32x16_bf16 v[4:19], v[218:221], v[230:233], v[4:19]
	s_waitcnt lgkmcnt(0)
	s_barrier
	s_setprio 1
	s_nop 7
	s_nop 3
	s_branch .LBB0_1555
